# hand-written pool_rows_state (sample first-block slow path): all window rows fetched in 2 latency rounds instead of 4*W serialized loads; same accumulation order
# speedup vs baseline: 1.0502x; 1.0270x over previous
.LBB0_275:
	s_mul_i32 s0, s54, 15
	s_ashr_i32 s1, s0, 31
	s_lshl_b64 s[0:1], s[0:1], 9
	s_and_b64 vcc, exec, s[8:9]
	s_cbranch_vccz .LBB0_301
	s_lshl_b64 s[8:9], s[0:1], 2
	s_add_u32 s8, s56, s8
	s_addc_u32 s9, s57, s9
	v_mov_b32_e32 v8, 0
	s_lshl_b32 s10, 2, s28
	v_lshl_add_u64 v[28:29], v[32:33], 1, s[52:53]
	v_lshl_add_u64 v[30:31], v[32:33], 2, s[8:9]
	v_add_u32_e32 v12, s21, v148
	s_mov_b64 s[98:99], exec
	v_mov_b32_e32 v12, v28
	v_mov_b32_e32 v13, v29
	v_mov_b32_e32 v14, v30
	v_mov_b32_e32 v15, v31
	v_mov_b32_e32 v59, s21
	v_add3_u32 v58, v148, v59, 0
	v_mad_u64_u32 v[0:1], vcc, v58, s19, v[12:13]
	global_load_dwordx4 v[0:3], v[0:1], off
	v_add3_u32 v58, v148, v59, 1
	v_mad_u64_u32 v[4:5], vcc, v58, s19, v[12:13]
	global_load_dwordx4 v[4:7], v[4:5], off
	v_add3_u32 v58, v148, v59, 2
	v_mad_u64_u32 v[8:9], vcc, v58, s19, v[12:13]
	global_load_dwordx4 v[8:11], v[8:9], off
	v_add3_u32 v58, v148, v59, 3
	v_mad_u64_u32 v[24:25], vcc, v58, s19, v[12:13]
	global_load_dwordx4 v[24:27], v[24:25], off
	v_add_u32_e32 v58, 15, v59
	v_mad_u64_u32 v[72:73], vcc, v58, s19, v[12:13]
	global_load_dwordx4 v[72:75], v[72:73], off
	v_add_u32_e32 v58, 14, v59
	v_mad_u64_u32 v[80:81], vcc, v58, s19, v[12:13]
	global_load_dwordx4 v[80:83], v[80:81], off
	v_add_u32_e32 v58, 13, v59
	v_mad_u64_u32 v[92:93], vcc, v58, s19, v[12:13]
	global_load_dwordx4 v[92:95], v[92:93], off
	v_add_u32_e32 v58, 12, v59
	v_mad_u64_u32 v[96:97], vcc, v58, s19, v[12:13]
	global_load_dwordx4 v[96:99], v[96:97], off
	v_add_u32_e32 v58, 11, v59
	v_mad_u64_u32 v[100:101], vcc, v58, s19, v[12:13]
	global_load_dwordx4 v[100:103], v[100:101], off
	v_add_u32_e32 v58, 10, v59
	v_mad_u64_u32 v[104:105], vcc, v58, s19, v[12:13]
	global_load_dwordx4 v[104:107], v[104:105], off
	v_add_u32_e32 v58, 9, v59
	v_mad_u64_u32 v[108:109], vcc, v58, s19, v[12:13]
	global_load_dwordx4 v[108:111], v[108:109], off
	v_add_u32_e32 v58, 8, v59
	v_mad_u64_u32 v[112:113], vcc, v58, s19, v[12:13]
	global_load_dwordx4 v[112:115], v[112:113], off
	v_add_u32_e32 v58, 7, v59
	v_mad_u64_u32 v[116:117], vcc, v58, s19, v[12:13]
	global_load_dwordx4 v[116:119], v[116:117], off
	v_add_u32_e32 v58, 6, v59
	v_mad_u64_u32 v[120:121], vcc, v58, s19, v[12:13]
	global_load_dwordx4 v[120:123], v[120:121], off
	v_add_u32_e32 v58, 5, v59
	v_mad_u64_u32 v[124:125], vcc, v58, s19, v[12:13]
	global_load_dwordx4 v[124:127], v[124:125], off
	v_add_u32_e32 v58, 4, v59
	v_mad_u64_u32 v[128:129], vcc, v58, s19, v[12:13]
	global_load_dwordx4 v[128:131], v[128:129], off
	v_add_u32_e32 v58, 3, v59
	v_mad_u64_u32 v[132:133], vcc, v58, s19, v[12:13]
	global_load_dwordx4 v[132:135], v[132:133], off
	v_add_u32_e32 v58, 2, v59
	v_mad_u64_u32 v[136:137], vcc, v58, s19, v[12:13]
	global_load_dwordx4 v[136:139], v[136:137], off
	v_add_u32_e32 v58, 1, v59
	v_mad_u64_u32 v[176:177], vcc, v58, s19, v[12:13]
	global_load_dwordx4 v[176:179], v[176:177], off
	v_add_u32_e32 v58, 0, v59
	v_mad_u64_u32 v[180:181], vcc, v58, s19, v[12:13]
	global_load_dwordx4 v[180:183], v[180:181], off
	v_add_co_u32_e32 v184, vcc, 0x7000, v14
	v_addc_co_u32_e32 v185, vcc, 0, v15, vcc
	global_load_dwordx4 v[188:191], v[184:185], off offset:16
	global_load_dwordx4 v[184:187], v[184:185], off
	v_add_co_u32_e32 v192, vcc, 0x6800, v14
	v_addc_co_u32_e32 v193, vcc, 0, v15, vcc
	global_load_dwordx4 v[196:199], v[192:193], off offset:16
	global_load_dwordx4 v[192:195], v[192:193], off
	v_add_co_u32_e32 v200, vcc, 0x6000, v14
	v_addc_co_u32_e32 v201, vcc, 0, v15, vcc
	global_load_dwordx4 v[218:221], v[200:201], off offset:16
	global_load_dwordx4 v[200:203], v[200:201], off
	v_add_co_u32_e32 v222, vcc, 0x5800, v14
	v_addc_co_u32_e32 v223, vcc, 0, v15, vcc
	global_load_dwordx4 v[226:229], v[222:223], off offset:16
	global_load_dwordx4 v[222:225], v[222:223], off
	v_add_co_u32_e32 v230, vcc, 0x5000, v14
	v_addc_co_u32_e32 v231, vcc, 0, v15, vcc
	global_load_dwordx4 v[236:239], v[230:231], off offset:16
	global_load_dwordx4 v[230:233], v[230:231], off
	v_add_co_u32_e32 v240, vcc, 0x4800, v14
	v_addc_co_u32_e32 v241, vcc, 0, v15, vcc
	global_load_dwordx4 v[244:247], v[240:241], off offset:16
	global_load_dwordx4 v[240:243], v[240:241], off
	v_add_co_u32_e32 v248, vcc, 0x4000, v14
	v_addc_co_u32_e32 v249, vcc, 0, v15, vcc
	global_load_dwordx4 v[252:255], v[248:249], off offset:16
	global_load_dwordx4 v[248:251], v[248:249], off
	v_mov_b32_e32 v34, 0
	v_mov_b32_e32 v35, 0
	v_mov_b32_e32 v36, 0
	v_mov_b32_e32 v37, 0
	v_mov_b32_e32 v38, 0
	v_mov_b32_e32 v39, 0
	v_mov_b32_e32 v40, 0
	v_mov_b32_e32 v41, 0
	v_mov_b32_e32 v42, 0
	v_mov_b32_e32 v43, 0
	v_mov_b32_e32 v44, 0
	v_mov_b32_e32 v45, 0
	v_mov_b32_e32 v46, 0
	v_mov_b32_e32 v47, 0
	v_mov_b32_e32 v48, 0
	v_mov_b32_e32 v49, 0
	v_mov_b32_e32 v50, 0
	v_mov_b32_e32 v51, 0
	v_mov_b32_e32 v52, 0
	v_mov_b32_e32 v53, 0
	v_mov_b32_e32 v54, 0
	v_mov_b32_e32 v55, 0
	v_mov_b32_e32 v56, 0
	v_mov_b32_e32 v57, 0
	v_mov_b32_e32 v64, 0
	v_mov_b32_e32 v65, 0
	v_mov_b32_e32 v66, 0
	v_mov_b32_e32 v67, 0
	v_mov_b32_e32 v68, 0
	v_mov_b32_e32 v69, 0
	v_mov_b32_e32 v70, 0
	v_mov_b32_e32 v71, 0
	s_waitcnt vmcnt(29)
	v_lshlrev_b32_e32 v16, 16, v72
	v_and_b32_e32 v17, 0xffff0000, v72
	v_lshlrev_b32_e32 v18, 16, v73
	v_and_b32_e32 v19, 0xffff0000, v73
	v_lshlrev_b32_e32 v20, 16, v74
	v_and_b32_e32 v21, 0xffff0000, v74
	v_lshlrev_b32_e32 v22, 16, v75
	v_and_b32_e32 v23, 0xffff0000, v75
	v_add_u32_e32 v58, -12, v148
	v_cmp_gt_u32_e32 vcc, s10, v58
	s_and_b64 exec, vcc, s[98:99]
	v_pk_add_f32 v[64:65], v[64:65], v[16:17]
	v_pk_add_f32 v[66:67], v[66:67], v[18:19]
	v_pk_add_f32 v[68:69], v[68:69], v[20:21]
	v_pk_add_f32 v[70:71], v[70:71], v[22:23]
	s_mov_b64 exec, s[98:99]
	s_waitcnt vmcnt(28)
	v_lshlrev_b32_e32 v16, 16, v80
	v_and_b32_e32 v17, 0xffff0000, v80
	v_lshlrev_b32_e32 v18, 16, v81
	v_and_b32_e32 v19, 0xffff0000, v81
	v_lshlrev_b32_e32 v20, 16, v82
	v_and_b32_e32 v21, 0xffff0000, v82
	v_lshlrev_b32_e32 v22, 16, v83
	v_and_b32_e32 v23, 0xffff0000, v83
	v_add_u32_e32 v58, -12, v148
	v_cmp_gt_u32_e32 vcc, s10, v58
	s_and_b64 exec, vcc, s[98:99]
	v_pk_add_f32 v[50:51], v[50:51], v[16:17]
	v_pk_add_f32 v[52:53], v[52:53], v[18:19]
	v_pk_add_f32 v[54:55], v[54:55], v[20:21]
	v_pk_add_f32 v[56:57], v[56:57], v[22:23]
	s_mov_b64 exec, s[98:99]
	v_add_u32_e32 v58, -11, v148
	v_cmp_gt_u32_e32 vcc, s10, v58
	s_and_b64 exec, vcc, s[98:99]
	v_pk_add_f32 v[64:65], v[64:65], v[16:17]
	v_pk_add_f32 v[66:67], v[66:67], v[18:19]
	v_pk_add_f32 v[68:69], v[68:69], v[20:21]
	v_pk_add_f32 v[70:71], v[70:71], v[22:23]
	s_mov_b64 exec, s[98:99]
	s_waitcnt vmcnt(27)
	v_lshlrev_b32_e32 v16, 16, v92
	v_and_b32_e32 v17, 0xffff0000, v92
	v_lshlrev_b32_e32 v18, 16, v93
	v_and_b32_e32 v19, 0xffff0000, v93
	v_lshlrev_b32_e32 v20, 16, v94
	v_and_b32_e32 v21, 0xffff0000, v94
	v_lshlrev_b32_e32 v22, 16, v95
	v_and_b32_e32 v23, 0xffff0000, v95
	v_add_u32_e32 v58, -12, v148
	v_cmp_gt_u32_e32 vcc, s10, v58
	s_and_b64 exec, vcc, s[98:99]
	v_pk_add_f32 v[42:43], v[42:43], v[16:17]
	v_pk_add_f32 v[44:45], v[44:45], v[18:19]
	v_pk_add_f32 v[46:47], v[46:47], v[20:21]
	v_pk_add_f32 v[48:49], v[48:49], v[22:23]
	s_mov_b64 exec, s[98:99]
	v_add_u32_e32 v58, -11, v148
	v_cmp_gt_u32_e32 vcc, s10, v58
	s_and_b64 exec, vcc, s[98:99]
	v_pk_add_f32 v[50:51], v[50:51], v[16:17]
	v_pk_add_f32 v[52:53], v[52:53], v[18:19]
	v_pk_add_f32 v[54:55], v[54:55], v[20:21]
	v_pk_add_f32 v[56:57], v[56:57], v[22:23]
	s_mov_b64 exec, s[98:99]
	v_add_u32_e32 v58, -10, v148
	v_cmp_gt_u32_e32 vcc, s10, v58
	s_and_b64 exec, vcc, s[98:99]
	v_pk_add_f32 v[64:65], v[64:65], v[16:17]
	v_pk_add_f32 v[66:67], v[66:67], v[18:19]
	v_pk_add_f32 v[68:69], v[68:69], v[20:21]
	v_pk_add_f32 v[70:71], v[70:71], v[22:23]
	s_mov_b64 exec, s[98:99]
	s_waitcnt vmcnt(26)
	v_lshlrev_b32_e32 v16, 16, v96
	v_and_b32_e32 v17, 0xffff0000, v96
	v_lshlrev_b32_e32 v18, 16, v97
	v_and_b32_e32 v19, 0xffff0000, v97
	v_lshlrev_b32_e32 v20, 16, v98
	v_and_b32_e32 v21, 0xffff0000, v98
	v_lshlrev_b32_e32 v22, 16, v99
	v_and_b32_e32 v23, 0xffff0000, v99
	v_add_u32_e32 v58, -12, v148
	v_cmp_gt_u32_e32 vcc, s10, v58
	s_and_b64 exec, vcc, s[98:99]
	v_pk_add_f32 v[34:35], v[34:35], v[16:17]
	v_pk_add_f32 v[36:37], v[36:37], v[18:19]
	v_pk_add_f32 v[38:39], v[38:39], v[20:21]
	v_pk_add_f32 v[40:41], v[40:41], v[22:23]
	s_mov_b64 exec, s[98:99]
	v_add_u32_e32 v58, -11, v148
	v_cmp_gt_u32_e32 vcc, s10, v58
	s_and_b64 exec, vcc, s[98:99]
	v_pk_add_f32 v[42:43], v[42:43], v[16:17]
	v_pk_add_f32 v[44:45], v[44:45], v[18:19]
	v_pk_add_f32 v[46:47], v[46:47], v[20:21]
	v_pk_add_f32 v[48:49], v[48:49], v[22:23]
	s_mov_b64 exec, s[98:99]
	v_add_u32_e32 v58, -10, v148
	v_cmp_gt_u32_e32 vcc, s10, v58
	s_and_b64 exec, vcc, s[98:99]
	v_pk_add_f32 v[50:51], v[50:51], v[16:17]
	v_pk_add_f32 v[52:53], v[52:53], v[18:19]
	v_pk_add_f32 v[54:55], v[54:55], v[20:21]
	v_pk_add_f32 v[56:57], v[56:57], v[22:23]
	s_mov_b64 exec, s[98:99]
	v_add_u32_e32 v58, -9, v148
	v_cmp_gt_u32_e32 vcc, s10, v58
	s_and_b64 exec, vcc, s[98:99]
	v_pk_add_f32 v[64:65], v[64:65], v[16:17]
	v_pk_add_f32 v[66:67], v[66:67], v[18:19]
	v_pk_add_f32 v[68:69], v[68:69], v[20:21]
	v_pk_add_f32 v[70:71], v[70:71], v[22:23]
	s_mov_b64 exec, s[98:99]
	s_waitcnt vmcnt(25)
	v_lshlrev_b32_e32 v16, 16, v100
	v_and_b32_e32 v17, 0xffff0000, v100
	v_lshlrev_b32_e32 v18, 16, v101
	v_and_b32_e32 v19, 0xffff0000, v101
	v_lshlrev_b32_e32 v20, 16, v102
	v_and_b32_e32 v21, 0xffff0000, v102
	v_lshlrev_b32_e32 v22, 16, v103
	v_and_b32_e32 v23, 0xffff0000, v103
	v_add_u32_e32 v58, -11, v148
	v_cmp_gt_u32_e32 vcc, s10, v58
	s_and_b64 exec, vcc, s[98:99]
	v_pk_add_f32 v[34:35], v[34:35], v[16:17]
	v_pk_add_f32 v[36:37], v[36:37], v[18:19]
	v_pk_add_f32 v[38:39], v[38:39], v[20:21]
	v_pk_add_f32 v[40:41], v[40:41], v[22:23]
	s_mov_b64 exec, s[98:99]
	v_add_u32_e32 v58, -10, v148
	v_cmp_gt_u32_e32 vcc, s10, v58
	s_and_b64 exec, vcc, s[98:99]
	v_pk_add_f32 v[42:43], v[42:43], v[16:17]
	v_pk_add_f32 v[44:45], v[44:45], v[18:19]
	v_pk_add_f32 v[46:47], v[46:47], v[20:21]
	v_pk_add_f32 v[48:49], v[48:49], v[22:23]
	s_mov_b64 exec, s[98:99]
	v_add_u32_e32 v58, -9, v148
	v_cmp_gt_u32_e32 vcc, s10, v58
	s_and_b64 exec, vcc, s[98:99]
	v_pk_add_f32 v[50:51], v[50:51], v[16:17]
	v_pk_add_f32 v[52:53], v[52:53], v[18:19]
	v_pk_add_f32 v[54:55], v[54:55], v[20:21]
	v_pk_add_f32 v[56:57], v[56:57], v[22:23]
	s_mov_b64 exec, s[98:99]
	v_add_u32_e32 v58, -8, v148
	v_cmp_gt_u32_e32 vcc, s10, v58
	s_and_b64 exec, vcc, s[98:99]
	v_pk_add_f32 v[64:65], v[64:65], v[16:17]
	v_pk_add_f32 v[66:67], v[66:67], v[18:19]
	v_pk_add_f32 v[68:69], v[68:69], v[20:21]
	v_pk_add_f32 v[70:71], v[70:71], v[22:23]
	s_mov_b64 exec, s[98:99]
	s_waitcnt vmcnt(24)
	v_lshlrev_b32_e32 v16, 16, v104
	v_and_b32_e32 v17, 0xffff0000, v104
	v_lshlrev_b32_e32 v18, 16, v105
	v_and_b32_e32 v19, 0xffff0000, v105
	v_lshlrev_b32_e32 v20, 16, v106
	v_and_b32_e32 v21, 0xffff0000, v106
	v_lshlrev_b32_e32 v22, 16, v107
	v_and_b32_e32 v23, 0xffff0000, v107
	v_add_u32_e32 v58, -10, v148
	v_cmp_gt_u32_e32 vcc, s10, v58
	s_and_b64 exec, vcc, s[98:99]
	v_pk_add_f32 v[34:35], v[34:35], v[16:17]
	v_pk_add_f32 v[36:37], v[36:37], v[18:19]
	v_pk_add_f32 v[38:39], v[38:39], v[20:21]
	v_pk_add_f32 v[40:41], v[40:41], v[22:23]
	s_mov_b64 exec, s[98:99]
	v_add_u32_e32 v58, -9, v148
	v_cmp_gt_u32_e32 vcc, s10, v58
	s_and_b64 exec, vcc, s[98:99]
	v_pk_add_f32 v[42:43], v[42:43], v[16:17]
	v_pk_add_f32 v[44:45], v[44:45], v[18:19]
	v_pk_add_f32 v[46:47], v[46:47], v[20:21]
	v_pk_add_f32 v[48:49], v[48:49], v[22:23]
	s_mov_b64 exec, s[98:99]
	v_add_u32_e32 v58, -8, v148
	v_cmp_gt_u32_e32 vcc, s10, v58
	s_and_b64 exec, vcc, s[98:99]
	v_pk_add_f32 v[50:51], v[50:51], v[16:17]
	v_pk_add_f32 v[52:53], v[52:53], v[18:19]
	v_pk_add_f32 v[54:55], v[54:55], v[20:21]
	v_pk_add_f32 v[56:57], v[56:57], v[22:23]
	s_mov_b64 exec, s[98:99]
	v_add_u32_e32 v58, -7, v148
	v_cmp_gt_u32_e32 vcc, s10, v58
	s_and_b64 exec, vcc, s[98:99]
	v_pk_add_f32 v[64:65], v[64:65], v[16:17]
	v_pk_add_f32 v[66:67], v[66:67], v[18:19]
	v_pk_add_f32 v[68:69], v[68:69], v[20:21]
	v_pk_add_f32 v[70:71], v[70:71], v[22:23]
	s_mov_b64 exec, s[98:99]
	s_waitcnt vmcnt(23)
	v_lshlrev_b32_e32 v16, 16, v108
	v_and_b32_e32 v17, 0xffff0000, v108
	v_lshlrev_b32_e32 v18, 16, v109
	v_and_b32_e32 v19, 0xffff0000, v109
	v_lshlrev_b32_e32 v20, 16, v110
	v_and_b32_e32 v21, 0xffff0000, v110
	v_lshlrev_b32_e32 v22, 16, v111
	v_and_b32_e32 v23, 0xffff0000, v111
	v_add_u32_e32 v58, -9, v148
	v_cmp_gt_u32_e32 vcc, s10, v58
	s_and_b64 exec, vcc, s[98:99]
	v_pk_add_f32 v[34:35], v[34:35], v[16:17]
	v_pk_add_f32 v[36:37], v[36:37], v[18:19]
	v_pk_add_f32 v[38:39], v[38:39], v[20:21]
	v_pk_add_f32 v[40:41], v[40:41], v[22:23]
	s_mov_b64 exec, s[98:99]
	v_add_u32_e32 v58, -8, v148
	v_cmp_gt_u32_e32 vcc, s10, v58
	s_and_b64 exec, vcc, s[98:99]
	v_pk_add_f32 v[42:43], v[42:43], v[16:17]
	v_pk_add_f32 v[44:45], v[44:45], v[18:19]
	v_pk_add_f32 v[46:47], v[46:47], v[20:21]
	v_pk_add_f32 v[48:49], v[48:49], v[22:23]
	s_mov_b64 exec, s[98:99]
	v_add_u32_e32 v58, -7, v148
	v_cmp_gt_u32_e32 vcc, s10, v58
	s_and_b64 exec, vcc, s[98:99]
	v_pk_add_f32 v[50:51], v[50:51], v[16:17]
	v_pk_add_f32 v[52:53], v[52:53], v[18:19]
	v_pk_add_f32 v[54:55], v[54:55], v[20:21]
	v_pk_add_f32 v[56:57], v[56:57], v[22:23]
	s_mov_b64 exec, s[98:99]
	v_add_u32_e32 v58, -6, v148
	v_cmp_gt_u32_e32 vcc, s10, v58
	s_and_b64 exec, vcc, s[98:99]
	v_pk_add_f32 v[64:65], v[64:65], v[16:17]
	v_pk_add_f32 v[66:67], v[66:67], v[18:19]
	v_pk_add_f32 v[68:69], v[68:69], v[20:21]
	v_pk_add_f32 v[70:71], v[70:71], v[22:23]
	s_mov_b64 exec, s[98:99]
	s_waitcnt vmcnt(22)
	v_lshlrev_b32_e32 v16, 16, v112
	v_and_b32_e32 v17, 0xffff0000, v112
	v_lshlrev_b32_e32 v18, 16, v113
	v_and_b32_e32 v19, 0xffff0000, v113
	v_lshlrev_b32_e32 v20, 16, v114
	v_and_b32_e32 v21, 0xffff0000, v114
	v_lshlrev_b32_e32 v22, 16, v115
	v_and_b32_e32 v23, 0xffff0000, v115
	v_add_u32_e32 v58, -8, v148
	v_cmp_gt_u32_e32 vcc, s10, v58
	s_and_b64 exec, vcc, s[98:99]
	v_pk_add_f32 v[34:35], v[34:35], v[16:17]
	v_pk_add_f32 v[36:37], v[36:37], v[18:19]
	v_pk_add_f32 v[38:39], v[38:39], v[20:21]
	v_pk_add_f32 v[40:41], v[40:41], v[22:23]
	s_mov_b64 exec, s[98:99]
	v_add_u32_e32 v58, -7, v148
	v_cmp_gt_u32_e32 vcc, s10, v58
	s_and_b64 exec, vcc, s[98:99]
	v_pk_add_f32 v[42:43], v[42:43], v[16:17]
	v_pk_add_f32 v[44:45], v[44:45], v[18:19]
	v_pk_add_f32 v[46:47], v[46:47], v[20:21]
	v_pk_add_f32 v[48:49], v[48:49], v[22:23]
	s_mov_b64 exec, s[98:99]
	v_add_u32_e32 v58, -6, v148
	v_cmp_gt_u32_e32 vcc, s10, v58
	s_and_b64 exec, vcc, s[98:99]
	v_pk_add_f32 v[50:51], v[50:51], v[16:17]
	v_pk_add_f32 v[52:53], v[52:53], v[18:19]
	v_pk_add_f32 v[54:55], v[54:55], v[20:21]
	v_pk_add_f32 v[56:57], v[56:57], v[22:23]
	s_mov_b64 exec, s[98:99]
	v_add_u32_e32 v58, -5, v148
	v_cmp_gt_u32_e32 vcc, s10, v58
	s_and_b64 exec, vcc, s[98:99]
	v_pk_add_f32 v[64:65], v[64:65], v[16:17]
	v_pk_add_f32 v[66:67], v[66:67], v[18:19]
	v_pk_add_f32 v[68:69], v[68:69], v[20:21]
	v_pk_add_f32 v[70:71], v[70:71], v[22:23]
	s_mov_b64 exec, s[98:99]
	s_waitcnt vmcnt(21)
	v_lshlrev_b32_e32 v16, 16, v116
	v_and_b32_e32 v17, 0xffff0000, v116
	v_lshlrev_b32_e32 v18, 16, v117
	v_and_b32_e32 v19, 0xffff0000, v117
	v_lshlrev_b32_e32 v20, 16, v118
	v_and_b32_e32 v21, 0xffff0000, v118
	v_lshlrev_b32_e32 v22, 16, v119
	v_and_b32_e32 v23, 0xffff0000, v119
	v_add_u32_e32 v58, -7, v148
	v_cmp_gt_u32_e32 vcc, s10, v58
	s_and_b64 exec, vcc, s[98:99]
	v_pk_add_f32 v[34:35], v[34:35], v[16:17]
	v_pk_add_f32 v[36:37], v[36:37], v[18:19]
	v_pk_add_f32 v[38:39], v[38:39], v[20:21]
	v_pk_add_f32 v[40:41], v[40:41], v[22:23]
	s_mov_b64 exec, s[98:99]
	v_add_u32_e32 v58, -6, v148
	v_cmp_gt_u32_e32 vcc, s10, v58
	s_and_b64 exec, vcc, s[98:99]
	v_pk_add_f32 v[42:43], v[42:43], v[16:17]
	v_pk_add_f32 v[44:45], v[44:45], v[18:19]
	v_pk_add_f32 v[46:47], v[46:47], v[20:21]
	v_pk_add_f32 v[48:49], v[48:49], v[22:23]
	s_mov_b64 exec, s[98:99]
	v_add_u32_e32 v58, -5, v148
	v_cmp_gt_u32_e32 vcc, s10, v58
	s_and_b64 exec, vcc, s[98:99]
	v_pk_add_f32 v[50:51], v[50:51], v[16:17]
	v_pk_add_f32 v[52:53], v[52:53], v[18:19]
	v_pk_add_f32 v[54:55], v[54:55], v[20:21]
	v_pk_add_f32 v[56:57], v[56:57], v[22:23]
	s_mov_b64 exec, s[98:99]
	v_add_u32_e32 v58, -4, v148
	v_cmp_gt_u32_e32 vcc, s10, v58
	s_and_b64 exec, vcc, s[98:99]
	v_pk_add_f32 v[64:65], v[64:65], v[16:17]
	v_pk_add_f32 v[66:67], v[66:67], v[18:19]
	v_pk_add_f32 v[68:69], v[68:69], v[20:21]
	v_pk_add_f32 v[70:71], v[70:71], v[22:23]
	s_mov_b64 exec, s[98:99]
	s_waitcnt vmcnt(20)
	v_lshlrev_b32_e32 v16, 16, v120
	v_and_b32_e32 v17, 0xffff0000, v120
	v_lshlrev_b32_e32 v18, 16, v121
	v_and_b32_e32 v19, 0xffff0000, v121
	v_lshlrev_b32_e32 v20, 16, v122
	v_and_b32_e32 v21, 0xffff0000, v122
	v_lshlrev_b32_e32 v22, 16, v123
	v_and_b32_e32 v23, 0xffff0000, v123
	v_add_u32_e32 v58, -6, v148
	v_cmp_gt_u32_e32 vcc, s10, v58
	s_and_b64 exec, vcc, s[98:99]
	v_pk_add_f32 v[34:35], v[34:35], v[16:17]
	v_pk_add_f32 v[36:37], v[36:37], v[18:19]
	v_pk_add_f32 v[38:39], v[38:39], v[20:21]
	v_pk_add_f32 v[40:41], v[40:41], v[22:23]
	s_mov_b64 exec, s[98:99]
	v_add_u32_e32 v58, -5, v148
	v_cmp_gt_u32_e32 vcc, s10, v58
	s_and_b64 exec, vcc, s[98:99]
	v_pk_add_f32 v[42:43], v[42:43], v[16:17]
	v_pk_add_f32 v[44:45], v[44:45], v[18:19]
	v_pk_add_f32 v[46:47], v[46:47], v[20:21]
	v_pk_add_f32 v[48:49], v[48:49], v[22:23]
	s_mov_b64 exec, s[98:99]
	v_add_u32_e32 v58, -4, v148
	v_cmp_gt_u32_e32 vcc, s10, v58
	s_and_b64 exec, vcc, s[98:99]
	v_pk_add_f32 v[50:51], v[50:51], v[16:17]
	v_pk_add_f32 v[52:53], v[52:53], v[18:19]
	v_pk_add_f32 v[54:55], v[54:55], v[20:21]
	v_pk_add_f32 v[56:57], v[56:57], v[22:23]
	s_mov_b64 exec, s[98:99]
	v_add_u32_e32 v58, -3, v148
	v_cmp_gt_u32_e32 vcc, s10, v58
	s_and_b64 exec, vcc, s[98:99]
	v_pk_add_f32 v[64:65], v[64:65], v[16:17]
	v_pk_add_f32 v[66:67], v[66:67], v[18:19]
	v_pk_add_f32 v[68:69], v[68:69], v[20:21]
	v_pk_add_f32 v[70:71], v[70:71], v[22:23]
	s_mov_b64 exec, s[98:99]
	s_waitcnt vmcnt(19)
	v_lshlrev_b32_e32 v16, 16, v124
	v_and_b32_e32 v17, 0xffff0000, v124
	v_lshlrev_b32_e32 v18, 16, v125
	v_and_b32_e32 v19, 0xffff0000, v125
	v_lshlrev_b32_e32 v20, 16, v126
	v_and_b32_e32 v21, 0xffff0000, v126
	v_lshlrev_b32_e32 v22, 16, v127
	v_and_b32_e32 v23, 0xffff0000, v127
	v_add_u32_e32 v58, -5, v148
	v_cmp_gt_u32_e32 vcc, s10, v58
	s_and_b64 exec, vcc, s[98:99]
	v_pk_add_f32 v[34:35], v[34:35], v[16:17]
	v_pk_add_f32 v[36:37], v[36:37], v[18:19]
	v_pk_add_f32 v[38:39], v[38:39], v[20:21]
	v_pk_add_f32 v[40:41], v[40:41], v[22:23]
	s_mov_b64 exec, s[98:99]
	v_add_u32_e32 v58, -4, v148
	v_cmp_gt_u32_e32 vcc, s10, v58
	s_and_b64 exec, vcc, s[98:99]
	v_pk_add_f32 v[42:43], v[42:43], v[16:17]
	v_pk_add_f32 v[44:45], v[44:45], v[18:19]
	v_pk_add_f32 v[46:47], v[46:47], v[20:21]
	v_pk_add_f32 v[48:49], v[48:49], v[22:23]
	s_mov_b64 exec, s[98:99]
	v_add_u32_e32 v58, -3, v148
	v_cmp_gt_u32_e32 vcc, s10, v58
	s_and_b64 exec, vcc, s[98:99]
	v_pk_add_f32 v[50:51], v[50:51], v[16:17]
	v_pk_add_f32 v[52:53], v[52:53], v[18:19]
	v_pk_add_f32 v[54:55], v[54:55], v[20:21]
	v_pk_add_f32 v[56:57], v[56:57], v[22:23]
	s_mov_b64 exec, s[98:99]
	v_add_u32_e32 v58, -2, v148
	v_cmp_gt_u32_e32 vcc, s10, v58
	s_and_b64 exec, vcc, s[98:99]
	v_pk_add_f32 v[64:65], v[64:65], v[16:17]
	v_pk_add_f32 v[66:67], v[66:67], v[18:19]
	v_pk_add_f32 v[68:69], v[68:69], v[20:21]
	v_pk_add_f32 v[70:71], v[70:71], v[22:23]
	s_mov_b64 exec, s[98:99]
	s_waitcnt vmcnt(18)
	v_lshlrev_b32_e32 v16, 16, v128
	v_and_b32_e32 v17, 0xffff0000, v128
	v_lshlrev_b32_e32 v18, 16, v129
	v_and_b32_e32 v19, 0xffff0000, v129
	v_lshlrev_b32_e32 v20, 16, v130
	v_and_b32_e32 v21, 0xffff0000, v130
	v_lshlrev_b32_e32 v22, 16, v131
	v_and_b32_e32 v23, 0xffff0000, v131
	v_add_u32_e32 v58, -4, v148
	v_cmp_gt_u32_e32 vcc, s10, v58
	s_and_b64 exec, vcc, s[98:99]
	v_pk_add_f32 v[34:35], v[34:35], v[16:17]
	v_pk_add_f32 v[36:37], v[36:37], v[18:19]
	v_pk_add_f32 v[38:39], v[38:39], v[20:21]
	v_pk_add_f32 v[40:41], v[40:41], v[22:23]
	s_mov_b64 exec, s[98:99]
	v_add_u32_e32 v58, -3, v148
	v_cmp_gt_u32_e32 vcc, s10, v58
	s_and_b64 exec, vcc, s[98:99]
	v_pk_add_f32 v[42:43], v[42:43], v[16:17]
	v_pk_add_f32 v[44:45], v[44:45], v[18:19]
	v_pk_add_f32 v[46:47], v[46:47], v[20:21]
	v_pk_add_f32 v[48:49], v[48:49], v[22:23]
	s_mov_b64 exec, s[98:99]
	v_add_u32_e32 v58, -2, v148
	v_cmp_gt_u32_e32 vcc, s10, v58
	s_and_b64 exec, vcc, s[98:99]
	v_pk_add_f32 v[50:51], v[50:51], v[16:17]
	v_pk_add_f32 v[52:53], v[52:53], v[18:19]
	v_pk_add_f32 v[54:55], v[54:55], v[20:21]
	v_pk_add_f32 v[56:57], v[56:57], v[22:23]
	s_mov_b64 exec, s[98:99]
	v_add_u32_e32 v58, -1, v148
	v_cmp_gt_u32_e32 vcc, s10, v58
	s_and_b64 exec, vcc, s[98:99]
	v_pk_add_f32 v[64:65], v[64:65], v[16:17]
	v_pk_add_f32 v[66:67], v[66:67], v[18:19]
	v_pk_add_f32 v[68:69], v[68:69], v[20:21]
	v_pk_add_f32 v[70:71], v[70:71], v[22:23]
	s_mov_b64 exec, s[98:99]
	s_waitcnt vmcnt(17)
	v_lshlrev_b32_e32 v16, 16, v132
	v_and_b32_e32 v17, 0xffff0000, v132
	v_lshlrev_b32_e32 v18, 16, v133
	v_and_b32_e32 v19, 0xffff0000, v133
	v_lshlrev_b32_e32 v20, 16, v134
	v_and_b32_e32 v21, 0xffff0000, v134
	v_lshlrev_b32_e32 v22, 16, v135
	v_and_b32_e32 v23, 0xffff0000, v135
	v_add_u32_e32 v58, -3, v148
	v_cmp_gt_u32_e32 vcc, s10, v58
	s_and_b64 exec, vcc, s[98:99]
	v_pk_add_f32 v[34:35], v[34:35], v[16:17]
	v_pk_add_f32 v[36:37], v[36:37], v[18:19]
	v_pk_add_f32 v[38:39], v[38:39], v[20:21]
	v_pk_add_f32 v[40:41], v[40:41], v[22:23]
	s_mov_b64 exec, s[98:99]
	v_add_u32_e32 v58, -2, v148
	v_cmp_gt_u32_e32 vcc, s10, v58
	s_and_b64 exec, vcc, s[98:99]
	v_pk_add_f32 v[42:43], v[42:43], v[16:17]
	v_pk_add_f32 v[44:45], v[44:45], v[18:19]
	v_pk_add_f32 v[46:47], v[46:47], v[20:21]
	v_pk_add_f32 v[48:49], v[48:49], v[22:23]
	s_mov_b64 exec, s[98:99]
	v_add_u32_e32 v58, -1, v148
	v_cmp_gt_u32_e32 vcc, s10, v58
	s_and_b64 exec, vcc, s[98:99]
	v_pk_add_f32 v[50:51], v[50:51], v[16:17]
	v_pk_add_f32 v[52:53], v[52:53], v[18:19]
	v_pk_add_f32 v[54:55], v[54:55], v[20:21]
	v_pk_add_f32 v[56:57], v[56:57], v[22:23]
	s_mov_b64 exec, s[98:99]
	v_add_u32_e32 v58, 0, v148
	v_cmp_gt_u32_e32 vcc, s10, v58
	s_and_b64 exec, vcc, s[98:99]
	v_pk_add_f32 v[64:65], v[64:65], v[16:17]
	v_pk_add_f32 v[66:67], v[66:67], v[18:19]
	v_pk_add_f32 v[68:69], v[68:69], v[20:21]
	v_pk_add_f32 v[70:71], v[70:71], v[22:23]
	s_mov_b64 exec, s[98:99]
	s_waitcnt vmcnt(16)
	v_lshlrev_b32_e32 v16, 16, v136
	v_and_b32_e32 v17, 0xffff0000, v136
	v_lshlrev_b32_e32 v18, 16, v137
	v_and_b32_e32 v19, 0xffff0000, v137
	v_lshlrev_b32_e32 v20, 16, v138
	v_and_b32_e32 v21, 0xffff0000, v138
	v_lshlrev_b32_e32 v22, 16, v139
	v_and_b32_e32 v23, 0xffff0000, v139
	v_add_u32_e32 v58, -2, v148
	v_cmp_gt_u32_e32 vcc, s10, v58
	s_and_b64 exec, vcc, s[98:99]
	v_pk_add_f32 v[34:35], v[34:35], v[16:17]
	v_pk_add_f32 v[36:37], v[36:37], v[18:19]
	v_pk_add_f32 v[38:39], v[38:39], v[20:21]
	v_pk_add_f32 v[40:41], v[40:41], v[22:23]
	s_mov_b64 exec, s[98:99]
	v_add_u32_e32 v58, -1, v148
	v_cmp_gt_u32_e32 vcc, s10, v58
	s_and_b64 exec, vcc, s[98:99]
	v_pk_add_f32 v[42:43], v[42:43], v[16:17]
	v_pk_add_f32 v[44:45], v[44:45], v[18:19]
	v_pk_add_f32 v[46:47], v[46:47], v[20:21]
	v_pk_add_f32 v[48:49], v[48:49], v[22:23]
	s_mov_b64 exec, s[98:99]
	v_add_u32_e32 v58, 0, v148
	v_cmp_gt_u32_e32 vcc, s10, v58
	s_and_b64 exec, vcc, s[98:99]
	v_pk_add_f32 v[50:51], v[50:51], v[16:17]
	v_pk_add_f32 v[52:53], v[52:53], v[18:19]
	v_pk_add_f32 v[54:55], v[54:55], v[20:21]
	v_pk_add_f32 v[56:57], v[56:57], v[22:23]
	s_mov_b64 exec, s[98:99]
	v_add_u32_e32 v58, 1, v148
	v_cmp_gt_u32_e32 vcc, s10, v58
	s_and_b64 exec, vcc, s[98:99]
	v_pk_add_f32 v[64:65], v[64:65], v[16:17]
	v_pk_add_f32 v[66:67], v[66:67], v[18:19]
	v_pk_add_f32 v[68:69], v[68:69], v[20:21]
	v_pk_add_f32 v[70:71], v[70:71], v[22:23]
	s_mov_b64 exec, s[98:99]
	s_waitcnt vmcnt(15)
	v_lshlrev_b32_e32 v16, 16, v176
	v_and_b32_e32 v17, 0xffff0000, v176
	v_lshlrev_b32_e32 v18, 16, v177
	v_and_b32_e32 v19, 0xffff0000, v177
	v_lshlrev_b32_e32 v20, 16, v178
	v_and_b32_e32 v21, 0xffff0000, v178
	v_lshlrev_b32_e32 v22, 16, v179
	v_and_b32_e32 v23, 0xffff0000, v179
	v_add_u32_e32 v58, -1, v148
	v_cmp_gt_u32_e32 vcc, s10, v58
	s_and_b64 exec, vcc, s[98:99]
	v_pk_add_f32 v[34:35], v[34:35], v[16:17]
	v_pk_add_f32 v[36:37], v[36:37], v[18:19]
	v_pk_add_f32 v[38:39], v[38:39], v[20:21]
	v_pk_add_f32 v[40:41], v[40:41], v[22:23]
	s_mov_b64 exec, s[98:99]
	v_add_u32_e32 v58, 0, v148
	v_cmp_gt_u32_e32 vcc, s10, v58
	s_and_b64 exec, vcc, s[98:99]
	v_pk_add_f32 v[42:43], v[42:43], v[16:17]
	v_pk_add_f32 v[44:45], v[44:45], v[18:19]
	v_pk_add_f32 v[46:47], v[46:47], v[20:21]
	v_pk_add_f32 v[48:49], v[48:49], v[22:23]
	s_mov_b64 exec, s[98:99]
	v_add_u32_e32 v58, 1, v148
	v_cmp_gt_u32_e32 vcc, s10, v58
	s_and_b64 exec, vcc, s[98:99]
	v_pk_add_f32 v[50:51], v[50:51], v[16:17]
	v_pk_add_f32 v[52:53], v[52:53], v[18:19]
	v_pk_add_f32 v[54:55], v[54:55], v[20:21]
	v_pk_add_f32 v[56:57], v[56:57], v[22:23]
	s_mov_b64 exec, s[98:99]
	v_add_u32_e32 v58, 2, v148
	v_cmp_gt_u32_e32 vcc, s10, v58
	s_and_b64 exec, vcc, s[98:99]
	v_pk_add_f32 v[64:65], v[64:65], v[16:17]
	v_pk_add_f32 v[66:67], v[66:67], v[18:19]
	v_pk_add_f32 v[68:69], v[68:69], v[20:21]
	v_pk_add_f32 v[70:71], v[70:71], v[22:23]
	s_mov_b64 exec, s[98:99]
	s_waitcnt vmcnt(14)
	v_lshlrev_b32_e32 v16, 16, v180
	v_and_b32_e32 v17, 0xffff0000, v180
	v_lshlrev_b32_e32 v18, 16, v181
	v_and_b32_e32 v19, 0xffff0000, v181
	v_lshlrev_b32_e32 v20, 16, v182
	v_and_b32_e32 v21, 0xffff0000, v182
	v_lshlrev_b32_e32 v22, 16, v183
	v_and_b32_e32 v23, 0xffff0000, v183
	v_add_u32_e32 v58, 0, v148
	v_cmp_gt_u32_e32 vcc, s10, v58
	s_and_b64 exec, vcc, s[98:99]
	v_pk_add_f32 v[34:35], v[34:35], v[16:17]
	v_pk_add_f32 v[36:37], v[36:37], v[18:19]
	v_pk_add_f32 v[38:39], v[38:39], v[20:21]
	v_pk_add_f32 v[40:41], v[40:41], v[22:23]
	s_mov_b64 exec, s[98:99]
	v_add_u32_e32 v58, 1, v148
	v_cmp_gt_u32_e32 vcc, s10, v58
	s_and_b64 exec, vcc, s[98:99]
	v_pk_add_f32 v[42:43], v[42:43], v[16:17]
	v_pk_add_f32 v[44:45], v[44:45], v[18:19]
	v_pk_add_f32 v[46:47], v[46:47], v[20:21]
	v_pk_add_f32 v[48:49], v[48:49], v[22:23]
	s_mov_b64 exec, s[98:99]
	v_add_u32_e32 v58, 2, v148
	v_cmp_gt_u32_e32 vcc, s10, v58
	s_and_b64 exec, vcc, s[98:99]
	v_pk_add_f32 v[50:51], v[50:51], v[16:17]
	v_pk_add_f32 v[52:53], v[52:53], v[18:19]
	v_pk_add_f32 v[54:55], v[54:55], v[20:21]
	v_pk_add_f32 v[56:57], v[56:57], v[22:23]
	s_mov_b64 exec, s[98:99]
	v_add_u32_e32 v58, 3, v148
	v_cmp_gt_u32_e32 vcc, s10, v58
	s_and_b64 exec, vcc, s[98:99]
	v_pk_add_f32 v[64:65], v[64:65], v[16:17]
	v_pk_add_f32 v[66:67], v[66:67], v[18:19]
	v_pk_add_f32 v[68:69], v[68:69], v[20:21]
	v_pk_add_f32 v[70:71], v[70:71], v[22:23]
	s_mov_b64 exec, s[98:99]
	v_add_co_u32_e32 v72, vcc, 0x3800, v14
	v_addc_co_u32_e32 v73, vcc, 0, v15, vcc
	global_load_dwordx4 v[80:83], v[72:73], off offset:16
	global_load_dwordx4 v[72:75], v[72:73], off
	v_add_co_u32_e32 v92, vcc, 0x3000, v14
	v_addc_co_u32_e32 v93, vcc, 0, v15, vcc
	global_load_dwordx4 v[96:99], v[92:93], off offset:16
	global_load_dwordx4 v[92:95], v[92:93], off
	v_add_co_u32_e32 v100, vcc, 0x2800, v14
	v_addc_co_u32_e32 v101, vcc, 0, v15, vcc
	global_load_dwordx4 v[104:107], v[100:101], off offset:16
	global_load_dwordx4 v[100:103], v[100:101], off
	v_add_co_u32_e32 v108, vcc, 0x2000, v14
	v_addc_co_u32_e32 v109, vcc, 0, v15, vcc
	global_load_dwordx4 v[112:115], v[108:109], off offset:16
	global_load_dwordx4 v[108:111], v[108:109], off
	v_add_co_u32_e32 v116, vcc, 0x1800, v14
	v_addc_co_u32_e32 v117, vcc, 0, v15, vcc
	global_load_dwordx4 v[120:123], v[116:117], off offset:16
	global_load_dwordx4 v[116:119], v[116:117], off
	v_add_co_u32_e32 v124, vcc, 0x1000, v14
	v_addc_co_u32_e32 v125, vcc, 0, v15, vcc
	global_load_dwordx4 v[128:131], v[124:125], off offset:16
	global_load_dwordx4 v[124:127], v[124:125], off
	v_add_co_u32_e32 v132, vcc, 0x800, v14
	v_addc_co_u32_e32 v133, vcc, 0, v15, vcc
	global_load_dwordx4 v[136:139], v[132:133], off offset:16
	global_load_dwordx4 v[132:135], v[132:133], off
	v_mov_b32_e32 v176, v14
	v_mov_b32_e32 v177, v15
	global_load_dwordx4 v[180:183], v[176:177], off offset:16
	global_load_dwordx4 v[176:179], v[176:177], off
	s_waitcnt vmcnt(28)
	v_add_u32_e32 v58, 1, v148
	v_cmp_gt_u32_e32 vcc, s10, v58
	s_and_b64 exec, vcc, s[98:99]
	v_pk_add_f32 v[34:35], v[34:35], v[184:185]
	v_pk_add_f32 v[36:37], v[36:37], v[186:187]
	v_pk_add_f32 v[38:39], v[38:39], v[188:189]
	v_pk_add_f32 v[40:41], v[40:41], v[190:191]
	s_mov_b64 exec, s[98:99]
	v_add_u32_e32 v58, 2, v148
	v_cmp_gt_u32_e32 vcc, s10, v58
	s_and_b64 exec, vcc, s[98:99]
	v_pk_add_f32 v[42:43], v[42:43], v[184:185]
	v_pk_add_f32 v[44:45], v[44:45], v[186:187]
	v_pk_add_f32 v[46:47], v[46:47], v[188:189]
	v_pk_add_f32 v[48:49], v[48:49], v[190:191]
	s_mov_b64 exec, s[98:99]
	v_add_u32_e32 v58, 3, v148
	v_cmp_gt_u32_e32 vcc, s10, v58
	s_and_b64 exec, vcc, s[98:99]
	v_pk_add_f32 v[50:51], v[50:51], v[184:185]
	v_pk_add_f32 v[52:53], v[52:53], v[186:187]
	v_pk_add_f32 v[54:55], v[54:55], v[188:189]
	v_pk_add_f32 v[56:57], v[56:57], v[190:191]
	s_mov_b64 exec, s[98:99]
	v_add_u32_e32 v58, 4, v148
	v_cmp_gt_u32_e32 vcc, s10, v58
	s_and_b64 exec, vcc, s[98:99]
	v_pk_add_f32 v[64:65], v[64:65], v[184:185]
	v_pk_add_f32 v[66:67], v[66:67], v[186:187]
	v_pk_add_f32 v[68:69], v[68:69], v[188:189]
	v_pk_add_f32 v[70:71], v[70:71], v[190:191]
	s_mov_b64 exec, s[98:99]
	s_cmp_lt_u32 s10, 4
	s_cbranch_scc1 ATS0_END
	s_waitcnt vmcnt(26)
	v_add_u32_e32 v58, 2, v148
	v_cmp_gt_u32_e32 vcc, s10, v58
	s_and_b64 exec, vcc, s[98:99]
	v_pk_add_f32 v[34:35], v[34:35], v[192:193]
	v_pk_add_f32 v[36:37], v[36:37], v[194:195]
	v_pk_add_f32 v[38:39], v[38:39], v[196:197]
	v_pk_add_f32 v[40:41], v[40:41], v[198:199]
	s_mov_b64 exec, s[98:99]
	v_add_u32_e32 v58, 3, v148
	v_cmp_gt_u32_e32 vcc, s10, v58
	s_and_b64 exec, vcc, s[98:99]
	v_pk_add_f32 v[42:43], v[42:43], v[192:193]
	v_pk_add_f32 v[44:45], v[44:45], v[194:195]
	v_pk_add_f32 v[46:47], v[46:47], v[196:197]
	v_pk_add_f32 v[48:49], v[48:49], v[198:199]
	s_mov_b64 exec, s[98:99]
	v_add_u32_e32 v58, 4, v148
	v_cmp_gt_u32_e32 vcc, s10, v58
	s_and_b64 exec, vcc, s[98:99]
	v_pk_add_f32 v[50:51], v[50:51], v[192:193]
	v_pk_add_f32 v[52:53], v[52:53], v[194:195]
	v_pk_add_f32 v[54:55], v[54:55], v[196:197]
	v_pk_add_f32 v[56:57], v[56:57], v[198:199]
	s_mov_b64 exec, s[98:99]
	v_add_u32_e32 v58, 5, v148
	v_cmp_gt_u32_e32 vcc, s10, v58
	s_and_b64 exec, vcc, s[98:99]
	v_pk_add_f32 v[64:65], v[64:65], v[192:193]
	v_pk_add_f32 v[66:67], v[66:67], v[194:195]
	v_pk_add_f32 v[68:69], v[68:69], v[196:197]
	v_pk_add_f32 v[70:71], v[70:71], v[198:199]
	s_mov_b64 exec, s[98:99]
	s_waitcnt vmcnt(24)
	v_add_u32_e32 v58, 3, v148
	v_cmp_gt_u32_e32 vcc, s10, v58
	s_and_b64 exec, vcc, s[98:99]
	v_pk_add_f32 v[34:35], v[34:35], v[200:201]
	v_pk_add_f32 v[36:37], v[36:37], v[202:203]
	v_pk_add_f32 v[38:39], v[38:39], v[218:219]
	v_pk_add_f32 v[40:41], v[40:41], v[220:221]
	s_mov_b64 exec, s[98:99]
	v_add_u32_e32 v58, 4, v148
	v_cmp_gt_u32_e32 vcc, s10, v58
	s_and_b64 exec, vcc, s[98:99]
	v_pk_add_f32 v[42:43], v[42:43], v[200:201]
	v_pk_add_f32 v[44:45], v[44:45], v[202:203]
	v_pk_add_f32 v[46:47], v[46:47], v[218:219]
	v_pk_add_f32 v[48:49], v[48:49], v[220:221]
	s_mov_b64 exec, s[98:99]
	v_add_u32_e32 v58, 5, v148
	v_cmp_gt_u32_e32 vcc, s10, v58
	s_and_b64 exec, vcc, s[98:99]
	v_pk_add_f32 v[50:51], v[50:51], v[200:201]
	v_pk_add_f32 v[52:53], v[52:53], v[202:203]
	v_pk_add_f32 v[54:55], v[54:55], v[218:219]
	v_pk_add_f32 v[56:57], v[56:57], v[220:221]
	s_mov_b64 exec, s[98:99]
	v_add_u32_e32 v58, 6, v148
	v_cmp_gt_u32_e32 vcc, s10, v58
	s_and_b64 exec, vcc, s[98:99]
	v_pk_add_f32 v[64:65], v[64:65], v[200:201]
	v_pk_add_f32 v[66:67], v[66:67], v[202:203]
	v_pk_add_f32 v[68:69], v[68:69], v[218:219]
	v_pk_add_f32 v[70:71], v[70:71], v[220:221]
	s_mov_b64 exec, s[98:99]
	s_cmp_lt_u32 s10, 5
	s_cbranch_scc1 ATS0_END
	s_waitcnt vmcnt(22)
	v_add_u32_e32 v58, 4, v148
	v_cmp_gt_u32_e32 vcc, s10, v58
	s_and_b64 exec, vcc, s[98:99]
	v_pk_add_f32 v[34:35], v[34:35], v[222:223]
	v_pk_add_f32 v[36:37], v[36:37], v[224:225]
	v_pk_add_f32 v[38:39], v[38:39], v[226:227]
	v_pk_add_f32 v[40:41], v[40:41], v[228:229]
	s_mov_b64 exec, s[98:99]
	v_add_u32_e32 v58, 5, v148
	v_cmp_gt_u32_e32 vcc, s10, v58
	s_and_b64 exec, vcc, s[98:99]
	v_pk_add_f32 v[42:43], v[42:43], v[222:223]
	v_pk_add_f32 v[44:45], v[44:45], v[224:225]
	v_pk_add_f32 v[46:47], v[46:47], v[226:227]
	v_pk_add_f32 v[48:49], v[48:49], v[228:229]
	s_mov_b64 exec, s[98:99]
	v_add_u32_e32 v58, 6, v148
	v_cmp_gt_u32_e32 vcc, s10, v58
	s_and_b64 exec, vcc, s[98:99]
	v_pk_add_f32 v[50:51], v[50:51], v[222:223]
	v_pk_add_f32 v[52:53], v[52:53], v[224:225]
	v_pk_add_f32 v[54:55], v[54:55], v[226:227]
	v_pk_add_f32 v[56:57], v[56:57], v[228:229]
	s_mov_b64 exec, s[98:99]
	v_add_u32_e32 v58, 7, v148
	v_cmp_gt_u32_e32 vcc, s10, v58
	s_and_b64 exec, vcc, s[98:99]
	v_pk_add_f32 v[64:65], v[64:65], v[222:223]
	v_pk_add_f32 v[66:67], v[66:67], v[224:225]
	v_pk_add_f32 v[68:69], v[68:69], v[226:227]
	v_pk_add_f32 v[70:71], v[70:71], v[228:229]
	s_mov_b64 exec, s[98:99]
	s_waitcnt vmcnt(20)
	v_add_u32_e32 v58, 5, v148
	v_cmp_gt_u32_e32 vcc, s10, v58
	s_and_b64 exec, vcc, s[98:99]
	v_pk_add_f32 v[34:35], v[34:35], v[230:231]
	v_pk_add_f32 v[36:37], v[36:37], v[232:233]
	v_pk_add_f32 v[38:39], v[38:39], v[236:237]
	v_pk_add_f32 v[40:41], v[40:41], v[238:239]
	s_mov_b64 exec, s[98:99]
	v_add_u32_e32 v58, 6, v148
	v_cmp_gt_u32_e32 vcc, s10, v58
	s_and_b64 exec, vcc, s[98:99]
	v_pk_add_f32 v[42:43], v[42:43], v[230:231]
	v_pk_add_f32 v[44:45], v[44:45], v[232:233]
	v_pk_add_f32 v[46:47], v[46:47], v[236:237]
	v_pk_add_f32 v[48:49], v[48:49], v[238:239]
	s_mov_b64 exec, s[98:99]
	v_add_u32_e32 v58, 7, v148
	v_cmp_gt_u32_e32 vcc, s10, v58
	s_and_b64 exec, vcc, s[98:99]
	v_pk_add_f32 v[50:51], v[50:51], v[230:231]
	v_pk_add_f32 v[52:53], v[52:53], v[232:233]
	v_pk_add_f32 v[54:55], v[54:55], v[236:237]
	v_pk_add_f32 v[56:57], v[56:57], v[238:239]
	s_mov_b64 exec, s[98:99]
	v_add_u32_e32 v58, 8, v148
	v_cmp_gt_u32_e32 vcc, s10, v58
	s_and_b64 exec, vcc, s[98:99]
	v_pk_add_f32 v[64:65], v[64:65], v[230:231]
	v_pk_add_f32 v[66:67], v[66:67], v[232:233]
	v_pk_add_f32 v[68:69], v[68:69], v[236:237]
	v_pk_add_f32 v[70:71], v[70:71], v[238:239]
	s_mov_b64 exec, s[98:99]
	s_waitcnt vmcnt(18)
	v_add_u32_e32 v58, 6, v148
	v_cmp_gt_u32_e32 vcc, s10, v58
	s_and_b64 exec, vcc, s[98:99]
	v_pk_add_f32 v[34:35], v[34:35], v[240:241]
	v_pk_add_f32 v[36:37], v[36:37], v[242:243]
	v_pk_add_f32 v[38:39], v[38:39], v[244:245]
	v_pk_add_f32 v[40:41], v[40:41], v[246:247]
	s_mov_b64 exec, s[98:99]
	v_add_u32_e32 v58, 7, v148
	v_cmp_gt_u32_e32 vcc, s10, v58
	s_and_b64 exec, vcc, s[98:99]
	v_pk_add_f32 v[42:43], v[42:43], v[240:241]
	v_pk_add_f32 v[44:45], v[44:45], v[242:243]
	v_pk_add_f32 v[46:47], v[46:47], v[244:245]
	v_pk_add_f32 v[48:49], v[48:49], v[246:247]
	s_mov_b64 exec, s[98:99]
	v_add_u32_e32 v58, 8, v148
	v_cmp_gt_u32_e32 vcc, s10, v58
	s_and_b64 exec, vcc, s[98:99]
	v_pk_add_f32 v[50:51], v[50:51], v[240:241]
	v_pk_add_f32 v[52:53], v[52:53], v[242:243]
	v_pk_add_f32 v[54:55], v[54:55], v[244:245]
	v_pk_add_f32 v[56:57], v[56:57], v[246:247]
	s_mov_b64 exec, s[98:99]
	v_add_u32_e32 v58, 9, v148
	v_cmp_gt_u32_e32 vcc, s10, v58
	s_and_b64 exec, vcc, s[98:99]
	v_pk_add_f32 v[64:65], v[64:65], v[240:241]
	v_pk_add_f32 v[66:67], v[66:67], v[242:243]
	v_pk_add_f32 v[68:69], v[68:69], v[244:245]
	v_pk_add_f32 v[70:71], v[70:71], v[246:247]
	s_mov_b64 exec, s[98:99]
	s_waitcnt vmcnt(16)
	v_add_u32_e32 v58, 7, v148
	v_cmp_gt_u32_e32 vcc, s10, v58
	s_and_b64 exec, vcc, s[98:99]
	v_pk_add_f32 v[34:35], v[34:35], v[248:249]
	v_pk_add_f32 v[36:37], v[36:37], v[250:251]
	v_pk_add_f32 v[38:39], v[38:39], v[252:253]
	v_pk_add_f32 v[40:41], v[40:41], v[254:255]
	s_mov_b64 exec, s[98:99]
	v_add_u32_e32 v58, 8, v148
	v_cmp_gt_u32_e32 vcc, s10, v58
	s_and_b64 exec, vcc, s[98:99]
	v_pk_add_f32 v[42:43], v[42:43], v[248:249]
	v_pk_add_f32 v[44:45], v[44:45], v[250:251]
	v_pk_add_f32 v[46:47], v[46:47], v[252:253]
	v_pk_add_f32 v[48:49], v[48:49], v[254:255]
	s_mov_b64 exec, s[98:99]
	v_add_u32_e32 v58, 9, v148
	v_cmp_gt_u32_e32 vcc, s10, v58
	s_and_b64 exec, vcc, s[98:99]
	v_pk_add_f32 v[50:51], v[50:51], v[248:249]
	v_pk_add_f32 v[52:53], v[52:53], v[250:251]
	v_pk_add_f32 v[54:55], v[54:55], v[252:253]
	v_pk_add_f32 v[56:57], v[56:57], v[254:255]
	s_mov_b64 exec, s[98:99]
	v_add_u32_e32 v58, 10, v148
	v_cmp_gt_u32_e32 vcc, s10, v58
	s_and_b64 exec, vcc, s[98:99]
	v_pk_add_f32 v[64:65], v[64:65], v[248:249]
	v_pk_add_f32 v[66:67], v[66:67], v[250:251]
	v_pk_add_f32 v[68:69], v[68:69], v[252:253]
	v_pk_add_f32 v[70:71], v[70:71], v[254:255]
	s_mov_b64 exec, s[98:99]
	s_cmp_lt_u32 s10, 9
	s_cbranch_scc1 ATS0_END
	s_waitcnt vmcnt(14)
	v_add_u32_e32 v58, 8, v148
	v_cmp_gt_u32_e32 vcc, s10, v58
	s_and_b64 exec, vcc, s[98:99]
	v_pk_add_f32 v[34:35], v[34:35], v[72:73]
	v_pk_add_f32 v[36:37], v[36:37], v[74:75]
	v_pk_add_f32 v[38:39], v[38:39], v[80:81]
	v_pk_add_f32 v[40:41], v[40:41], v[82:83]
	s_mov_b64 exec, s[98:99]
	v_add_u32_e32 v58, 9, v148
	v_cmp_gt_u32_e32 vcc, s10, v58
	s_and_b64 exec, vcc, s[98:99]
	v_pk_add_f32 v[42:43], v[42:43], v[72:73]
	v_pk_add_f32 v[44:45], v[44:45], v[74:75]
	v_pk_add_f32 v[46:47], v[46:47], v[80:81]
	v_pk_add_f32 v[48:49], v[48:49], v[82:83]
	s_mov_b64 exec, s[98:99]
	v_add_u32_e32 v58, 10, v148
	v_cmp_gt_u32_e32 vcc, s10, v58
	s_and_b64 exec, vcc, s[98:99]
	v_pk_add_f32 v[50:51], v[50:51], v[72:73]
	v_pk_add_f32 v[52:53], v[52:53], v[74:75]
	v_pk_add_f32 v[54:55], v[54:55], v[80:81]
	v_pk_add_f32 v[56:57], v[56:57], v[82:83]
	s_mov_b64 exec, s[98:99]
	v_add_u32_e32 v58, 11, v148
	v_cmp_gt_u32_e32 vcc, s10, v58
	s_and_b64 exec, vcc, s[98:99]
	v_pk_add_f32 v[64:65], v[64:65], v[72:73]
	v_pk_add_f32 v[66:67], v[66:67], v[74:75]
	v_pk_add_f32 v[68:69], v[68:69], v[80:81]
	v_pk_add_f32 v[70:71], v[70:71], v[82:83]
	s_mov_b64 exec, s[98:99]
	s_waitcnt vmcnt(12)
	v_add_u32_e32 v58, 9, v148
	v_cmp_gt_u32_e32 vcc, s10, v58
	s_and_b64 exec, vcc, s[98:99]
	v_pk_add_f32 v[34:35], v[34:35], v[92:93]
	v_pk_add_f32 v[36:37], v[36:37], v[94:95]
	v_pk_add_f32 v[38:39], v[38:39], v[96:97]
	v_pk_add_f32 v[40:41], v[40:41], v[98:99]
	s_mov_b64 exec, s[98:99]
	v_add_u32_e32 v58, 10, v148
	v_cmp_gt_u32_e32 vcc, s10, v58
	s_and_b64 exec, vcc, s[98:99]
	v_pk_add_f32 v[42:43], v[42:43], v[92:93]
	v_pk_add_f32 v[44:45], v[44:45], v[94:95]
	v_pk_add_f32 v[46:47], v[46:47], v[96:97]
	v_pk_add_f32 v[48:49], v[48:49], v[98:99]
	s_mov_b64 exec, s[98:99]
	v_add_u32_e32 v58, 11, v148
	v_cmp_gt_u32_e32 vcc, s10, v58
	s_and_b64 exec, vcc, s[98:99]
	v_pk_add_f32 v[50:51], v[50:51], v[92:93]
	v_pk_add_f32 v[52:53], v[52:53], v[94:95]
	v_pk_add_f32 v[54:55], v[54:55], v[96:97]
	v_pk_add_f32 v[56:57], v[56:57], v[98:99]
	s_mov_b64 exec, s[98:99]
	v_add_u32_e32 v58, 12, v148
	v_cmp_gt_u32_e32 vcc, s10, v58
	s_and_b64 exec, vcc, s[98:99]
	v_pk_add_f32 v[64:65], v[64:65], v[92:93]
	v_pk_add_f32 v[66:67], v[66:67], v[94:95]
	v_pk_add_f32 v[68:69], v[68:69], v[96:97]
	v_pk_add_f32 v[70:71], v[70:71], v[98:99]
	s_mov_b64 exec, s[98:99]
	s_waitcnt vmcnt(10)
	v_add_u32_e32 v58, 10, v148
	v_cmp_gt_u32_e32 vcc, s10, v58
	s_and_b64 exec, vcc, s[98:99]
	v_pk_add_f32 v[34:35], v[34:35], v[100:101]
	v_pk_add_f32 v[36:37], v[36:37], v[102:103]
	v_pk_add_f32 v[38:39], v[38:39], v[104:105]
	v_pk_add_f32 v[40:41], v[40:41], v[106:107]
	s_mov_b64 exec, s[98:99]
	v_add_u32_e32 v58, 11, v148
	v_cmp_gt_u32_e32 vcc, s10, v58
	s_and_b64 exec, vcc, s[98:99]
	v_pk_add_f32 v[42:43], v[42:43], v[100:101]
	v_pk_add_f32 v[44:45], v[44:45], v[102:103]
	v_pk_add_f32 v[46:47], v[46:47], v[104:105]
	v_pk_add_f32 v[48:49], v[48:49], v[106:107]
	s_mov_b64 exec, s[98:99]
	v_add_u32_e32 v58, 12, v148
	v_cmp_gt_u32_e32 vcc, s10, v58
	s_and_b64 exec, vcc, s[98:99]
	v_pk_add_f32 v[50:51], v[50:51], v[100:101]
	v_pk_add_f32 v[52:53], v[52:53], v[102:103]
	v_pk_add_f32 v[54:55], v[54:55], v[104:105]
	v_pk_add_f32 v[56:57], v[56:57], v[106:107]
	s_mov_b64 exec, s[98:99]
	v_add_u32_e32 v58, 13, v148
	v_cmp_gt_u32_e32 vcc, s10, v58
	s_and_b64 exec, vcc, s[98:99]
	v_pk_add_f32 v[64:65], v[64:65], v[100:101]
	v_pk_add_f32 v[66:67], v[66:67], v[102:103]
	v_pk_add_f32 v[68:69], v[68:69], v[104:105]
	v_pk_add_f32 v[70:71], v[70:71], v[106:107]
	s_mov_b64 exec, s[98:99]
	s_waitcnt vmcnt(8)
	v_add_u32_e32 v58, 11, v148
	v_cmp_gt_u32_e32 vcc, s10, v58
	s_and_b64 exec, vcc, s[98:99]
	v_pk_add_f32 v[34:35], v[34:35], v[108:109]
	v_pk_add_f32 v[36:37], v[36:37], v[110:111]
	v_pk_add_f32 v[38:39], v[38:39], v[112:113]
	v_pk_add_f32 v[40:41], v[40:41], v[114:115]
	s_mov_b64 exec, s[98:99]
	v_add_u32_e32 v58, 12, v148
	v_cmp_gt_u32_e32 vcc, s10, v58
	s_and_b64 exec, vcc, s[98:99]
	v_pk_add_f32 v[42:43], v[42:43], v[108:109]
	v_pk_add_f32 v[44:45], v[44:45], v[110:111]
	v_pk_add_f32 v[46:47], v[46:47], v[112:113]
	v_pk_add_f32 v[48:49], v[48:49], v[114:115]
	s_mov_b64 exec, s[98:99]
	v_add_u32_e32 v58, 13, v148
	v_cmp_gt_u32_e32 vcc, s10, v58
	s_and_b64 exec, vcc, s[98:99]
	v_pk_add_f32 v[50:51], v[50:51], v[108:109]
	v_pk_add_f32 v[52:53], v[52:53], v[110:111]
	v_pk_add_f32 v[54:55], v[54:55], v[112:113]
	v_pk_add_f32 v[56:57], v[56:57], v[114:115]
	s_mov_b64 exec, s[98:99]
	v_add_u32_e32 v58, 14, v148
	v_cmp_gt_u32_e32 vcc, s10, v58
	s_and_b64 exec, vcc, s[98:99]
	v_pk_add_f32 v[64:65], v[64:65], v[108:109]
	v_pk_add_f32 v[66:67], v[66:67], v[110:111]
	v_pk_add_f32 v[68:69], v[68:69], v[112:113]
	v_pk_add_f32 v[70:71], v[70:71], v[114:115]
	s_mov_b64 exec, s[98:99]
	s_waitcnt vmcnt(6)
	v_add_u32_e32 v58, 12, v148
	v_cmp_gt_u32_e32 vcc, s10, v58
	s_and_b64 exec, vcc, s[98:99]
	v_pk_add_f32 v[34:35], v[34:35], v[116:117]
	v_pk_add_f32 v[36:37], v[36:37], v[118:119]
	v_pk_add_f32 v[38:39], v[38:39], v[120:121]
	v_pk_add_f32 v[40:41], v[40:41], v[122:123]
	s_mov_b64 exec, s[98:99]
	v_add_u32_e32 v58, 13, v148
	v_cmp_gt_u32_e32 vcc, s10, v58
	s_and_b64 exec, vcc, s[98:99]
	v_pk_add_f32 v[42:43], v[42:43], v[116:117]
	v_pk_add_f32 v[44:45], v[44:45], v[118:119]
	v_pk_add_f32 v[46:47], v[46:47], v[120:121]
	v_pk_add_f32 v[48:49], v[48:49], v[122:123]
	s_mov_b64 exec, s[98:99]
	v_add_u32_e32 v58, 14, v148
	v_cmp_gt_u32_e32 vcc, s10, v58
	s_and_b64 exec, vcc, s[98:99]
	v_pk_add_f32 v[50:51], v[50:51], v[116:117]
	v_pk_add_f32 v[52:53], v[52:53], v[118:119]
	v_pk_add_f32 v[54:55], v[54:55], v[120:121]
	v_pk_add_f32 v[56:57], v[56:57], v[122:123]
	s_mov_b64 exec, s[98:99]
	v_add_u32_e32 v58, 15, v148
	v_cmp_gt_u32_e32 vcc, s10, v58
	s_and_b64 exec, vcc, s[98:99]
	v_pk_add_f32 v[64:65], v[64:65], v[116:117]
	v_pk_add_f32 v[66:67], v[66:67], v[118:119]
	v_pk_add_f32 v[68:69], v[68:69], v[120:121]
	v_pk_add_f32 v[70:71], v[70:71], v[122:123]
	s_mov_b64 exec, s[98:99]
	s_waitcnt vmcnt(4)
	v_add_u32_e32 v58, 13, v148
	v_cmp_gt_u32_e32 vcc, s10, v58
	s_and_b64 exec, vcc, s[98:99]
	v_pk_add_f32 v[34:35], v[34:35], v[124:125]
	v_pk_add_f32 v[36:37], v[36:37], v[126:127]
	v_pk_add_f32 v[38:39], v[38:39], v[128:129]
	v_pk_add_f32 v[40:41], v[40:41], v[130:131]
	s_mov_b64 exec, s[98:99]
	v_add_u32_e32 v58, 14, v148
	v_cmp_gt_u32_e32 vcc, s10, v58
	s_and_b64 exec, vcc, s[98:99]
	v_pk_add_f32 v[42:43], v[42:43], v[124:125]
	v_pk_add_f32 v[44:45], v[44:45], v[126:127]
	v_pk_add_f32 v[46:47], v[46:47], v[128:129]
	v_pk_add_f32 v[48:49], v[48:49], v[130:131]
	s_mov_b64 exec, s[98:99]
	v_add_u32_e32 v58, 15, v148
	v_cmp_gt_u32_e32 vcc, s10, v58
	s_and_b64 exec, vcc, s[98:99]
	v_pk_add_f32 v[50:51], v[50:51], v[124:125]
	v_pk_add_f32 v[52:53], v[52:53], v[126:127]
	v_pk_add_f32 v[54:55], v[54:55], v[128:129]
	v_pk_add_f32 v[56:57], v[56:57], v[130:131]
	s_mov_b64 exec, s[98:99]
	s_waitcnt vmcnt(2)
	v_add_u32_e32 v58, 14, v148
	v_cmp_gt_u32_e32 vcc, s10, v58
	s_and_b64 exec, vcc, s[98:99]
	v_pk_add_f32 v[34:35], v[34:35], v[132:133]
	v_pk_add_f32 v[36:37], v[36:37], v[134:135]
	v_pk_add_f32 v[38:39], v[38:39], v[136:137]
	v_pk_add_f32 v[40:41], v[40:41], v[138:139]
	s_mov_b64 exec, s[98:99]
	v_add_u32_e32 v58, 15, v148
	v_cmp_gt_u32_e32 vcc, s10, v58
	s_and_b64 exec, vcc, s[98:99]
	v_pk_add_f32 v[42:43], v[42:43], v[132:133]
	v_pk_add_f32 v[44:45], v[44:45], v[134:135]
	v_pk_add_f32 v[46:47], v[46:47], v[136:137]
	v_pk_add_f32 v[48:49], v[48:49], v[138:139]
	s_mov_b64 exec, s[98:99]
	s_waitcnt vmcnt(0)
	v_add_u32_e32 v58, 15, v148
	v_cmp_gt_u32_e32 vcc, s10, v58
	s_and_b64 exec, vcc, s[98:99]
	v_pk_add_f32 v[34:35], v[34:35], v[176:177]
	v_pk_add_f32 v[36:37], v[36:37], v[178:179]
	v_pk_add_f32 v[38:39], v[38:39], v[180:181]
	v_pk_add_f32 v[40:41], v[40:41], v[182:183]
	s_mov_b64 exec, s[98:99]
ATS0_END:
	s_waitcnt vmcnt(0)
	v_ffbl_b32_e32 v58, s10
	v_lshlrev_b32_e32 v58, 23, v58
	v_sub_u32_e32 v58, 0x3f800000, v58
	v_lshlrev_b32_e32 v72, 16, v0
	v_and_b32_e32 v73, 0xffff0000, v0
	v_lshlrev_b32_e32 v74, 16, v1
	v_and_b32_e32 v75, 0xffff0000, v1
	v_lshlrev_b32_e32 v80, 16, v2
	v_and_b32_e32 v81, 0xffff0000, v2
	v_lshlrev_b32_e32 v82, 16, v3
	v_and_b32_e32 v83, 0xffff0000, v3
	v_fma_f32 v72, v58, v34, -v72
	v_fma_f32 v73, v58, v35, -v73
	v_fma_f32 v74, v58, v36, -v74
	v_fma_f32 v75, v58, v37, -v75
	v_fma_f32 v80, v58, v38, -v80
	v_fma_f32 v81, v58, v39, -v81
	v_fma_f32 v82, v58, v40, -v82
	v_fma_f32 v83, v58, v41, -v83
	v_cvt_pk_bf16_f32 v12, v72, v73
	v_cvt_pk_bf16_f32 v13, v74, v75
	v_cvt_pk_bf16_f32 v14, v80, v81
	v_cvt_pk_bf16_f32 v15, v82, v83
	v_lshlrev_b32_e32 v72, 16, v4
	v_and_b32_e32 v73, 0xffff0000, v4
	v_lshlrev_b32_e32 v74, 16, v5
	v_and_b32_e32 v75, 0xffff0000, v5
	v_lshlrev_b32_e32 v80, 16, v6
	v_and_b32_e32 v81, 0xffff0000, v6
	v_lshlrev_b32_e32 v82, 16, v7
	v_and_b32_e32 v83, 0xffff0000, v7
	v_fma_f32 v72, v58, v42, -v72
	v_fma_f32 v73, v58, v43, -v73
	v_fma_f32 v74, v58, v44, -v74
	v_fma_f32 v75, v58, v45, -v75
	v_fma_f32 v80, v58, v46, -v80
	v_fma_f32 v81, v58, v47, -v81
	v_fma_f32 v82, v58, v48, -v82
	v_fma_f32 v83, v58, v49, -v83
	v_cvt_pk_bf16_f32 v16, v72, v73
	v_cvt_pk_bf16_f32 v17, v74, v75
	v_cvt_pk_bf16_f32 v18, v80, v81
	v_cvt_pk_bf16_f32 v19, v82, v83
	v_lshlrev_b32_e32 v72, 16, v8
	v_and_b32_e32 v73, 0xffff0000, v8
	v_lshlrev_b32_e32 v74, 16, v9
	v_and_b32_e32 v75, 0xffff0000, v9
	v_lshlrev_b32_e32 v80, 16, v10
	v_and_b32_e32 v81, 0xffff0000, v10
	v_lshlrev_b32_e32 v82, 16, v11
	v_and_b32_e32 v83, 0xffff0000, v11
	v_fma_f32 v72, v58, v50, -v72
	v_fma_f32 v73, v58, v51, -v73
	v_fma_f32 v74, v58, v52, -v74
	v_fma_f32 v75, v58, v53, -v75
	v_fma_f32 v80, v58, v54, -v80
	v_fma_f32 v81, v58, v55, -v81
	v_fma_f32 v82, v58, v56, -v82
	v_fma_f32 v83, v58, v57, -v83
	v_cvt_pk_bf16_f32 v20, v72, v73
	v_cvt_pk_bf16_f32 v21, v74, v75
	v_cvt_pk_bf16_f32 v22, v80, v81
	v_cvt_pk_bf16_f32 v23, v82, v83
	v_lshlrev_b32_e32 v72, 16, v24
	v_and_b32_e32 v73, 0xffff0000, v24
	v_lshlrev_b32_e32 v74, 16, v25
	v_and_b32_e32 v75, 0xffff0000, v25
	v_lshlrev_b32_e32 v80, 16, v26
	v_and_b32_e32 v81, 0xffff0000, v26
	v_lshlrev_b32_e32 v82, 16, v27
	v_and_b32_e32 v83, 0xffff0000, v27
	v_fma_f32 v72, v58, v64, -v72
	v_fma_f32 v73, v58, v65, -v73
	v_fma_f32 v74, v58, v66, -v74
	v_fma_f32 v75, v58, v67, -v75
	v_fma_f32 v80, v58, v68, -v80
	v_fma_f32 v81, v58, v69, -v81
	v_fma_f32 v82, v58, v70, -v82
	v_fma_f32 v83, v58, v71, -v83
	v_cvt_pk_bf16_f32 v28, v72, v73
	v_cvt_pk_bf16_f32 v29, v74, v75
	v_cvt_pk_bf16_f32 v30, v80, v81
	v_cvt_pk_bf16_f32 v31, v82, v83
	s_branch .LBB0_301

.LBB0_983:
	s_and_b64 vcc, exec, s[0:1]
	s_cbranch_vccz .LBB0_1009
	s_lshl_b64 s[0:1], s[24:25], 2
	s_add_u32 s0, s56, s0
	s_addc_u32 s1, s57, s1
	v_mov_b32_e32 v8, 0
	s_lshl_b32 s9, 2, s6
	v_lshl_add_u64 v[28:29], v[32:33], 1, s[52:53]
	v_lshl_add_u64 v[30:31], v[32:33], 2, s[0:1]
	v_add_u32_e32 v12, s29, v150
	s_mov_b64 s[98:99], exec
	v_mov_b32_e32 v12, v28
	v_mov_b32_e32 v13, v29
	v_mov_b32_e32 v14, v30
	v_mov_b32_e32 v15, v31
	v_mov_b32_e32 v59, s29
	v_add3_u32 v58, v150, v59, 0
	v_mad_u64_u32 v[0:1], vcc, v58, s27, v[12:13]
	global_load_dwordx4 v[0:3], v[0:1], off
	v_add3_u32 v58, v150, v59, 1
	v_mad_u64_u32 v[4:5], vcc, v58, s27, v[12:13]
	global_load_dwordx4 v[4:7], v[4:5], off
	v_add3_u32 v58, v150, v59, 2
	v_mad_u64_u32 v[8:9], vcc, v58, s27, v[12:13]
	global_load_dwordx4 v[8:11], v[8:9], off
	v_add3_u32 v58, v150, v59, 3
	v_mad_u64_u32 v[24:25], vcc, v58, s27, v[12:13]
	global_load_dwordx4 v[24:27], v[24:25], off
	v_add_u32_e32 v58, 15, v59
	v_mad_u64_u32 v[72:73], vcc, v58, s27, v[12:13]
	global_load_dwordx4 v[72:75], v[72:73], off
	v_add_u32_e32 v58, 14, v59
	v_mad_u64_u32 v[80:81], vcc, v58, s27, v[12:13]
	global_load_dwordx4 v[80:83], v[80:81], off
	v_add_u32_e32 v58, 13, v59
	v_mad_u64_u32 v[92:93], vcc, v58, s27, v[12:13]
	global_load_dwordx4 v[92:95], v[92:93], off
	v_add_u32_e32 v58, 12, v59
	v_mad_u64_u32 v[96:97], vcc, v58, s27, v[12:13]
	global_load_dwordx4 v[96:99], v[96:97], off
	v_add_u32_e32 v58, 11, v59
	v_mad_u64_u32 v[100:101], vcc, v58, s27, v[12:13]
	global_load_dwordx4 v[100:103], v[100:101], off
	v_add_u32_e32 v58, 10, v59
	v_mad_u64_u32 v[104:105], vcc, v58, s27, v[12:13]
	global_load_dwordx4 v[104:107], v[104:105], off
	v_add_u32_e32 v58, 9, v59
	v_mad_u64_u32 v[108:109], vcc, v58, s27, v[12:13]
	global_load_dwordx4 v[108:111], v[108:109], off
	v_add_u32_e32 v58, 8, v59
	v_mad_u64_u32 v[112:113], vcc, v58, s27, v[12:13]
	global_load_dwordx4 v[112:115], v[112:113], off
	v_add_u32_e32 v58, 7, v59
	v_mad_u64_u32 v[116:117], vcc, v58, s27, v[12:13]
	global_load_dwordx4 v[116:119], v[116:117], off
	v_add_u32_e32 v58, 6, v59
	v_mad_u64_u32 v[120:121], vcc, v58, s27, v[12:13]
	global_load_dwordx4 v[120:123], v[120:121], off
	v_add_u32_e32 v58, 5, v59
	v_mad_u64_u32 v[124:125], vcc, v58, s27, v[12:13]
	global_load_dwordx4 v[124:127], v[124:125], off
	v_add_u32_e32 v58, 4, v59
	v_mad_u64_u32 v[128:129], vcc, v58, s27, v[12:13]
	global_load_dwordx4 v[128:131], v[128:129], off
	v_add_u32_e32 v58, 3, v59
	v_mad_u64_u32 v[132:133], vcc, v58, s27, v[12:13]
	global_load_dwordx4 v[132:135], v[132:133], off
	v_add_u32_e32 v58, 2, v59
	v_mad_u64_u32 v[136:137], vcc, v58, s27, v[12:13]
	global_load_dwordx4 v[136:139], v[136:137], off
	v_add_u32_e32 v58, 1, v59
	v_mad_u64_u32 v[176:177], vcc, v58, s27, v[12:13]
	global_load_dwordx4 v[176:179], v[176:177], off
	v_add_u32_e32 v58, 0, v59
	v_mad_u64_u32 v[180:181], vcc, v58, s27, v[12:13]
	global_load_dwordx4 v[180:183], v[180:181], off
	v_add_co_u32_e32 v184, vcc, 0x7000, v14
	v_addc_co_u32_e32 v185, vcc, 0, v15, vcc
	global_load_dwordx4 v[188:191], v[184:185], off offset:16
	global_load_dwordx4 v[184:187], v[184:185], off
	v_add_co_u32_e32 v192, vcc, 0x6800, v14
	v_addc_co_u32_e32 v193, vcc, 0, v15, vcc
	global_load_dwordx4 v[196:199], v[192:193], off offset:16
	global_load_dwordx4 v[192:195], v[192:193], off
	v_add_co_u32_e32 v200, vcc, 0x6000, v14
	v_addc_co_u32_e32 v201, vcc, 0, v15, vcc
	global_load_dwordx4 v[218:221], v[200:201], off offset:16
	global_load_dwordx4 v[200:203], v[200:201], off
	v_add_co_u32_e32 v222, vcc, 0x5800, v14
	v_addc_co_u32_e32 v223, vcc, 0, v15, vcc
	global_load_dwordx4 v[226:229], v[222:223], off offset:16
	global_load_dwordx4 v[222:225], v[222:223], off
	v_add_co_u32_e32 v230, vcc, 0x5000, v14
	v_addc_co_u32_e32 v231, vcc, 0, v15, vcc
	global_load_dwordx4 v[236:239], v[230:231], off offset:16
	global_load_dwordx4 v[230:233], v[230:231], off
	v_add_co_u32_e32 v240, vcc, 0x4800, v14
	v_addc_co_u32_e32 v241, vcc, 0, v15, vcc
	global_load_dwordx4 v[244:247], v[240:241], off offset:16
	global_load_dwordx4 v[240:243], v[240:241], off
	v_add_co_u32_e32 v248, vcc, 0x4000, v14
	v_addc_co_u32_e32 v249, vcc, 0, v15, vcc
	global_load_dwordx4 v[252:255], v[248:249], off offset:16
	global_load_dwordx4 v[248:251], v[248:249], off
	v_mov_b32_e32 v34, 0
	v_mov_b32_e32 v35, 0
	v_mov_b32_e32 v36, 0
	v_mov_b32_e32 v37, 0
	v_mov_b32_e32 v38, 0
	v_mov_b32_e32 v39, 0
	v_mov_b32_e32 v40, 0
	v_mov_b32_e32 v41, 0
	v_mov_b32_e32 v42, 0
	v_mov_b32_e32 v43, 0
	v_mov_b32_e32 v44, 0
	v_mov_b32_e32 v45, 0
	v_mov_b32_e32 v46, 0
	v_mov_b32_e32 v47, 0
	v_mov_b32_e32 v48, 0
	v_mov_b32_e32 v49, 0
	v_mov_b32_e32 v50, 0
	v_mov_b32_e32 v51, 0
	v_mov_b32_e32 v52, 0
	v_mov_b32_e32 v53, 0
	v_mov_b32_e32 v54, 0
	v_mov_b32_e32 v55, 0
	v_mov_b32_e32 v56, 0
	v_mov_b32_e32 v57, 0
	v_mov_b32_e32 v64, 0
	v_mov_b32_e32 v65, 0
	v_mov_b32_e32 v66, 0
	v_mov_b32_e32 v67, 0
	v_mov_b32_e32 v68, 0
	v_mov_b32_e32 v69, 0
	v_mov_b32_e32 v70, 0
	v_mov_b32_e32 v71, 0
	s_waitcnt vmcnt(29)
	v_lshlrev_b32_e32 v16, 16, v72
	v_and_b32_e32 v17, 0xffff0000, v72
	v_lshlrev_b32_e32 v18, 16, v73
	v_and_b32_e32 v19, 0xffff0000, v73
	v_lshlrev_b32_e32 v20, 16, v74
	v_and_b32_e32 v21, 0xffff0000, v74
	v_lshlrev_b32_e32 v22, 16, v75
	v_and_b32_e32 v23, 0xffff0000, v75
	v_add_u32_e32 v58, -12, v150
	v_cmp_gt_u32_e32 vcc, s9, v58
	s_and_b64 exec, vcc, s[98:99]
	v_pk_add_f32 v[64:65], v[64:65], v[16:17]
	v_pk_add_f32 v[66:67], v[66:67], v[18:19]
	v_pk_add_f32 v[68:69], v[68:69], v[20:21]
	v_pk_add_f32 v[70:71], v[70:71], v[22:23]
	s_mov_b64 exec, s[98:99]
	s_waitcnt vmcnt(28)
	v_lshlrev_b32_e32 v16, 16, v80
	v_and_b32_e32 v17, 0xffff0000, v80
	v_lshlrev_b32_e32 v18, 16, v81
	v_and_b32_e32 v19, 0xffff0000, v81
	v_lshlrev_b32_e32 v20, 16, v82
	v_and_b32_e32 v21, 0xffff0000, v82
	v_lshlrev_b32_e32 v22, 16, v83
	v_and_b32_e32 v23, 0xffff0000, v83
	v_add_u32_e32 v58, -12, v150
	v_cmp_gt_u32_e32 vcc, s9, v58
	s_and_b64 exec, vcc, s[98:99]
	v_pk_add_f32 v[50:51], v[50:51], v[16:17]
	v_pk_add_f32 v[52:53], v[52:53], v[18:19]
	v_pk_add_f32 v[54:55], v[54:55], v[20:21]
	v_pk_add_f32 v[56:57], v[56:57], v[22:23]
	s_mov_b64 exec, s[98:99]
	v_add_u32_e32 v58, -11, v150
	v_cmp_gt_u32_e32 vcc, s9, v58
	s_and_b64 exec, vcc, s[98:99]
	v_pk_add_f32 v[64:65], v[64:65], v[16:17]
	v_pk_add_f32 v[66:67], v[66:67], v[18:19]
	v_pk_add_f32 v[68:69], v[68:69], v[20:21]
	v_pk_add_f32 v[70:71], v[70:71], v[22:23]
	s_mov_b64 exec, s[98:99]
	s_waitcnt vmcnt(27)
	v_lshlrev_b32_e32 v16, 16, v92
	v_and_b32_e32 v17, 0xffff0000, v92
	v_lshlrev_b32_e32 v18, 16, v93
	v_and_b32_e32 v19, 0xffff0000, v93
	v_lshlrev_b32_e32 v20, 16, v94
	v_and_b32_e32 v21, 0xffff0000, v94
	v_lshlrev_b32_e32 v22, 16, v95
	v_and_b32_e32 v23, 0xffff0000, v95
	v_add_u32_e32 v58, -12, v150
	v_cmp_gt_u32_e32 vcc, s9, v58
	s_and_b64 exec, vcc, s[98:99]
	v_pk_add_f32 v[42:43], v[42:43], v[16:17]
	v_pk_add_f32 v[44:45], v[44:45], v[18:19]
	v_pk_add_f32 v[46:47], v[46:47], v[20:21]
	v_pk_add_f32 v[48:49], v[48:49], v[22:23]
	s_mov_b64 exec, s[98:99]
	v_add_u32_e32 v58, -11, v150
	v_cmp_gt_u32_e32 vcc, s9, v58
	s_and_b64 exec, vcc, s[98:99]
	v_pk_add_f32 v[50:51], v[50:51], v[16:17]
	v_pk_add_f32 v[52:53], v[52:53], v[18:19]
	v_pk_add_f32 v[54:55], v[54:55], v[20:21]
	v_pk_add_f32 v[56:57], v[56:57], v[22:23]
	s_mov_b64 exec, s[98:99]
	v_add_u32_e32 v58, -10, v150
	v_cmp_gt_u32_e32 vcc, s9, v58
	s_and_b64 exec, vcc, s[98:99]
	v_pk_add_f32 v[64:65], v[64:65], v[16:17]
	v_pk_add_f32 v[66:67], v[66:67], v[18:19]
	v_pk_add_f32 v[68:69], v[68:69], v[20:21]
	v_pk_add_f32 v[70:71], v[70:71], v[22:23]
	s_mov_b64 exec, s[98:99]
	s_waitcnt vmcnt(26)
	v_lshlrev_b32_e32 v16, 16, v96
	v_and_b32_e32 v17, 0xffff0000, v96
	v_lshlrev_b32_e32 v18, 16, v97
	v_and_b32_e32 v19, 0xffff0000, v97
	v_lshlrev_b32_e32 v20, 16, v98
	v_and_b32_e32 v21, 0xffff0000, v98
	v_lshlrev_b32_e32 v22, 16, v99
	v_and_b32_e32 v23, 0xffff0000, v99
	v_add_u32_e32 v58, -12, v150
	v_cmp_gt_u32_e32 vcc, s9, v58
	s_and_b64 exec, vcc, s[98:99]
	v_pk_add_f32 v[34:35], v[34:35], v[16:17]
	v_pk_add_f32 v[36:37], v[36:37], v[18:19]
	v_pk_add_f32 v[38:39], v[38:39], v[20:21]
	v_pk_add_f32 v[40:41], v[40:41], v[22:23]
	s_mov_b64 exec, s[98:99]
	v_add_u32_e32 v58, -11, v150
	v_cmp_gt_u32_e32 vcc, s9, v58
	s_and_b64 exec, vcc, s[98:99]
	v_pk_add_f32 v[42:43], v[42:43], v[16:17]
	v_pk_add_f32 v[44:45], v[44:45], v[18:19]
	v_pk_add_f32 v[46:47], v[46:47], v[20:21]
	v_pk_add_f32 v[48:49], v[48:49], v[22:23]
	s_mov_b64 exec, s[98:99]
	v_add_u32_e32 v58, -10, v150
	v_cmp_gt_u32_e32 vcc, s9, v58
	s_and_b64 exec, vcc, s[98:99]
	v_pk_add_f32 v[50:51], v[50:51], v[16:17]
	v_pk_add_f32 v[52:53], v[52:53], v[18:19]
	v_pk_add_f32 v[54:55], v[54:55], v[20:21]
	v_pk_add_f32 v[56:57], v[56:57], v[22:23]
	s_mov_b64 exec, s[98:99]
	v_add_u32_e32 v58, -9, v150
	v_cmp_gt_u32_e32 vcc, s9, v58
	s_and_b64 exec, vcc, s[98:99]
	v_pk_add_f32 v[64:65], v[64:65], v[16:17]
	v_pk_add_f32 v[66:67], v[66:67], v[18:19]
	v_pk_add_f32 v[68:69], v[68:69], v[20:21]
	v_pk_add_f32 v[70:71], v[70:71], v[22:23]
	s_mov_b64 exec, s[98:99]
	s_waitcnt vmcnt(25)
	v_lshlrev_b32_e32 v16, 16, v100
	v_and_b32_e32 v17, 0xffff0000, v100
	v_lshlrev_b32_e32 v18, 16, v101
	v_and_b32_e32 v19, 0xffff0000, v101
	v_lshlrev_b32_e32 v20, 16, v102
	v_and_b32_e32 v21, 0xffff0000, v102
	v_lshlrev_b32_e32 v22, 16, v103
	v_and_b32_e32 v23, 0xffff0000, v103
	v_add_u32_e32 v58, -11, v150
	v_cmp_gt_u32_e32 vcc, s9, v58
	s_and_b64 exec, vcc, s[98:99]
	v_pk_add_f32 v[34:35], v[34:35], v[16:17]
	v_pk_add_f32 v[36:37], v[36:37], v[18:19]
	v_pk_add_f32 v[38:39], v[38:39], v[20:21]
	v_pk_add_f32 v[40:41], v[40:41], v[22:23]
	s_mov_b64 exec, s[98:99]
	v_add_u32_e32 v58, -10, v150
	v_cmp_gt_u32_e32 vcc, s9, v58
	s_and_b64 exec, vcc, s[98:99]
	v_pk_add_f32 v[42:43], v[42:43], v[16:17]
	v_pk_add_f32 v[44:45], v[44:45], v[18:19]
	v_pk_add_f32 v[46:47], v[46:47], v[20:21]
	v_pk_add_f32 v[48:49], v[48:49], v[22:23]
	s_mov_b64 exec, s[98:99]
	v_add_u32_e32 v58, -9, v150
	v_cmp_gt_u32_e32 vcc, s9, v58
	s_and_b64 exec, vcc, s[98:99]
	v_pk_add_f32 v[50:51], v[50:51], v[16:17]
	v_pk_add_f32 v[52:53], v[52:53], v[18:19]
	v_pk_add_f32 v[54:55], v[54:55], v[20:21]
	v_pk_add_f32 v[56:57], v[56:57], v[22:23]
	s_mov_b64 exec, s[98:99]
	v_add_u32_e32 v58, -8, v150
	v_cmp_gt_u32_e32 vcc, s9, v58
	s_and_b64 exec, vcc, s[98:99]
	v_pk_add_f32 v[64:65], v[64:65], v[16:17]
	v_pk_add_f32 v[66:67], v[66:67], v[18:19]
	v_pk_add_f32 v[68:69], v[68:69], v[20:21]
	v_pk_add_f32 v[70:71], v[70:71], v[22:23]
	s_mov_b64 exec, s[98:99]
	s_waitcnt vmcnt(24)
	v_lshlrev_b32_e32 v16, 16, v104
	v_and_b32_e32 v17, 0xffff0000, v104
	v_lshlrev_b32_e32 v18, 16, v105
	v_and_b32_e32 v19, 0xffff0000, v105
	v_lshlrev_b32_e32 v20, 16, v106
	v_and_b32_e32 v21, 0xffff0000, v106
	v_lshlrev_b32_e32 v22, 16, v107
	v_and_b32_e32 v23, 0xffff0000, v107
	v_add_u32_e32 v58, -10, v150
	v_cmp_gt_u32_e32 vcc, s9, v58
	s_and_b64 exec, vcc, s[98:99]
	v_pk_add_f32 v[34:35], v[34:35], v[16:17]
	v_pk_add_f32 v[36:37], v[36:37], v[18:19]
	v_pk_add_f32 v[38:39], v[38:39], v[20:21]
	v_pk_add_f32 v[40:41], v[40:41], v[22:23]
	s_mov_b64 exec, s[98:99]
	v_add_u32_e32 v58, -9, v150
	v_cmp_gt_u32_e32 vcc, s9, v58
	s_and_b64 exec, vcc, s[98:99]
	v_pk_add_f32 v[42:43], v[42:43], v[16:17]
	v_pk_add_f32 v[44:45], v[44:45], v[18:19]
	v_pk_add_f32 v[46:47], v[46:47], v[20:21]
	v_pk_add_f32 v[48:49], v[48:49], v[22:23]
	s_mov_b64 exec, s[98:99]
	v_add_u32_e32 v58, -8, v150
	v_cmp_gt_u32_e32 vcc, s9, v58
	s_and_b64 exec, vcc, s[98:99]
	v_pk_add_f32 v[50:51], v[50:51], v[16:17]
	v_pk_add_f32 v[52:53], v[52:53], v[18:19]
	v_pk_add_f32 v[54:55], v[54:55], v[20:21]
	v_pk_add_f32 v[56:57], v[56:57], v[22:23]
	s_mov_b64 exec, s[98:99]
	v_add_u32_e32 v58, -7, v150
	v_cmp_gt_u32_e32 vcc, s9, v58
	s_and_b64 exec, vcc, s[98:99]
	v_pk_add_f32 v[64:65], v[64:65], v[16:17]
	v_pk_add_f32 v[66:67], v[66:67], v[18:19]
	v_pk_add_f32 v[68:69], v[68:69], v[20:21]
	v_pk_add_f32 v[70:71], v[70:71], v[22:23]
	s_mov_b64 exec, s[98:99]
	s_waitcnt vmcnt(23)
	v_lshlrev_b32_e32 v16, 16, v108
	v_and_b32_e32 v17, 0xffff0000, v108
	v_lshlrev_b32_e32 v18, 16, v109
	v_and_b32_e32 v19, 0xffff0000, v109
	v_lshlrev_b32_e32 v20, 16, v110
	v_and_b32_e32 v21, 0xffff0000, v110
	v_lshlrev_b32_e32 v22, 16, v111
	v_and_b32_e32 v23, 0xffff0000, v111
	v_add_u32_e32 v58, -9, v150
	v_cmp_gt_u32_e32 vcc, s9, v58
	s_and_b64 exec, vcc, s[98:99]
	v_pk_add_f32 v[34:35], v[34:35], v[16:17]
	v_pk_add_f32 v[36:37], v[36:37], v[18:19]
	v_pk_add_f32 v[38:39], v[38:39], v[20:21]
	v_pk_add_f32 v[40:41], v[40:41], v[22:23]
	s_mov_b64 exec, s[98:99]
	v_add_u32_e32 v58, -8, v150
	v_cmp_gt_u32_e32 vcc, s9, v58
	s_and_b64 exec, vcc, s[98:99]
	v_pk_add_f32 v[42:43], v[42:43], v[16:17]
	v_pk_add_f32 v[44:45], v[44:45], v[18:19]
	v_pk_add_f32 v[46:47], v[46:47], v[20:21]
	v_pk_add_f32 v[48:49], v[48:49], v[22:23]
	s_mov_b64 exec, s[98:99]
	v_add_u32_e32 v58, -7, v150
	v_cmp_gt_u32_e32 vcc, s9, v58
	s_and_b64 exec, vcc, s[98:99]
	v_pk_add_f32 v[50:51], v[50:51], v[16:17]
	v_pk_add_f32 v[52:53], v[52:53], v[18:19]
	v_pk_add_f32 v[54:55], v[54:55], v[20:21]
	v_pk_add_f32 v[56:57], v[56:57], v[22:23]
	s_mov_b64 exec, s[98:99]
	v_add_u32_e32 v58, -6, v150
	v_cmp_gt_u32_e32 vcc, s9, v58
	s_and_b64 exec, vcc, s[98:99]
	v_pk_add_f32 v[64:65], v[64:65], v[16:17]
	v_pk_add_f32 v[66:67], v[66:67], v[18:19]
	v_pk_add_f32 v[68:69], v[68:69], v[20:21]
	v_pk_add_f32 v[70:71], v[70:71], v[22:23]
	s_mov_b64 exec, s[98:99]
	s_waitcnt vmcnt(22)
	v_lshlrev_b32_e32 v16, 16, v112
	v_and_b32_e32 v17, 0xffff0000, v112
	v_lshlrev_b32_e32 v18, 16, v113
	v_and_b32_e32 v19, 0xffff0000, v113
	v_lshlrev_b32_e32 v20, 16, v114
	v_and_b32_e32 v21, 0xffff0000, v114
	v_lshlrev_b32_e32 v22, 16, v115
	v_and_b32_e32 v23, 0xffff0000, v115
	v_add_u32_e32 v58, -8, v150
	v_cmp_gt_u32_e32 vcc, s9, v58
	s_and_b64 exec, vcc, s[98:99]
	v_pk_add_f32 v[34:35], v[34:35], v[16:17]
	v_pk_add_f32 v[36:37], v[36:37], v[18:19]
	v_pk_add_f32 v[38:39], v[38:39], v[20:21]
	v_pk_add_f32 v[40:41], v[40:41], v[22:23]
	s_mov_b64 exec, s[98:99]
	v_add_u32_e32 v58, -7, v150
	v_cmp_gt_u32_e32 vcc, s9, v58
	s_and_b64 exec, vcc, s[98:99]
	v_pk_add_f32 v[42:43], v[42:43], v[16:17]
	v_pk_add_f32 v[44:45], v[44:45], v[18:19]
	v_pk_add_f32 v[46:47], v[46:47], v[20:21]
	v_pk_add_f32 v[48:49], v[48:49], v[22:23]
	s_mov_b64 exec, s[98:99]
	v_add_u32_e32 v58, -6, v150
	v_cmp_gt_u32_e32 vcc, s9, v58
	s_and_b64 exec, vcc, s[98:99]
	v_pk_add_f32 v[50:51], v[50:51], v[16:17]
	v_pk_add_f32 v[52:53], v[52:53], v[18:19]
	v_pk_add_f32 v[54:55], v[54:55], v[20:21]
	v_pk_add_f32 v[56:57], v[56:57], v[22:23]
	s_mov_b64 exec, s[98:99]
	v_add_u32_e32 v58, -5, v150
	v_cmp_gt_u32_e32 vcc, s9, v58
	s_and_b64 exec, vcc, s[98:99]
	v_pk_add_f32 v[64:65], v[64:65], v[16:17]
	v_pk_add_f32 v[66:67], v[66:67], v[18:19]
	v_pk_add_f32 v[68:69], v[68:69], v[20:21]
	v_pk_add_f32 v[70:71], v[70:71], v[22:23]
	s_mov_b64 exec, s[98:99]
	s_waitcnt vmcnt(21)
	v_lshlrev_b32_e32 v16, 16, v116
	v_and_b32_e32 v17, 0xffff0000, v116
	v_lshlrev_b32_e32 v18, 16, v117
	v_and_b32_e32 v19, 0xffff0000, v117
	v_lshlrev_b32_e32 v20, 16, v118
	v_and_b32_e32 v21, 0xffff0000, v118
	v_lshlrev_b32_e32 v22, 16, v119
	v_and_b32_e32 v23, 0xffff0000, v119
	v_add_u32_e32 v58, -7, v150
	v_cmp_gt_u32_e32 vcc, s9, v58
	s_and_b64 exec, vcc, s[98:99]
	v_pk_add_f32 v[34:35], v[34:35], v[16:17]
	v_pk_add_f32 v[36:37], v[36:37], v[18:19]
	v_pk_add_f32 v[38:39], v[38:39], v[20:21]
	v_pk_add_f32 v[40:41], v[40:41], v[22:23]
	s_mov_b64 exec, s[98:99]
	v_add_u32_e32 v58, -6, v150
	v_cmp_gt_u32_e32 vcc, s9, v58
	s_and_b64 exec, vcc, s[98:99]
	v_pk_add_f32 v[42:43], v[42:43], v[16:17]
	v_pk_add_f32 v[44:45], v[44:45], v[18:19]
	v_pk_add_f32 v[46:47], v[46:47], v[20:21]
	v_pk_add_f32 v[48:49], v[48:49], v[22:23]
	s_mov_b64 exec, s[98:99]
	v_add_u32_e32 v58, -5, v150
	v_cmp_gt_u32_e32 vcc, s9, v58
	s_and_b64 exec, vcc, s[98:99]
	v_pk_add_f32 v[50:51], v[50:51], v[16:17]
	v_pk_add_f32 v[52:53], v[52:53], v[18:19]
	v_pk_add_f32 v[54:55], v[54:55], v[20:21]
	v_pk_add_f32 v[56:57], v[56:57], v[22:23]
	s_mov_b64 exec, s[98:99]
	v_add_u32_e32 v58, -4, v150
	v_cmp_gt_u32_e32 vcc, s9, v58
	s_and_b64 exec, vcc, s[98:99]
	v_pk_add_f32 v[64:65], v[64:65], v[16:17]
	v_pk_add_f32 v[66:67], v[66:67], v[18:19]
	v_pk_add_f32 v[68:69], v[68:69], v[20:21]
	v_pk_add_f32 v[70:71], v[70:71], v[22:23]
	s_mov_b64 exec, s[98:99]
	s_waitcnt vmcnt(20)
	v_lshlrev_b32_e32 v16, 16, v120
	v_and_b32_e32 v17, 0xffff0000, v120
	v_lshlrev_b32_e32 v18, 16, v121
	v_and_b32_e32 v19, 0xffff0000, v121
	v_lshlrev_b32_e32 v20, 16, v122
	v_and_b32_e32 v21, 0xffff0000, v122
	v_lshlrev_b32_e32 v22, 16, v123
	v_and_b32_e32 v23, 0xffff0000, v123
	v_add_u32_e32 v58, -6, v150
	v_cmp_gt_u32_e32 vcc, s9, v58
	s_and_b64 exec, vcc, s[98:99]
	v_pk_add_f32 v[34:35], v[34:35], v[16:17]
	v_pk_add_f32 v[36:37], v[36:37], v[18:19]
	v_pk_add_f32 v[38:39], v[38:39], v[20:21]
	v_pk_add_f32 v[40:41], v[40:41], v[22:23]
	s_mov_b64 exec, s[98:99]
	v_add_u32_e32 v58, -5, v150
	v_cmp_gt_u32_e32 vcc, s9, v58
	s_and_b64 exec, vcc, s[98:99]
	v_pk_add_f32 v[42:43], v[42:43], v[16:17]
	v_pk_add_f32 v[44:45], v[44:45], v[18:19]
	v_pk_add_f32 v[46:47], v[46:47], v[20:21]
	v_pk_add_f32 v[48:49], v[48:49], v[22:23]
	s_mov_b64 exec, s[98:99]
	v_add_u32_e32 v58, -4, v150
	v_cmp_gt_u32_e32 vcc, s9, v58
	s_and_b64 exec, vcc, s[98:99]
	v_pk_add_f32 v[50:51], v[50:51], v[16:17]
	v_pk_add_f32 v[52:53], v[52:53], v[18:19]
	v_pk_add_f32 v[54:55], v[54:55], v[20:21]
	v_pk_add_f32 v[56:57], v[56:57], v[22:23]
	s_mov_b64 exec, s[98:99]
	v_add_u32_e32 v58, -3, v150
	v_cmp_gt_u32_e32 vcc, s9, v58
	s_and_b64 exec, vcc, s[98:99]
	v_pk_add_f32 v[64:65], v[64:65], v[16:17]
	v_pk_add_f32 v[66:67], v[66:67], v[18:19]
	v_pk_add_f32 v[68:69], v[68:69], v[20:21]
	v_pk_add_f32 v[70:71], v[70:71], v[22:23]
	s_mov_b64 exec, s[98:99]
	s_waitcnt vmcnt(19)
	v_lshlrev_b32_e32 v16, 16, v124
	v_and_b32_e32 v17, 0xffff0000, v124
	v_lshlrev_b32_e32 v18, 16, v125
	v_and_b32_e32 v19, 0xffff0000, v125
	v_lshlrev_b32_e32 v20, 16, v126
	v_and_b32_e32 v21, 0xffff0000, v126
	v_lshlrev_b32_e32 v22, 16, v127
	v_and_b32_e32 v23, 0xffff0000, v127
	v_add_u32_e32 v58, -5, v150
	v_cmp_gt_u32_e32 vcc, s9, v58
	s_and_b64 exec, vcc, s[98:99]
	v_pk_add_f32 v[34:35], v[34:35], v[16:17]
	v_pk_add_f32 v[36:37], v[36:37], v[18:19]
	v_pk_add_f32 v[38:39], v[38:39], v[20:21]
	v_pk_add_f32 v[40:41], v[40:41], v[22:23]
	s_mov_b64 exec, s[98:99]
	v_add_u32_e32 v58, -4, v150
	v_cmp_gt_u32_e32 vcc, s9, v58
	s_and_b64 exec, vcc, s[98:99]
	v_pk_add_f32 v[42:43], v[42:43], v[16:17]
	v_pk_add_f32 v[44:45], v[44:45], v[18:19]
	v_pk_add_f32 v[46:47], v[46:47], v[20:21]
	v_pk_add_f32 v[48:49], v[48:49], v[22:23]
	s_mov_b64 exec, s[98:99]
	v_add_u32_e32 v58, -3, v150
	v_cmp_gt_u32_e32 vcc, s9, v58
	s_and_b64 exec, vcc, s[98:99]
	v_pk_add_f32 v[50:51], v[50:51], v[16:17]
	v_pk_add_f32 v[52:53], v[52:53], v[18:19]
	v_pk_add_f32 v[54:55], v[54:55], v[20:21]
	v_pk_add_f32 v[56:57], v[56:57], v[22:23]
	s_mov_b64 exec, s[98:99]
	v_add_u32_e32 v58, -2, v150
	v_cmp_gt_u32_e32 vcc, s9, v58
	s_and_b64 exec, vcc, s[98:99]
	v_pk_add_f32 v[64:65], v[64:65], v[16:17]
	v_pk_add_f32 v[66:67], v[66:67], v[18:19]
	v_pk_add_f32 v[68:69], v[68:69], v[20:21]
	v_pk_add_f32 v[70:71], v[70:71], v[22:23]
	s_mov_b64 exec, s[98:99]
	s_waitcnt vmcnt(18)
	v_lshlrev_b32_e32 v16, 16, v128
	v_and_b32_e32 v17, 0xffff0000, v128
	v_lshlrev_b32_e32 v18, 16, v129
	v_and_b32_e32 v19, 0xffff0000, v129
	v_lshlrev_b32_e32 v20, 16, v130
	v_and_b32_e32 v21, 0xffff0000, v130
	v_lshlrev_b32_e32 v22, 16, v131
	v_and_b32_e32 v23, 0xffff0000, v131
	v_add_u32_e32 v58, -4, v150
	v_cmp_gt_u32_e32 vcc, s9, v58
	s_and_b64 exec, vcc, s[98:99]
	v_pk_add_f32 v[34:35], v[34:35], v[16:17]
	v_pk_add_f32 v[36:37], v[36:37], v[18:19]
	v_pk_add_f32 v[38:39], v[38:39], v[20:21]
	v_pk_add_f32 v[40:41], v[40:41], v[22:23]
	s_mov_b64 exec, s[98:99]
	v_add_u32_e32 v58, -3, v150
	v_cmp_gt_u32_e32 vcc, s9, v58
	s_and_b64 exec, vcc, s[98:99]
	v_pk_add_f32 v[42:43], v[42:43], v[16:17]
	v_pk_add_f32 v[44:45], v[44:45], v[18:19]
	v_pk_add_f32 v[46:47], v[46:47], v[20:21]
	v_pk_add_f32 v[48:49], v[48:49], v[22:23]
	s_mov_b64 exec, s[98:99]
	v_add_u32_e32 v58, -2, v150
	v_cmp_gt_u32_e32 vcc, s9, v58
	s_and_b64 exec, vcc, s[98:99]
	v_pk_add_f32 v[50:51], v[50:51], v[16:17]
	v_pk_add_f32 v[52:53], v[52:53], v[18:19]
	v_pk_add_f32 v[54:55], v[54:55], v[20:21]
	v_pk_add_f32 v[56:57], v[56:57], v[22:23]
	s_mov_b64 exec, s[98:99]
	v_add_u32_e32 v58, -1, v150
	v_cmp_gt_u32_e32 vcc, s9, v58
	s_and_b64 exec, vcc, s[98:99]
	v_pk_add_f32 v[64:65], v[64:65], v[16:17]
	v_pk_add_f32 v[66:67], v[66:67], v[18:19]
	v_pk_add_f32 v[68:69], v[68:69], v[20:21]
	v_pk_add_f32 v[70:71], v[70:71], v[22:23]
	s_mov_b64 exec, s[98:99]
	s_waitcnt vmcnt(17)
	v_lshlrev_b32_e32 v16, 16, v132
	v_and_b32_e32 v17, 0xffff0000, v132
	v_lshlrev_b32_e32 v18, 16, v133
	v_and_b32_e32 v19, 0xffff0000, v133
	v_lshlrev_b32_e32 v20, 16, v134
	v_and_b32_e32 v21, 0xffff0000, v134
	v_lshlrev_b32_e32 v22, 16, v135
	v_and_b32_e32 v23, 0xffff0000, v135
	v_add_u32_e32 v58, -3, v150
	v_cmp_gt_u32_e32 vcc, s9, v58
	s_and_b64 exec, vcc, s[98:99]
	v_pk_add_f32 v[34:35], v[34:35], v[16:17]
	v_pk_add_f32 v[36:37], v[36:37], v[18:19]
	v_pk_add_f32 v[38:39], v[38:39], v[20:21]
	v_pk_add_f32 v[40:41], v[40:41], v[22:23]
	s_mov_b64 exec, s[98:99]
	v_add_u32_e32 v58, -2, v150
	v_cmp_gt_u32_e32 vcc, s9, v58
	s_and_b64 exec, vcc, s[98:99]
	v_pk_add_f32 v[42:43], v[42:43], v[16:17]
	v_pk_add_f32 v[44:45], v[44:45], v[18:19]
	v_pk_add_f32 v[46:47], v[46:47], v[20:21]
	v_pk_add_f32 v[48:49], v[48:49], v[22:23]
	s_mov_b64 exec, s[98:99]
	v_add_u32_e32 v58, -1, v150
	v_cmp_gt_u32_e32 vcc, s9, v58
	s_and_b64 exec, vcc, s[98:99]
	v_pk_add_f32 v[50:51], v[50:51], v[16:17]
	v_pk_add_f32 v[52:53], v[52:53], v[18:19]
	v_pk_add_f32 v[54:55], v[54:55], v[20:21]
	v_pk_add_f32 v[56:57], v[56:57], v[22:23]
	s_mov_b64 exec, s[98:99]
	v_add_u32_e32 v58, 0, v150
	v_cmp_gt_u32_e32 vcc, s9, v58
	s_and_b64 exec, vcc, s[98:99]
	v_pk_add_f32 v[64:65], v[64:65], v[16:17]
	v_pk_add_f32 v[66:67], v[66:67], v[18:19]
	v_pk_add_f32 v[68:69], v[68:69], v[20:21]
	v_pk_add_f32 v[70:71], v[70:71], v[22:23]
	s_mov_b64 exec, s[98:99]
	s_waitcnt vmcnt(16)
	v_lshlrev_b32_e32 v16, 16, v136
	v_and_b32_e32 v17, 0xffff0000, v136
	v_lshlrev_b32_e32 v18, 16, v137
	v_and_b32_e32 v19, 0xffff0000, v137
	v_lshlrev_b32_e32 v20, 16, v138
	v_and_b32_e32 v21, 0xffff0000, v138
	v_lshlrev_b32_e32 v22, 16, v139
	v_and_b32_e32 v23, 0xffff0000, v139
	v_add_u32_e32 v58, -2, v150
	v_cmp_gt_u32_e32 vcc, s9, v58
	s_and_b64 exec, vcc, s[98:99]
	v_pk_add_f32 v[34:35], v[34:35], v[16:17]
	v_pk_add_f32 v[36:37], v[36:37], v[18:19]
	v_pk_add_f32 v[38:39], v[38:39], v[20:21]
	v_pk_add_f32 v[40:41], v[40:41], v[22:23]
	s_mov_b64 exec, s[98:99]
	v_add_u32_e32 v58, -1, v150
	v_cmp_gt_u32_e32 vcc, s9, v58
	s_and_b64 exec, vcc, s[98:99]
	v_pk_add_f32 v[42:43], v[42:43], v[16:17]
	v_pk_add_f32 v[44:45], v[44:45], v[18:19]
	v_pk_add_f32 v[46:47], v[46:47], v[20:21]
	v_pk_add_f32 v[48:49], v[48:49], v[22:23]
	s_mov_b64 exec, s[98:99]
	v_add_u32_e32 v58, 0, v150
	v_cmp_gt_u32_e32 vcc, s9, v58
	s_and_b64 exec, vcc, s[98:99]
	v_pk_add_f32 v[50:51], v[50:51], v[16:17]
	v_pk_add_f32 v[52:53], v[52:53], v[18:19]
	v_pk_add_f32 v[54:55], v[54:55], v[20:21]
	v_pk_add_f32 v[56:57], v[56:57], v[22:23]
	s_mov_b64 exec, s[98:99]
	v_add_u32_e32 v58, 1, v150
	v_cmp_gt_u32_e32 vcc, s9, v58
	s_and_b64 exec, vcc, s[98:99]
	v_pk_add_f32 v[64:65], v[64:65], v[16:17]
	v_pk_add_f32 v[66:67], v[66:67], v[18:19]
	v_pk_add_f32 v[68:69], v[68:69], v[20:21]
	v_pk_add_f32 v[70:71], v[70:71], v[22:23]
	s_mov_b64 exec, s[98:99]
	s_waitcnt vmcnt(15)
	v_lshlrev_b32_e32 v16, 16, v176
	v_and_b32_e32 v17, 0xffff0000, v176
	v_lshlrev_b32_e32 v18, 16, v177
	v_and_b32_e32 v19, 0xffff0000, v177
	v_lshlrev_b32_e32 v20, 16, v178
	v_and_b32_e32 v21, 0xffff0000, v178
	v_lshlrev_b32_e32 v22, 16, v179
	v_and_b32_e32 v23, 0xffff0000, v179
	v_add_u32_e32 v58, -1, v150
	v_cmp_gt_u32_e32 vcc, s9, v58
	s_and_b64 exec, vcc, s[98:99]
	v_pk_add_f32 v[34:35], v[34:35], v[16:17]
	v_pk_add_f32 v[36:37], v[36:37], v[18:19]
	v_pk_add_f32 v[38:39], v[38:39], v[20:21]
	v_pk_add_f32 v[40:41], v[40:41], v[22:23]
	s_mov_b64 exec, s[98:99]
	v_add_u32_e32 v58, 0, v150
	v_cmp_gt_u32_e32 vcc, s9, v58
	s_and_b64 exec, vcc, s[98:99]
	v_pk_add_f32 v[42:43], v[42:43], v[16:17]
	v_pk_add_f32 v[44:45], v[44:45], v[18:19]
	v_pk_add_f32 v[46:47], v[46:47], v[20:21]
	v_pk_add_f32 v[48:49], v[48:49], v[22:23]
	s_mov_b64 exec, s[98:99]
	v_add_u32_e32 v58, 1, v150
	v_cmp_gt_u32_e32 vcc, s9, v58
	s_and_b64 exec, vcc, s[98:99]
	v_pk_add_f32 v[50:51], v[50:51], v[16:17]
	v_pk_add_f32 v[52:53], v[52:53], v[18:19]
	v_pk_add_f32 v[54:55], v[54:55], v[20:21]
	v_pk_add_f32 v[56:57], v[56:57], v[22:23]
	s_mov_b64 exec, s[98:99]
	v_add_u32_e32 v58, 2, v150
	v_cmp_gt_u32_e32 vcc, s9, v58
	s_and_b64 exec, vcc, s[98:99]
	v_pk_add_f32 v[64:65], v[64:65], v[16:17]
	v_pk_add_f32 v[66:67], v[66:67], v[18:19]
	v_pk_add_f32 v[68:69], v[68:69], v[20:21]
	v_pk_add_f32 v[70:71], v[70:71], v[22:23]
	s_mov_b64 exec, s[98:99]
	s_waitcnt vmcnt(14)
	v_lshlrev_b32_e32 v16, 16, v180
	v_and_b32_e32 v17, 0xffff0000, v180
	v_lshlrev_b32_e32 v18, 16, v181
	v_and_b32_e32 v19, 0xffff0000, v181
	v_lshlrev_b32_e32 v20, 16, v182
	v_and_b32_e32 v21, 0xffff0000, v182
	v_lshlrev_b32_e32 v22, 16, v183
	v_and_b32_e32 v23, 0xffff0000, v183
	v_add_u32_e32 v58, 0, v150
	v_cmp_gt_u32_e32 vcc, s9, v58
	s_and_b64 exec, vcc, s[98:99]
	v_pk_add_f32 v[34:35], v[34:35], v[16:17]
	v_pk_add_f32 v[36:37], v[36:37], v[18:19]
	v_pk_add_f32 v[38:39], v[38:39], v[20:21]
	v_pk_add_f32 v[40:41], v[40:41], v[22:23]
	s_mov_b64 exec, s[98:99]
	v_add_u32_e32 v58, 1, v150
	v_cmp_gt_u32_e32 vcc, s9, v58
	s_and_b64 exec, vcc, s[98:99]
	v_pk_add_f32 v[42:43], v[42:43], v[16:17]
	v_pk_add_f32 v[44:45], v[44:45], v[18:19]
	v_pk_add_f32 v[46:47], v[46:47], v[20:21]
	v_pk_add_f32 v[48:49], v[48:49], v[22:23]
	s_mov_b64 exec, s[98:99]
	v_add_u32_e32 v58, 2, v150
	v_cmp_gt_u32_e32 vcc, s9, v58
	s_and_b64 exec, vcc, s[98:99]
	v_pk_add_f32 v[50:51], v[50:51], v[16:17]
	v_pk_add_f32 v[52:53], v[52:53], v[18:19]
	v_pk_add_f32 v[54:55], v[54:55], v[20:21]
	v_pk_add_f32 v[56:57], v[56:57], v[22:23]
	s_mov_b64 exec, s[98:99]
	v_add_u32_e32 v58, 3, v150
	v_cmp_gt_u32_e32 vcc, s9, v58
	s_and_b64 exec, vcc, s[98:99]
	v_pk_add_f32 v[64:65], v[64:65], v[16:17]
	v_pk_add_f32 v[66:67], v[66:67], v[18:19]
	v_pk_add_f32 v[68:69], v[68:69], v[20:21]
	v_pk_add_f32 v[70:71], v[70:71], v[22:23]
	s_mov_b64 exec, s[98:99]
	v_add_co_u32_e32 v72, vcc, 0x3800, v14
	v_addc_co_u32_e32 v73, vcc, 0, v15, vcc
	global_load_dwordx4 v[80:83], v[72:73], off offset:16
	global_load_dwordx4 v[72:75], v[72:73], off
	v_add_co_u32_e32 v92, vcc, 0x3000, v14
	v_addc_co_u32_e32 v93, vcc, 0, v15, vcc
	global_load_dwordx4 v[96:99], v[92:93], off offset:16
	global_load_dwordx4 v[92:95], v[92:93], off
	v_add_co_u32_e32 v100, vcc, 0x2800, v14
	v_addc_co_u32_e32 v101, vcc, 0, v15, vcc
	global_load_dwordx4 v[104:107], v[100:101], off offset:16
	global_load_dwordx4 v[100:103], v[100:101], off
	v_add_co_u32_e32 v108, vcc, 0x2000, v14
	v_addc_co_u32_e32 v109, vcc, 0, v15, vcc
	global_load_dwordx4 v[112:115], v[108:109], off offset:16
	global_load_dwordx4 v[108:111], v[108:109], off
	v_add_co_u32_e32 v116, vcc, 0x1800, v14
	v_addc_co_u32_e32 v117, vcc, 0, v15, vcc
	global_load_dwordx4 v[120:123], v[116:117], off offset:16
	global_load_dwordx4 v[116:119], v[116:117], off
	v_add_co_u32_e32 v124, vcc, 0x1000, v14
	v_addc_co_u32_e32 v125, vcc, 0, v15, vcc
	global_load_dwordx4 v[128:131], v[124:125], off offset:16
	global_load_dwordx4 v[124:127], v[124:125], off
	v_add_co_u32_e32 v132, vcc, 0x800, v14
	v_addc_co_u32_e32 v133, vcc, 0, v15, vcc
	global_load_dwordx4 v[136:139], v[132:133], off offset:16
	global_load_dwordx4 v[132:135], v[132:133], off
	v_mov_b32_e32 v176, v14
	v_mov_b32_e32 v177, v15
	global_load_dwordx4 v[180:183], v[176:177], off offset:16
	global_load_dwordx4 v[176:179], v[176:177], off
	s_waitcnt vmcnt(28)
	v_add_u32_e32 v58, 1, v150
	v_cmp_gt_u32_e32 vcc, s9, v58
	s_and_b64 exec, vcc, s[98:99]
	v_pk_add_f32 v[34:35], v[34:35], v[184:185]
	v_pk_add_f32 v[36:37], v[36:37], v[186:187]
	v_pk_add_f32 v[38:39], v[38:39], v[188:189]
	v_pk_add_f32 v[40:41], v[40:41], v[190:191]
	s_mov_b64 exec, s[98:99]
	v_add_u32_e32 v58, 2, v150
	v_cmp_gt_u32_e32 vcc, s9, v58
	s_and_b64 exec, vcc, s[98:99]
	v_pk_add_f32 v[42:43], v[42:43], v[184:185]
	v_pk_add_f32 v[44:45], v[44:45], v[186:187]
	v_pk_add_f32 v[46:47], v[46:47], v[188:189]
	v_pk_add_f32 v[48:49], v[48:49], v[190:191]
	s_mov_b64 exec, s[98:99]
	v_add_u32_e32 v58, 3, v150
	v_cmp_gt_u32_e32 vcc, s9, v58
	s_and_b64 exec, vcc, s[98:99]
	v_pk_add_f32 v[50:51], v[50:51], v[184:185]
	v_pk_add_f32 v[52:53], v[52:53], v[186:187]
	v_pk_add_f32 v[54:55], v[54:55], v[188:189]
	v_pk_add_f32 v[56:57], v[56:57], v[190:191]
	s_mov_b64 exec, s[98:99]
	v_add_u32_e32 v58, 4, v150
	v_cmp_gt_u32_e32 vcc, s9, v58
	s_and_b64 exec, vcc, s[98:99]
	v_pk_add_f32 v[64:65], v[64:65], v[184:185]
	v_pk_add_f32 v[66:67], v[66:67], v[186:187]
	v_pk_add_f32 v[68:69], v[68:69], v[188:189]
	v_pk_add_f32 v[70:71], v[70:71], v[190:191]
	s_mov_b64 exec, s[98:99]
	s_cmp_lt_u32 s9, 4
	s_cbranch_scc1 ATS1_END
	s_waitcnt vmcnt(26)
	v_add_u32_e32 v58, 2, v150
	v_cmp_gt_u32_e32 vcc, s9, v58
	s_and_b64 exec, vcc, s[98:99]
	v_pk_add_f32 v[34:35], v[34:35], v[192:193]
	v_pk_add_f32 v[36:37], v[36:37], v[194:195]
	v_pk_add_f32 v[38:39], v[38:39], v[196:197]
	v_pk_add_f32 v[40:41], v[40:41], v[198:199]
	s_mov_b64 exec, s[98:99]
	v_add_u32_e32 v58, 3, v150
	v_cmp_gt_u32_e32 vcc, s9, v58
	s_and_b64 exec, vcc, s[98:99]
	v_pk_add_f32 v[42:43], v[42:43], v[192:193]
	v_pk_add_f32 v[44:45], v[44:45], v[194:195]
	v_pk_add_f32 v[46:47], v[46:47], v[196:197]
	v_pk_add_f32 v[48:49], v[48:49], v[198:199]
	s_mov_b64 exec, s[98:99]
	v_add_u32_e32 v58, 4, v150
	v_cmp_gt_u32_e32 vcc, s9, v58
	s_and_b64 exec, vcc, s[98:99]
	v_pk_add_f32 v[50:51], v[50:51], v[192:193]
	v_pk_add_f32 v[52:53], v[52:53], v[194:195]
	v_pk_add_f32 v[54:55], v[54:55], v[196:197]
	v_pk_add_f32 v[56:57], v[56:57], v[198:199]
	s_mov_b64 exec, s[98:99]
	v_add_u32_e32 v58, 5, v150
	v_cmp_gt_u32_e32 vcc, s9, v58
	s_and_b64 exec, vcc, s[98:99]
	v_pk_add_f32 v[64:65], v[64:65], v[192:193]
	v_pk_add_f32 v[66:67], v[66:67], v[194:195]
	v_pk_add_f32 v[68:69], v[68:69], v[196:197]
	v_pk_add_f32 v[70:71], v[70:71], v[198:199]
	s_mov_b64 exec, s[98:99]
	s_waitcnt vmcnt(24)
	v_add_u32_e32 v58, 3, v150
	v_cmp_gt_u32_e32 vcc, s9, v58
	s_and_b64 exec, vcc, s[98:99]
	v_pk_add_f32 v[34:35], v[34:35], v[200:201]
	v_pk_add_f32 v[36:37], v[36:37], v[202:203]
	v_pk_add_f32 v[38:39], v[38:39], v[218:219]
	v_pk_add_f32 v[40:41], v[40:41], v[220:221]
	s_mov_b64 exec, s[98:99]
	v_add_u32_e32 v58, 4, v150
	v_cmp_gt_u32_e32 vcc, s9, v58
	s_and_b64 exec, vcc, s[98:99]
	v_pk_add_f32 v[42:43], v[42:43], v[200:201]
	v_pk_add_f32 v[44:45], v[44:45], v[202:203]
	v_pk_add_f32 v[46:47], v[46:47], v[218:219]
	v_pk_add_f32 v[48:49], v[48:49], v[220:221]
	s_mov_b64 exec, s[98:99]
	v_add_u32_e32 v58, 5, v150
	v_cmp_gt_u32_e32 vcc, s9, v58
	s_and_b64 exec, vcc, s[98:99]
	v_pk_add_f32 v[50:51], v[50:51], v[200:201]
	v_pk_add_f32 v[52:53], v[52:53], v[202:203]
	v_pk_add_f32 v[54:55], v[54:55], v[218:219]
	v_pk_add_f32 v[56:57], v[56:57], v[220:221]
	s_mov_b64 exec, s[98:99]
	v_add_u32_e32 v58, 6, v150
	v_cmp_gt_u32_e32 vcc, s9, v58
	s_and_b64 exec, vcc, s[98:99]
	v_pk_add_f32 v[64:65], v[64:65], v[200:201]
	v_pk_add_f32 v[66:67], v[66:67], v[202:203]
	v_pk_add_f32 v[68:69], v[68:69], v[218:219]
	v_pk_add_f32 v[70:71], v[70:71], v[220:221]
	s_mov_b64 exec, s[98:99]
	s_cmp_lt_u32 s9, 5
	s_cbranch_scc1 ATS1_END
	s_waitcnt vmcnt(22)
	v_add_u32_e32 v58, 4, v150
	v_cmp_gt_u32_e32 vcc, s9, v58
	s_and_b64 exec, vcc, s[98:99]
	v_pk_add_f32 v[34:35], v[34:35], v[222:223]
	v_pk_add_f32 v[36:37], v[36:37], v[224:225]
	v_pk_add_f32 v[38:39], v[38:39], v[226:227]
	v_pk_add_f32 v[40:41], v[40:41], v[228:229]
	s_mov_b64 exec, s[98:99]
	v_add_u32_e32 v58, 5, v150
	v_cmp_gt_u32_e32 vcc, s9, v58
	s_and_b64 exec, vcc, s[98:99]
	v_pk_add_f32 v[42:43], v[42:43], v[222:223]
	v_pk_add_f32 v[44:45], v[44:45], v[224:225]
	v_pk_add_f32 v[46:47], v[46:47], v[226:227]
	v_pk_add_f32 v[48:49], v[48:49], v[228:229]
	s_mov_b64 exec, s[98:99]
	v_add_u32_e32 v58, 6, v150
	v_cmp_gt_u32_e32 vcc, s9, v58
	s_and_b64 exec, vcc, s[98:99]
	v_pk_add_f32 v[50:51], v[50:51], v[222:223]
	v_pk_add_f32 v[52:53], v[52:53], v[224:225]
	v_pk_add_f32 v[54:55], v[54:55], v[226:227]
	v_pk_add_f32 v[56:57], v[56:57], v[228:229]
	s_mov_b64 exec, s[98:99]
	v_add_u32_e32 v58, 7, v150
	v_cmp_gt_u32_e32 vcc, s9, v58
	s_and_b64 exec, vcc, s[98:99]
	v_pk_add_f32 v[64:65], v[64:65], v[222:223]
	v_pk_add_f32 v[66:67], v[66:67], v[224:225]
	v_pk_add_f32 v[68:69], v[68:69], v[226:227]
	v_pk_add_f32 v[70:71], v[70:71], v[228:229]
	s_mov_b64 exec, s[98:99]
	s_waitcnt vmcnt(20)
	v_add_u32_e32 v58, 5, v150
	v_cmp_gt_u32_e32 vcc, s9, v58
	s_and_b64 exec, vcc, s[98:99]
	v_pk_add_f32 v[34:35], v[34:35], v[230:231]
	v_pk_add_f32 v[36:37], v[36:37], v[232:233]
	v_pk_add_f32 v[38:39], v[38:39], v[236:237]
	v_pk_add_f32 v[40:41], v[40:41], v[238:239]
	s_mov_b64 exec, s[98:99]
	v_add_u32_e32 v58, 6, v150
	v_cmp_gt_u32_e32 vcc, s9, v58
	s_and_b64 exec, vcc, s[98:99]
	v_pk_add_f32 v[42:43], v[42:43], v[230:231]
	v_pk_add_f32 v[44:45], v[44:45], v[232:233]
	v_pk_add_f32 v[46:47], v[46:47], v[236:237]
	v_pk_add_f32 v[48:49], v[48:49], v[238:239]
	s_mov_b64 exec, s[98:99]
	v_add_u32_e32 v58, 7, v150
	v_cmp_gt_u32_e32 vcc, s9, v58
	s_and_b64 exec, vcc, s[98:99]
	v_pk_add_f32 v[50:51], v[50:51], v[230:231]
	v_pk_add_f32 v[52:53], v[52:53], v[232:233]
	v_pk_add_f32 v[54:55], v[54:55], v[236:237]
	v_pk_add_f32 v[56:57], v[56:57], v[238:239]
	s_mov_b64 exec, s[98:99]
	v_add_u32_e32 v58, 8, v150
	v_cmp_gt_u32_e32 vcc, s9, v58
	s_and_b64 exec, vcc, s[98:99]
	v_pk_add_f32 v[64:65], v[64:65], v[230:231]
	v_pk_add_f32 v[66:67], v[66:67], v[232:233]
	v_pk_add_f32 v[68:69], v[68:69], v[236:237]
	v_pk_add_f32 v[70:71], v[70:71], v[238:239]
	s_mov_b64 exec, s[98:99]
	s_waitcnt vmcnt(18)
	v_add_u32_e32 v58, 6, v150
	v_cmp_gt_u32_e32 vcc, s9, v58
	s_and_b64 exec, vcc, s[98:99]
	v_pk_add_f32 v[34:35], v[34:35], v[240:241]
	v_pk_add_f32 v[36:37], v[36:37], v[242:243]
	v_pk_add_f32 v[38:39], v[38:39], v[244:245]
	v_pk_add_f32 v[40:41], v[40:41], v[246:247]
	s_mov_b64 exec, s[98:99]
	v_add_u32_e32 v58, 7, v150
	v_cmp_gt_u32_e32 vcc, s9, v58
	s_and_b64 exec, vcc, s[98:99]
	v_pk_add_f32 v[42:43], v[42:43], v[240:241]
	v_pk_add_f32 v[44:45], v[44:45], v[242:243]
	v_pk_add_f32 v[46:47], v[46:47], v[244:245]
	v_pk_add_f32 v[48:49], v[48:49], v[246:247]
	s_mov_b64 exec, s[98:99]
	v_add_u32_e32 v58, 8, v150
	v_cmp_gt_u32_e32 vcc, s9, v58
	s_and_b64 exec, vcc, s[98:99]
	v_pk_add_f32 v[50:51], v[50:51], v[240:241]
	v_pk_add_f32 v[52:53], v[52:53], v[242:243]
	v_pk_add_f32 v[54:55], v[54:55], v[244:245]
	v_pk_add_f32 v[56:57], v[56:57], v[246:247]
	s_mov_b64 exec, s[98:99]
	v_add_u32_e32 v58, 9, v150
	v_cmp_gt_u32_e32 vcc, s9, v58
	s_and_b64 exec, vcc, s[98:99]
	v_pk_add_f32 v[64:65], v[64:65], v[240:241]
	v_pk_add_f32 v[66:67], v[66:67], v[242:243]
	v_pk_add_f32 v[68:69], v[68:69], v[244:245]
	v_pk_add_f32 v[70:71], v[70:71], v[246:247]
	s_mov_b64 exec, s[98:99]
	s_waitcnt vmcnt(16)
	v_add_u32_e32 v58, 7, v150
	v_cmp_gt_u32_e32 vcc, s9, v58
	s_and_b64 exec, vcc, s[98:99]
	v_pk_add_f32 v[34:35], v[34:35], v[248:249]
	v_pk_add_f32 v[36:37], v[36:37], v[250:251]
	v_pk_add_f32 v[38:39], v[38:39], v[252:253]
	v_pk_add_f32 v[40:41], v[40:41], v[254:255]
	s_mov_b64 exec, s[98:99]
	v_add_u32_e32 v58, 8, v150
	v_cmp_gt_u32_e32 vcc, s9, v58
	s_and_b64 exec, vcc, s[98:99]
	v_pk_add_f32 v[42:43], v[42:43], v[248:249]
	v_pk_add_f32 v[44:45], v[44:45], v[250:251]
	v_pk_add_f32 v[46:47], v[46:47], v[252:253]
	v_pk_add_f32 v[48:49], v[48:49], v[254:255]
	s_mov_b64 exec, s[98:99]
	v_add_u32_e32 v58, 9, v150
	v_cmp_gt_u32_e32 vcc, s9, v58
	s_and_b64 exec, vcc, s[98:99]
	v_pk_add_f32 v[50:51], v[50:51], v[248:249]
	v_pk_add_f32 v[52:53], v[52:53], v[250:251]
	v_pk_add_f32 v[54:55], v[54:55], v[252:253]
	v_pk_add_f32 v[56:57], v[56:57], v[254:255]
	s_mov_b64 exec, s[98:99]
	v_add_u32_e32 v58, 10, v150
	v_cmp_gt_u32_e32 vcc, s9, v58
	s_and_b64 exec, vcc, s[98:99]
	v_pk_add_f32 v[64:65], v[64:65], v[248:249]
	v_pk_add_f32 v[66:67], v[66:67], v[250:251]
	v_pk_add_f32 v[68:69], v[68:69], v[252:253]
	v_pk_add_f32 v[70:71], v[70:71], v[254:255]
	s_mov_b64 exec, s[98:99]
	s_cmp_lt_u32 s9, 9
	s_cbranch_scc1 ATS1_END
	s_waitcnt vmcnt(14)
	v_add_u32_e32 v58, 8, v150
	v_cmp_gt_u32_e32 vcc, s9, v58
	s_and_b64 exec, vcc, s[98:99]
	v_pk_add_f32 v[34:35], v[34:35], v[72:73]
	v_pk_add_f32 v[36:37], v[36:37], v[74:75]
	v_pk_add_f32 v[38:39], v[38:39], v[80:81]
	v_pk_add_f32 v[40:41], v[40:41], v[82:83]
	s_mov_b64 exec, s[98:99]
	v_add_u32_e32 v58, 9, v150
	v_cmp_gt_u32_e32 vcc, s9, v58
	s_and_b64 exec, vcc, s[98:99]
	v_pk_add_f32 v[42:43], v[42:43], v[72:73]
	v_pk_add_f32 v[44:45], v[44:45], v[74:75]
	v_pk_add_f32 v[46:47], v[46:47], v[80:81]
	v_pk_add_f32 v[48:49], v[48:49], v[82:83]
	s_mov_b64 exec, s[98:99]
	v_add_u32_e32 v58, 10, v150
	v_cmp_gt_u32_e32 vcc, s9, v58
	s_and_b64 exec, vcc, s[98:99]
	v_pk_add_f32 v[50:51], v[50:51], v[72:73]
	v_pk_add_f32 v[52:53], v[52:53], v[74:75]
	v_pk_add_f32 v[54:55], v[54:55], v[80:81]
	v_pk_add_f32 v[56:57], v[56:57], v[82:83]
	s_mov_b64 exec, s[98:99]
	v_add_u32_e32 v58, 11, v150
	v_cmp_gt_u32_e32 vcc, s9, v58
	s_and_b64 exec, vcc, s[98:99]
	v_pk_add_f32 v[64:65], v[64:65], v[72:73]
	v_pk_add_f32 v[66:67], v[66:67], v[74:75]
	v_pk_add_f32 v[68:69], v[68:69], v[80:81]
	v_pk_add_f32 v[70:71], v[70:71], v[82:83]
	s_mov_b64 exec, s[98:99]
	s_waitcnt vmcnt(12)
	v_add_u32_e32 v58, 9, v150
	v_cmp_gt_u32_e32 vcc, s9, v58
	s_and_b64 exec, vcc, s[98:99]
	v_pk_add_f32 v[34:35], v[34:35], v[92:93]
	v_pk_add_f32 v[36:37], v[36:37], v[94:95]
	v_pk_add_f32 v[38:39], v[38:39], v[96:97]
	v_pk_add_f32 v[40:41], v[40:41], v[98:99]
	s_mov_b64 exec, s[98:99]
	v_add_u32_e32 v58, 10, v150
	v_cmp_gt_u32_e32 vcc, s9, v58
	s_and_b64 exec, vcc, s[98:99]
	v_pk_add_f32 v[42:43], v[42:43], v[92:93]
	v_pk_add_f32 v[44:45], v[44:45], v[94:95]
	v_pk_add_f32 v[46:47], v[46:47], v[96:97]
	v_pk_add_f32 v[48:49], v[48:49], v[98:99]
	s_mov_b64 exec, s[98:99]
	v_add_u32_e32 v58, 11, v150
	v_cmp_gt_u32_e32 vcc, s9, v58
	s_and_b64 exec, vcc, s[98:99]
	v_pk_add_f32 v[50:51], v[50:51], v[92:93]
	v_pk_add_f32 v[52:53], v[52:53], v[94:95]
	v_pk_add_f32 v[54:55], v[54:55], v[96:97]
	v_pk_add_f32 v[56:57], v[56:57], v[98:99]
	s_mov_b64 exec, s[98:99]
	v_add_u32_e32 v58, 12, v150
	v_cmp_gt_u32_e32 vcc, s9, v58
	s_and_b64 exec, vcc, s[98:99]
	v_pk_add_f32 v[64:65], v[64:65], v[92:93]
	v_pk_add_f32 v[66:67], v[66:67], v[94:95]
	v_pk_add_f32 v[68:69], v[68:69], v[96:97]
	v_pk_add_f32 v[70:71], v[70:71], v[98:99]
	s_mov_b64 exec, s[98:99]
	s_waitcnt vmcnt(10)
	v_add_u32_e32 v58, 10, v150
	v_cmp_gt_u32_e32 vcc, s9, v58
	s_and_b64 exec, vcc, s[98:99]
	v_pk_add_f32 v[34:35], v[34:35], v[100:101]
	v_pk_add_f32 v[36:37], v[36:37], v[102:103]
	v_pk_add_f32 v[38:39], v[38:39], v[104:105]
	v_pk_add_f32 v[40:41], v[40:41], v[106:107]
	s_mov_b64 exec, s[98:99]
	v_add_u32_e32 v58, 11, v150
	v_cmp_gt_u32_e32 vcc, s9, v58
	s_and_b64 exec, vcc, s[98:99]
	v_pk_add_f32 v[42:43], v[42:43], v[100:101]
	v_pk_add_f32 v[44:45], v[44:45], v[102:103]
	v_pk_add_f32 v[46:47], v[46:47], v[104:105]
	v_pk_add_f32 v[48:49], v[48:49], v[106:107]
	s_mov_b64 exec, s[98:99]
	v_add_u32_e32 v58, 12, v150
	v_cmp_gt_u32_e32 vcc, s9, v58
	s_and_b64 exec, vcc, s[98:99]
	v_pk_add_f32 v[50:51], v[50:51], v[100:101]
	v_pk_add_f32 v[52:53], v[52:53], v[102:103]
	v_pk_add_f32 v[54:55], v[54:55], v[104:105]
	v_pk_add_f32 v[56:57], v[56:57], v[106:107]
	s_mov_b64 exec, s[98:99]
	v_add_u32_e32 v58, 13, v150
	v_cmp_gt_u32_e32 vcc, s9, v58
	s_and_b64 exec, vcc, s[98:99]
	v_pk_add_f32 v[64:65], v[64:65], v[100:101]
	v_pk_add_f32 v[66:67], v[66:67], v[102:103]
	v_pk_add_f32 v[68:69], v[68:69], v[104:105]
	v_pk_add_f32 v[70:71], v[70:71], v[106:107]
	s_mov_b64 exec, s[98:99]
	s_waitcnt vmcnt(8)
	v_add_u32_e32 v58, 11, v150
	v_cmp_gt_u32_e32 vcc, s9, v58
	s_and_b64 exec, vcc, s[98:99]
	v_pk_add_f32 v[34:35], v[34:35], v[108:109]
	v_pk_add_f32 v[36:37], v[36:37], v[110:111]
	v_pk_add_f32 v[38:39], v[38:39], v[112:113]
	v_pk_add_f32 v[40:41], v[40:41], v[114:115]
	s_mov_b64 exec, s[98:99]
	v_add_u32_e32 v58, 12, v150
	v_cmp_gt_u32_e32 vcc, s9, v58
	s_and_b64 exec, vcc, s[98:99]
	v_pk_add_f32 v[42:43], v[42:43], v[108:109]
	v_pk_add_f32 v[44:45], v[44:45], v[110:111]
	v_pk_add_f32 v[46:47], v[46:47], v[112:113]
	v_pk_add_f32 v[48:49], v[48:49], v[114:115]
	s_mov_b64 exec, s[98:99]
	v_add_u32_e32 v58, 13, v150
	v_cmp_gt_u32_e32 vcc, s9, v58
	s_and_b64 exec, vcc, s[98:99]
	v_pk_add_f32 v[50:51], v[50:51], v[108:109]
	v_pk_add_f32 v[52:53], v[52:53], v[110:111]
	v_pk_add_f32 v[54:55], v[54:55], v[112:113]
	v_pk_add_f32 v[56:57], v[56:57], v[114:115]
	s_mov_b64 exec, s[98:99]
	v_add_u32_e32 v58, 14, v150
	v_cmp_gt_u32_e32 vcc, s9, v58
	s_and_b64 exec, vcc, s[98:99]
	v_pk_add_f32 v[64:65], v[64:65], v[108:109]
	v_pk_add_f32 v[66:67], v[66:67], v[110:111]
	v_pk_add_f32 v[68:69], v[68:69], v[112:113]
	v_pk_add_f32 v[70:71], v[70:71], v[114:115]
	s_mov_b64 exec, s[98:99]
	s_waitcnt vmcnt(6)
	v_add_u32_e32 v58, 12, v150
	v_cmp_gt_u32_e32 vcc, s9, v58
	s_and_b64 exec, vcc, s[98:99]
	v_pk_add_f32 v[34:35], v[34:35], v[116:117]
	v_pk_add_f32 v[36:37], v[36:37], v[118:119]
	v_pk_add_f32 v[38:39], v[38:39], v[120:121]
	v_pk_add_f32 v[40:41], v[40:41], v[122:123]
	s_mov_b64 exec, s[98:99]
	v_add_u32_e32 v58, 13, v150
	v_cmp_gt_u32_e32 vcc, s9, v58
	s_and_b64 exec, vcc, s[98:99]
	v_pk_add_f32 v[42:43], v[42:43], v[116:117]
	v_pk_add_f32 v[44:45], v[44:45], v[118:119]
	v_pk_add_f32 v[46:47], v[46:47], v[120:121]
	v_pk_add_f32 v[48:49], v[48:49], v[122:123]
	s_mov_b64 exec, s[98:99]
	v_add_u32_e32 v58, 14, v150
	v_cmp_gt_u32_e32 vcc, s9, v58
	s_and_b64 exec, vcc, s[98:99]
	v_pk_add_f32 v[50:51], v[50:51], v[116:117]
	v_pk_add_f32 v[52:53], v[52:53], v[118:119]
	v_pk_add_f32 v[54:55], v[54:55], v[120:121]
	v_pk_add_f32 v[56:57], v[56:57], v[122:123]
	s_mov_b64 exec, s[98:99]
	v_add_u32_e32 v58, 15, v150
	v_cmp_gt_u32_e32 vcc, s9, v58
	s_and_b64 exec, vcc, s[98:99]
	v_pk_add_f32 v[64:65], v[64:65], v[116:117]
	v_pk_add_f32 v[66:67], v[66:67], v[118:119]
	v_pk_add_f32 v[68:69], v[68:69], v[120:121]
	v_pk_add_f32 v[70:71], v[70:71], v[122:123]
	s_mov_b64 exec, s[98:99]
	s_waitcnt vmcnt(4)
	v_add_u32_e32 v58, 13, v150
	v_cmp_gt_u32_e32 vcc, s9, v58
	s_and_b64 exec, vcc, s[98:99]
	v_pk_add_f32 v[34:35], v[34:35], v[124:125]
	v_pk_add_f32 v[36:37], v[36:37], v[126:127]
	v_pk_add_f32 v[38:39], v[38:39], v[128:129]
	v_pk_add_f32 v[40:41], v[40:41], v[130:131]
	s_mov_b64 exec, s[98:99]
	v_add_u32_e32 v58, 14, v150
	v_cmp_gt_u32_e32 vcc, s9, v58
	s_and_b64 exec, vcc, s[98:99]
	v_pk_add_f32 v[42:43], v[42:43], v[124:125]
	v_pk_add_f32 v[44:45], v[44:45], v[126:127]
	v_pk_add_f32 v[46:47], v[46:47], v[128:129]
	v_pk_add_f32 v[48:49], v[48:49], v[130:131]
	s_mov_b64 exec, s[98:99]
	v_add_u32_e32 v58, 15, v150
	v_cmp_gt_u32_e32 vcc, s9, v58
	s_and_b64 exec, vcc, s[98:99]
	v_pk_add_f32 v[50:51], v[50:51], v[124:125]
	v_pk_add_f32 v[52:53], v[52:53], v[126:127]
	v_pk_add_f32 v[54:55], v[54:55], v[128:129]
	v_pk_add_f32 v[56:57], v[56:57], v[130:131]
	s_mov_b64 exec, s[98:99]
	s_waitcnt vmcnt(2)
	v_add_u32_e32 v58, 14, v150
	v_cmp_gt_u32_e32 vcc, s9, v58
	s_and_b64 exec, vcc, s[98:99]
	v_pk_add_f32 v[34:35], v[34:35], v[132:133]
	v_pk_add_f32 v[36:37], v[36:37], v[134:135]
	v_pk_add_f32 v[38:39], v[38:39], v[136:137]
	v_pk_add_f32 v[40:41], v[40:41], v[138:139]
	s_mov_b64 exec, s[98:99]
	v_add_u32_e32 v58, 15, v150
	v_cmp_gt_u32_e32 vcc, s9, v58
	s_and_b64 exec, vcc, s[98:99]
	v_pk_add_f32 v[42:43], v[42:43], v[132:133]
	v_pk_add_f32 v[44:45], v[44:45], v[134:135]
	v_pk_add_f32 v[46:47], v[46:47], v[136:137]
	v_pk_add_f32 v[48:49], v[48:49], v[138:139]
	s_mov_b64 exec, s[98:99]
	s_waitcnt vmcnt(0)
	v_add_u32_e32 v58, 15, v150
	v_cmp_gt_u32_e32 vcc, s9, v58
	s_and_b64 exec, vcc, s[98:99]
	v_pk_add_f32 v[34:35], v[34:35], v[176:177]
	v_pk_add_f32 v[36:37], v[36:37], v[178:179]
	v_pk_add_f32 v[38:39], v[38:39], v[180:181]
	v_pk_add_f32 v[40:41], v[40:41], v[182:183]
	s_mov_b64 exec, s[98:99]
ATS1_END:
	s_waitcnt vmcnt(0)
	v_ffbl_b32_e32 v58, s9
	v_lshlrev_b32_e32 v58, 23, v58
	v_sub_u32_e32 v58, 0x3f800000, v58
	v_lshlrev_b32_e32 v72, 16, v0
	v_and_b32_e32 v73, 0xffff0000, v0
	v_lshlrev_b32_e32 v74, 16, v1
	v_and_b32_e32 v75, 0xffff0000, v1
	v_lshlrev_b32_e32 v80, 16, v2
	v_and_b32_e32 v81, 0xffff0000, v2
	v_lshlrev_b32_e32 v82, 16, v3
	v_and_b32_e32 v83, 0xffff0000, v3
	v_fma_f32 v72, v58, v34, -v72
	v_fma_f32 v73, v58, v35, -v73
	v_fma_f32 v74, v58, v36, -v74
	v_fma_f32 v75, v58, v37, -v75
	v_fma_f32 v80, v58, v38, -v80
	v_fma_f32 v81, v58, v39, -v81
	v_fma_f32 v82, v58, v40, -v82
	v_fma_f32 v83, v58, v41, -v83
	v_cvt_pk_bf16_f32 v12, v72, v73
	v_cvt_pk_bf16_f32 v13, v74, v75
	v_cvt_pk_bf16_f32 v14, v80, v81
	v_cvt_pk_bf16_f32 v15, v82, v83
	v_lshlrev_b32_e32 v72, 16, v4
	v_and_b32_e32 v73, 0xffff0000, v4
	v_lshlrev_b32_e32 v74, 16, v5
	v_and_b32_e32 v75, 0xffff0000, v5
	v_lshlrev_b32_e32 v80, 16, v6
	v_and_b32_e32 v81, 0xffff0000, v6
	v_lshlrev_b32_e32 v82, 16, v7
	v_and_b32_e32 v83, 0xffff0000, v7
	v_fma_f32 v72, v58, v42, -v72
	v_fma_f32 v73, v58, v43, -v73
	v_fma_f32 v74, v58, v44, -v74
	v_fma_f32 v75, v58, v45, -v75
	v_fma_f32 v80, v58, v46, -v80
	v_fma_f32 v81, v58, v47, -v81
	v_fma_f32 v82, v58, v48, -v82
	v_fma_f32 v83, v58, v49, -v83
	v_cvt_pk_bf16_f32 v16, v72, v73
	v_cvt_pk_bf16_f32 v17, v74, v75
	v_cvt_pk_bf16_f32 v18, v80, v81
	v_cvt_pk_bf16_f32 v19, v82, v83
	v_lshlrev_b32_e32 v72, 16, v8
	v_and_b32_e32 v73, 0xffff0000, v8
	v_lshlrev_b32_e32 v74, 16, v9
	v_and_b32_e32 v75, 0xffff0000, v9
	v_lshlrev_b32_e32 v80, 16, v10
	v_and_b32_e32 v81, 0xffff0000, v10
	v_lshlrev_b32_e32 v82, 16, v11
	v_and_b32_e32 v83, 0xffff0000, v11
	v_fma_f32 v72, v58, v50, -v72
	v_fma_f32 v73, v58, v51, -v73
	v_fma_f32 v74, v58, v52, -v74
	v_fma_f32 v75, v58, v53, -v75
	v_fma_f32 v80, v58, v54, -v80
	v_fma_f32 v81, v58, v55, -v81
	v_fma_f32 v82, v58, v56, -v82
	v_fma_f32 v83, v58, v57, -v83
	v_cvt_pk_bf16_f32 v20, v72, v73
	v_cvt_pk_bf16_f32 v21, v74, v75
	v_cvt_pk_bf16_f32 v22, v80, v81
	v_cvt_pk_bf16_f32 v23, v82, v83
	v_lshlrev_b32_e32 v72, 16, v24
	v_and_b32_e32 v73, 0xffff0000, v24
	v_lshlrev_b32_e32 v74, 16, v25
	v_and_b32_e32 v75, 0xffff0000, v25
	v_lshlrev_b32_e32 v80, 16, v26
	v_and_b32_e32 v81, 0xffff0000, v26
	v_lshlrev_b32_e32 v82, 16, v27
	v_and_b32_e32 v83, 0xffff0000, v27
	v_fma_f32 v72, v58, v64, -v72
	v_fma_f32 v73, v58, v65, -v73
	v_fma_f32 v74, v58, v66, -v74
	v_fma_f32 v75, v58, v67, -v75
	v_fma_f32 v80, v58, v68, -v80
	v_fma_f32 v81, v58, v69, -v81
	v_fma_f32 v82, v58, v70, -v82
	v_fma_f32 v83, v58, v71, -v83
	v_cvt_pk_bf16_f32 v28, v72, v73
	v_cvt_pk_bf16_f32 v29, v74, v75
	v_cvt_pk_bf16_f32 v30, v80, v81
	v_cvt_pk_bf16_f32 v31, v82, v83
	s_branch .LBB0_1009

.LBB0_1692:
	s_and_b64 vcc, exec, s[0:1]
	s_cbranch_vccz .LBB0_1718
	s_lshl_b64 s[0:1], s[10:11], 2
	s_add_u32 s0, s56, s0
	s_addc_u32 s1, s57, s1
	v_mov_b32_e32 v8, 0
	s_lshl_b32 s9, 2, s6
	v_lshl_add_u64 v[28:29], v[32:33], 1, s[52:53]
	v_lshl_add_u64 v[30:31], v[32:33], 2, s[0:1]
	v_add_u32_e32 v12, s37, v150
	s_mov_b64 s[98:99], exec
	v_mov_b32_e32 v12, v28
	v_mov_b32_e32 v13, v29
	v_mov_b32_e32 v14, v30
	v_mov_b32_e32 v15, v31
	v_mov_b32_e32 v59, s37
	v_add3_u32 v58, v150, v59, 0
	v_mad_u64_u32 v[0:1], vcc, v58, s31, v[12:13]
	global_load_dwordx4 v[0:3], v[0:1], off
	v_add3_u32 v58, v150, v59, 1
	v_mad_u64_u32 v[4:5], vcc, v58, s31, v[12:13]
	global_load_dwordx4 v[4:7], v[4:5], off
	v_add3_u32 v58, v150, v59, 2
	v_mad_u64_u32 v[8:9], vcc, v58, s31, v[12:13]
	global_load_dwordx4 v[8:11], v[8:9], off
	v_add3_u32 v58, v150, v59, 3
	v_mad_u64_u32 v[24:25], vcc, v58, s31, v[12:13]
	global_load_dwordx4 v[24:27], v[24:25], off
	v_add_u32_e32 v58, 15, v59
	v_mad_u64_u32 v[72:73], vcc, v58, s31, v[12:13]
	global_load_dwordx4 v[72:75], v[72:73], off
	v_add_u32_e32 v58, 14, v59
	v_mad_u64_u32 v[80:81], vcc, v58, s31, v[12:13]
	global_load_dwordx4 v[80:83], v[80:81], off
	v_add_u32_e32 v58, 13, v59
	v_mad_u64_u32 v[92:93], vcc, v58, s31, v[12:13]
	global_load_dwordx4 v[92:95], v[92:93], off
	v_add_u32_e32 v58, 12, v59
	v_mad_u64_u32 v[96:97], vcc, v58, s31, v[12:13]
	global_load_dwordx4 v[96:99], v[96:97], off
	v_add_u32_e32 v58, 11, v59
	v_mad_u64_u32 v[100:101], vcc, v58, s31, v[12:13]
	global_load_dwordx4 v[100:103], v[100:101], off
	v_add_u32_e32 v58, 10, v59
	v_mad_u64_u32 v[104:105], vcc, v58, s31, v[12:13]
	global_load_dwordx4 v[104:107], v[104:105], off
	v_add_u32_e32 v58, 9, v59
	v_mad_u64_u32 v[108:109], vcc, v58, s31, v[12:13]
	global_load_dwordx4 v[108:111], v[108:109], off
	v_add_u32_e32 v58, 8, v59
	v_mad_u64_u32 v[112:113], vcc, v58, s31, v[12:13]
	global_load_dwordx4 v[112:115], v[112:113], off
	v_add_u32_e32 v58, 7, v59
	v_mad_u64_u32 v[116:117], vcc, v58, s31, v[12:13]
	global_load_dwordx4 v[116:119], v[116:117], off
	v_add_u32_e32 v58, 6, v59
	v_mad_u64_u32 v[120:121], vcc, v58, s31, v[12:13]
	global_load_dwordx4 v[120:123], v[120:121], off
	v_add_u32_e32 v58, 5, v59
	v_mad_u64_u32 v[124:125], vcc, v58, s31, v[12:13]
	global_load_dwordx4 v[124:127], v[124:125], off
	v_add_u32_e32 v58, 4, v59
	v_mad_u64_u32 v[128:129], vcc, v58, s31, v[12:13]
	global_load_dwordx4 v[128:131], v[128:129], off
	v_add_u32_e32 v58, 3, v59
	v_mad_u64_u32 v[132:133], vcc, v58, s31, v[12:13]
	global_load_dwordx4 v[132:135], v[132:133], off
	v_add_u32_e32 v58, 2, v59
	v_mad_u64_u32 v[136:137], vcc, v58, s31, v[12:13]
	global_load_dwordx4 v[136:139], v[136:137], off
	v_add_u32_e32 v58, 1, v59
	v_mad_u64_u32 v[176:177], vcc, v58, s31, v[12:13]
	global_load_dwordx4 v[176:179], v[176:177], off
	v_add_u32_e32 v58, 0, v59
	v_mad_u64_u32 v[180:181], vcc, v58, s31, v[12:13]
	global_load_dwordx4 v[180:183], v[180:181], off
	v_add_co_u32_e32 v184, vcc, 0x7000, v14
	v_addc_co_u32_e32 v185, vcc, 0, v15, vcc
	global_load_dwordx4 v[188:191], v[184:185], off offset:16
	global_load_dwordx4 v[184:187], v[184:185], off
	v_add_co_u32_e32 v192, vcc, 0x6800, v14
	v_addc_co_u32_e32 v193, vcc, 0, v15, vcc
	global_load_dwordx4 v[196:199], v[192:193], off offset:16
	global_load_dwordx4 v[192:195], v[192:193], off
	v_add_co_u32_e32 v200, vcc, 0x6000, v14
	v_addc_co_u32_e32 v201, vcc, 0, v15, vcc
	global_load_dwordx4 v[218:221], v[200:201], off offset:16
	global_load_dwordx4 v[200:203], v[200:201], off
	v_add_co_u32_e32 v222, vcc, 0x5800, v14
	v_addc_co_u32_e32 v223, vcc, 0, v15, vcc
	global_load_dwordx4 v[226:229], v[222:223], off offset:16
	global_load_dwordx4 v[222:225], v[222:223], off
	v_add_co_u32_e32 v230, vcc, 0x5000, v14
	v_addc_co_u32_e32 v231, vcc, 0, v15, vcc
	global_load_dwordx4 v[236:239], v[230:231], off offset:16
	global_load_dwordx4 v[230:233], v[230:231], off
	v_add_co_u32_e32 v240, vcc, 0x4800, v14
	v_addc_co_u32_e32 v241, vcc, 0, v15, vcc
	global_load_dwordx4 v[244:247], v[240:241], off offset:16
	global_load_dwordx4 v[240:243], v[240:241], off
	v_add_co_u32_e32 v248, vcc, 0x4000, v14
	v_addc_co_u32_e32 v249, vcc, 0, v15, vcc
	global_load_dwordx4 v[252:255], v[248:249], off offset:16
	global_load_dwordx4 v[248:251], v[248:249], off
	v_mov_b32_e32 v34, 0
	v_mov_b32_e32 v35, 0
	v_mov_b32_e32 v36, 0
	v_mov_b32_e32 v37, 0
	v_mov_b32_e32 v38, 0
	v_mov_b32_e32 v39, 0
	v_mov_b32_e32 v40, 0
	v_mov_b32_e32 v41, 0
	v_mov_b32_e32 v42, 0
	v_mov_b32_e32 v43, 0
	v_mov_b32_e32 v44, 0
	v_mov_b32_e32 v45, 0
	v_mov_b32_e32 v46, 0
	v_mov_b32_e32 v47, 0
	v_mov_b32_e32 v48, 0
	v_mov_b32_e32 v49, 0
	v_mov_b32_e32 v50, 0
	v_mov_b32_e32 v51, 0
	v_mov_b32_e32 v52, 0
	v_mov_b32_e32 v53, 0
	v_mov_b32_e32 v54, 0
	v_mov_b32_e32 v55, 0
	v_mov_b32_e32 v56, 0
	v_mov_b32_e32 v57, 0
	v_mov_b32_e32 v64, 0
	v_mov_b32_e32 v65, 0
	v_mov_b32_e32 v66, 0
	v_mov_b32_e32 v67, 0
	v_mov_b32_e32 v68, 0
	v_mov_b32_e32 v69, 0
	v_mov_b32_e32 v70, 0
	v_mov_b32_e32 v71, 0
	s_waitcnt vmcnt(29)
	v_lshlrev_b32_e32 v16, 16, v72
	v_and_b32_e32 v17, 0xffff0000, v72
	v_lshlrev_b32_e32 v18, 16, v73
	v_and_b32_e32 v19, 0xffff0000, v73
	v_lshlrev_b32_e32 v20, 16, v74
	v_and_b32_e32 v21, 0xffff0000, v74
	v_lshlrev_b32_e32 v22, 16, v75
	v_and_b32_e32 v23, 0xffff0000, v75
	v_add_u32_e32 v58, -12, v150
	v_cmp_gt_u32_e32 vcc, s9, v58
	s_and_b64 exec, vcc, s[98:99]
	v_pk_add_f32 v[64:65], v[64:65], v[16:17]
	v_pk_add_f32 v[66:67], v[66:67], v[18:19]
	v_pk_add_f32 v[68:69], v[68:69], v[20:21]
	v_pk_add_f32 v[70:71], v[70:71], v[22:23]
	s_mov_b64 exec, s[98:99]
	s_waitcnt vmcnt(28)
	v_lshlrev_b32_e32 v16, 16, v80
	v_and_b32_e32 v17, 0xffff0000, v80
	v_lshlrev_b32_e32 v18, 16, v81
	v_and_b32_e32 v19, 0xffff0000, v81
	v_lshlrev_b32_e32 v20, 16, v82
	v_and_b32_e32 v21, 0xffff0000, v82
	v_lshlrev_b32_e32 v22, 16, v83
	v_and_b32_e32 v23, 0xffff0000, v83
	v_add_u32_e32 v58, -12, v150
	v_cmp_gt_u32_e32 vcc, s9, v58
	s_and_b64 exec, vcc, s[98:99]
	v_pk_add_f32 v[50:51], v[50:51], v[16:17]
	v_pk_add_f32 v[52:53], v[52:53], v[18:19]
	v_pk_add_f32 v[54:55], v[54:55], v[20:21]
	v_pk_add_f32 v[56:57], v[56:57], v[22:23]
	s_mov_b64 exec, s[98:99]
	v_add_u32_e32 v58, -11, v150
	v_cmp_gt_u32_e32 vcc, s9, v58
	s_and_b64 exec, vcc, s[98:99]
	v_pk_add_f32 v[64:65], v[64:65], v[16:17]
	v_pk_add_f32 v[66:67], v[66:67], v[18:19]
	v_pk_add_f32 v[68:69], v[68:69], v[20:21]
	v_pk_add_f32 v[70:71], v[70:71], v[22:23]
	s_mov_b64 exec, s[98:99]
	s_waitcnt vmcnt(27)
	v_lshlrev_b32_e32 v16, 16, v92
	v_and_b32_e32 v17, 0xffff0000, v92
	v_lshlrev_b32_e32 v18, 16, v93
	v_and_b32_e32 v19, 0xffff0000, v93
	v_lshlrev_b32_e32 v20, 16, v94
	v_and_b32_e32 v21, 0xffff0000, v94
	v_lshlrev_b32_e32 v22, 16, v95
	v_and_b32_e32 v23, 0xffff0000, v95
	v_add_u32_e32 v58, -12, v150
	v_cmp_gt_u32_e32 vcc, s9, v58
	s_and_b64 exec, vcc, s[98:99]
	v_pk_add_f32 v[42:43], v[42:43], v[16:17]
	v_pk_add_f32 v[44:45], v[44:45], v[18:19]
	v_pk_add_f32 v[46:47], v[46:47], v[20:21]
	v_pk_add_f32 v[48:49], v[48:49], v[22:23]
	s_mov_b64 exec, s[98:99]
	v_add_u32_e32 v58, -11, v150
	v_cmp_gt_u32_e32 vcc, s9, v58
	s_and_b64 exec, vcc, s[98:99]
	v_pk_add_f32 v[50:51], v[50:51], v[16:17]
	v_pk_add_f32 v[52:53], v[52:53], v[18:19]
	v_pk_add_f32 v[54:55], v[54:55], v[20:21]
	v_pk_add_f32 v[56:57], v[56:57], v[22:23]
	s_mov_b64 exec, s[98:99]
	v_add_u32_e32 v58, -10, v150
	v_cmp_gt_u32_e32 vcc, s9, v58
	s_and_b64 exec, vcc, s[98:99]
	v_pk_add_f32 v[64:65], v[64:65], v[16:17]
	v_pk_add_f32 v[66:67], v[66:67], v[18:19]
	v_pk_add_f32 v[68:69], v[68:69], v[20:21]
	v_pk_add_f32 v[70:71], v[70:71], v[22:23]
	s_mov_b64 exec, s[98:99]
	s_waitcnt vmcnt(26)
	v_lshlrev_b32_e32 v16, 16, v96
	v_and_b32_e32 v17, 0xffff0000, v96
	v_lshlrev_b32_e32 v18, 16, v97
	v_and_b32_e32 v19, 0xffff0000, v97
	v_lshlrev_b32_e32 v20, 16, v98
	v_and_b32_e32 v21, 0xffff0000, v98
	v_lshlrev_b32_e32 v22, 16, v99
	v_and_b32_e32 v23, 0xffff0000, v99
	v_add_u32_e32 v58, -12, v150
	v_cmp_gt_u32_e32 vcc, s9, v58
	s_and_b64 exec, vcc, s[98:99]
	v_pk_add_f32 v[34:35], v[34:35], v[16:17]
	v_pk_add_f32 v[36:37], v[36:37], v[18:19]
	v_pk_add_f32 v[38:39], v[38:39], v[20:21]
	v_pk_add_f32 v[40:41], v[40:41], v[22:23]
	s_mov_b64 exec, s[98:99]
	v_add_u32_e32 v58, -11, v150
	v_cmp_gt_u32_e32 vcc, s9, v58
	s_and_b64 exec, vcc, s[98:99]
	v_pk_add_f32 v[42:43], v[42:43], v[16:17]
	v_pk_add_f32 v[44:45], v[44:45], v[18:19]
	v_pk_add_f32 v[46:47], v[46:47], v[20:21]
	v_pk_add_f32 v[48:49], v[48:49], v[22:23]
	s_mov_b64 exec, s[98:99]
	v_add_u32_e32 v58, -10, v150
	v_cmp_gt_u32_e32 vcc, s9, v58
	s_and_b64 exec, vcc, s[98:99]
	v_pk_add_f32 v[50:51], v[50:51], v[16:17]
	v_pk_add_f32 v[52:53], v[52:53], v[18:19]
	v_pk_add_f32 v[54:55], v[54:55], v[20:21]
	v_pk_add_f32 v[56:57], v[56:57], v[22:23]
	s_mov_b64 exec, s[98:99]
	v_add_u32_e32 v58, -9, v150
	v_cmp_gt_u32_e32 vcc, s9, v58
	s_and_b64 exec, vcc, s[98:99]
	v_pk_add_f32 v[64:65], v[64:65], v[16:17]
	v_pk_add_f32 v[66:67], v[66:67], v[18:19]
	v_pk_add_f32 v[68:69], v[68:69], v[20:21]
	v_pk_add_f32 v[70:71], v[70:71], v[22:23]
	s_mov_b64 exec, s[98:99]
	s_waitcnt vmcnt(25)
	v_lshlrev_b32_e32 v16, 16, v100
	v_and_b32_e32 v17, 0xffff0000, v100
	v_lshlrev_b32_e32 v18, 16, v101
	v_and_b32_e32 v19, 0xffff0000, v101
	v_lshlrev_b32_e32 v20, 16, v102
	v_and_b32_e32 v21, 0xffff0000, v102
	v_lshlrev_b32_e32 v22, 16, v103
	v_and_b32_e32 v23, 0xffff0000, v103
	v_add_u32_e32 v58, -11, v150
	v_cmp_gt_u32_e32 vcc, s9, v58
	s_and_b64 exec, vcc, s[98:99]
	v_pk_add_f32 v[34:35], v[34:35], v[16:17]
	v_pk_add_f32 v[36:37], v[36:37], v[18:19]
	v_pk_add_f32 v[38:39], v[38:39], v[20:21]
	v_pk_add_f32 v[40:41], v[40:41], v[22:23]
	s_mov_b64 exec, s[98:99]
	v_add_u32_e32 v58, -10, v150
	v_cmp_gt_u32_e32 vcc, s9, v58
	s_and_b64 exec, vcc, s[98:99]
	v_pk_add_f32 v[42:43], v[42:43], v[16:17]
	v_pk_add_f32 v[44:45], v[44:45], v[18:19]
	v_pk_add_f32 v[46:47], v[46:47], v[20:21]
	v_pk_add_f32 v[48:49], v[48:49], v[22:23]
	s_mov_b64 exec, s[98:99]
	v_add_u32_e32 v58, -9, v150
	v_cmp_gt_u32_e32 vcc, s9, v58
	s_and_b64 exec, vcc, s[98:99]
	v_pk_add_f32 v[50:51], v[50:51], v[16:17]
	v_pk_add_f32 v[52:53], v[52:53], v[18:19]
	v_pk_add_f32 v[54:55], v[54:55], v[20:21]
	v_pk_add_f32 v[56:57], v[56:57], v[22:23]
	s_mov_b64 exec, s[98:99]
	v_add_u32_e32 v58, -8, v150
	v_cmp_gt_u32_e32 vcc, s9, v58
	s_and_b64 exec, vcc, s[98:99]
	v_pk_add_f32 v[64:65], v[64:65], v[16:17]
	v_pk_add_f32 v[66:67], v[66:67], v[18:19]
	v_pk_add_f32 v[68:69], v[68:69], v[20:21]
	v_pk_add_f32 v[70:71], v[70:71], v[22:23]
	s_mov_b64 exec, s[98:99]
	s_waitcnt vmcnt(24)
	v_lshlrev_b32_e32 v16, 16, v104
	v_and_b32_e32 v17, 0xffff0000, v104
	v_lshlrev_b32_e32 v18, 16, v105
	v_and_b32_e32 v19, 0xffff0000, v105
	v_lshlrev_b32_e32 v20, 16, v106
	v_and_b32_e32 v21, 0xffff0000, v106
	v_lshlrev_b32_e32 v22, 16, v107
	v_and_b32_e32 v23, 0xffff0000, v107
	v_add_u32_e32 v58, -10, v150
	v_cmp_gt_u32_e32 vcc, s9, v58
	s_and_b64 exec, vcc, s[98:99]
	v_pk_add_f32 v[34:35], v[34:35], v[16:17]
	v_pk_add_f32 v[36:37], v[36:37], v[18:19]
	v_pk_add_f32 v[38:39], v[38:39], v[20:21]
	v_pk_add_f32 v[40:41], v[40:41], v[22:23]
	s_mov_b64 exec, s[98:99]
	v_add_u32_e32 v58, -9, v150
	v_cmp_gt_u32_e32 vcc, s9, v58
	s_and_b64 exec, vcc, s[98:99]
	v_pk_add_f32 v[42:43], v[42:43], v[16:17]
	v_pk_add_f32 v[44:45], v[44:45], v[18:19]
	v_pk_add_f32 v[46:47], v[46:47], v[20:21]
	v_pk_add_f32 v[48:49], v[48:49], v[22:23]
	s_mov_b64 exec, s[98:99]
	v_add_u32_e32 v58, -8, v150
	v_cmp_gt_u32_e32 vcc, s9, v58
	s_and_b64 exec, vcc, s[98:99]
	v_pk_add_f32 v[50:51], v[50:51], v[16:17]
	v_pk_add_f32 v[52:53], v[52:53], v[18:19]
	v_pk_add_f32 v[54:55], v[54:55], v[20:21]
	v_pk_add_f32 v[56:57], v[56:57], v[22:23]
	s_mov_b64 exec, s[98:99]
	v_add_u32_e32 v58, -7, v150
	v_cmp_gt_u32_e32 vcc, s9, v58
	s_and_b64 exec, vcc, s[98:99]
	v_pk_add_f32 v[64:65], v[64:65], v[16:17]
	v_pk_add_f32 v[66:67], v[66:67], v[18:19]
	v_pk_add_f32 v[68:69], v[68:69], v[20:21]
	v_pk_add_f32 v[70:71], v[70:71], v[22:23]
	s_mov_b64 exec, s[98:99]
	s_waitcnt vmcnt(23)
	v_lshlrev_b32_e32 v16, 16, v108
	v_and_b32_e32 v17, 0xffff0000, v108
	v_lshlrev_b32_e32 v18, 16, v109
	v_and_b32_e32 v19, 0xffff0000, v109
	v_lshlrev_b32_e32 v20, 16, v110
	v_and_b32_e32 v21, 0xffff0000, v110
	v_lshlrev_b32_e32 v22, 16, v111
	v_and_b32_e32 v23, 0xffff0000, v111
	v_add_u32_e32 v58, -9, v150
	v_cmp_gt_u32_e32 vcc, s9, v58
	s_and_b64 exec, vcc, s[98:99]
	v_pk_add_f32 v[34:35], v[34:35], v[16:17]
	v_pk_add_f32 v[36:37], v[36:37], v[18:19]
	v_pk_add_f32 v[38:39], v[38:39], v[20:21]
	v_pk_add_f32 v[40:41], v[40:41], v[22:23]
	s_mov_b64 exec, s[98:99]
	v_add_u32_e32 v58, -8, v150
	v_cmp_gt_u32_e32 vcc, s9, v58
	s_and_b64 exec, vcc, s[98:99]
	v_pk_add_f32 v[42:43], v[42:43], v[16:17]
	v_pk_add_f32 v[44:45], v[44:45], v[18:19]
	v_pk_add_f32 v[46:47], v[46:47], v[20:21]
	v_pk_add_f32 v[48:49], v[48:49], v[22:23]
	s_mov_b64 exec, s[98:99]
	v_add_u32_e32 v58, -7, v150
	v_cmp_gt_u32_e32 vcc, s9, v58
	s_and_b64 exec, vcc, s[98:99]
	v_pk_add_f32 v[50:51], v[50:51], v[16:17]
	v_pk_add_f32 v[52:53], v[52:53], v[18:19]
	v_pk_add_f32 v[54:55], v[54:55], v[20:21]
	v_pk_add_f32 v[56:57], v[56:57], v[22:23]
	s_mov_b64 exec, s[98:99]
	v_add_u32_e32 v58, -6, v150
	v_cmp_gt_u32_e32 vcc, s9, v58
	s_and_b64 exec, vcc, s[98:99]
	v_pk_add_f32 v[64:65], v[64:65], v[16:17]
	v_pk_add_f32 v[66:67], v[66:67], v[18:19]
	v_pk_add_f32 v[68:69], v[68:69], v[20:21]
	v_pk_add_f32 v[70:71], v[70:71], v[22:23]
	s_mov_b64 exec, s[98:99]
	s_waitcnt vmcnt(22)
	v_lshlrev_b32_e32 v16, 16, v112
	v_and_b32_e32 v17, 0xffff0000, v112
	v_lshlrev_b32_e32 v18, 16, v113
	v_and_b32_e32 v19, 0xffff0000, v113
	v_lshlrev_b32_e32 v20, 16, v114
	v_and_b32_e32 v21, 0xffff0000, v114
	v_lshlrev_b32_e32 v22, 16, v115
	v_and_b32_e32 v23, 0xffff0000, v115
	v_add_u32_e32 v58, -8, v150
	v_cmp_gt_u32_e32 vcc, s9, v58
	s_and_b64 exec, vcc, s[98:99]
	v_pk_add_f32 v[34:35], v[34:35], v[16:17]
	v_pk_add_f32 v[36:37], v[36:37], v[18:19]
	v_pk_add_f32 v[38:39], v[38:39], v[20:21]
	v_pk_add_f32 v[40:41], v[40:41], v[22:23]
	s_mov_b64 exec, s[98:99]
	v_add_u32_e32 v58, -7, v150
	v_cmp_gt_u32_e32 vcc, s9, v58
	s_and_b64 exec, vcc, s[98:99]
	v_pk_add_f32 v[42:43], v[42:43], v[16:17]
	v_pk_add_f32 v[44:45], v[44:45], v[18:19]
	v_pk_add_f32 v[46:47], v[46:47], v[20:21]
	v_pk_add_f32 v[48:49], v[48:49], v[22:23]
	s_mov_b64 exec, s[98:99]
	v_add_u32_e32 v58, -6, v150
	v_cmp_gt_u32_e32 vcc, s9, v58
	s_and_b64 exec, vcc, s[98:99]
	v_pk_add_f32 v[50:51], v[50:51], v[16:17]
	v_pk_add_f32 v[52:53], v[52:53], v[18:19]
	v_pk_add_f32 v[54:55], v[54:55], v[20:21]
	v_pk_add_f32 v[56:57], v[56:57], v[22:23]
	s_mov_b64 exec, s[98:99]
	v_add_u32_e32 v58, -5, v150
	v_cmp_gt_u32_e32 vcc, s9, v58
	s_and_b64 exec, vcc, s[98:99]
	v_pk_add_f32 v[64:65], v[64:65], v[16:17]
	v_pk_add_f32 v[66:67], v[66:67], v[18:19]
	v_pk_add_f32 v[68:69], v[68:69], v[20:21]
	v_pk_add_f32 v[70:71], v[70:71], v[22:23]
	s_mov_b64 exec, s[98:99]
	s_waitcnt vmcnt(21)
	v_lshlrev_b32_e32 v16, 16, v116
	v_and_b32_e32 v17, 0xffff0000, v116
	v_lshlrev_b32_e32 v18, 16, v117
	v_and_b32_e32 v19, 0xffff0000, v117
	v_lshlrev_b32_e32 v20, 16, v118
	v_and_b32_e32 v21, 0xffff0000, v118
	v_lshlrev_b32_e32 v22, 16, v119
	v_and_b32_e32 v23, 0xffff0000, v119
	v_add_u32_e32 v58, -7, v150
	v_cmp_gt_u32_e32 vcc, s9, v58
	s_and_b64 exec, vcc, s[98:99]
	v_pk_add_f32 v[34:35], v[34:35], v[16:17]
	v_pk_add_f32 v[36:37], v[36:37], v[18:19]
	v_pk_add_f32 v[38:39], v[38:39], v[20:21]
	v_pk_add_f32 v[40:41], v[40:41], v[22:23]
	s_mov_b64 exec, s[98:99]
	v_add_u32_e32 v58, -6, v150
	v_cmp_gt_u32_e32 vcc, s9, v58
	s_and_b64 exec, vcc, s[98:99]
	v_pk_add_f32 v[42:43], v[42:43], v[16:17]
	v_pk_add_f32 v[44:45], v[44:45], v[18:19]
	v_pk_add_f32 v[46:47], v[46:47], v[20:21]
	v_pk_add_f32 v[48:49], v[48:49], v[22:23]
	s_mov_b64 exec, s[98:99]
	v_add_u32_e32 v58, -5, v150
	v_cmp_gt_u32_e32 vcc, s9, v58
	s_and_b64 exec, vcc, s[98:99]
	v_pk_add_f32 v[50:51], v[50:51], v[16:17]
	v_pk_add_f32 v[52:53], v[52:53], v[18:19]
	v_pk_add_f32 v[54:55], v[54:55], v[20:21]
	v_pk_add_f32 v[56:57], v[56:57], v[22:23]
	s_mov_b64 exec, s[98:99]
	v_add_u32_e32 v58, -4, v150
	v_cmp_gt_u32_e32 vcc, s9, v58
	s_and_b64 exec, vcc, s[98:99]
	v_pk_add_f32 v[64:65], v[64:65], v[16:17]
	v_pk_add_f32 v[66:67], v[66:67], v[18:19]
	v_pk_add_f32 v[68:69], v[68:69], v[20:21]
	v_pk_add_f32 v[70:71], v[70:71], v[22:23]
	s_mov_b64 exec, s[98:99]
	s_waitcnt vmcnt(20)
	v_lshlrev_b32_e32 v16, 16, v120
	v_and_b32_e32 v17, 0xffff0000, v120
	v_lshlrev_b32_e32 v18, 16, v121
	v_and_b32_e32 v19, 0xffff0000, v121
	v_lshlrev_b32_e32 v20, 16, v122
	v_and_b32_e32 v21, 0xffff0000, v122
	v_lshlrev_b32_e32 v22, 16, v123
	v_and_b32_e32 v23, 0xffff0000, v123
	v_add_u32_e32 v58, -6, v150
	v_cmp_gt_u32_e32 vcc, s9, v58
	s_and_b64 exec, vcc, s[98:99]
	v_pk_add_f32 v[34:35], v[34:35], v[16:17]
	v_pk_add_f32 v[36:37], v[36:37], v[18:19]
	v_pk_add_f32 v[38:39], v[38:39], v[20:21]
	v_pk_add_f32 v[40:41], v[40:41], v[22:23]
	s_mov_b64 exec, s[98:99]
	v_add_u32_e32 v58, -5, v150
	v_cmp_gt_u32_e32 vcc, s9, v58
	s_and_b64 exec, vcc, s[98:99]
	v_pk_add_f32 v[42:43], v[42:43], v[16:17]
	v_pk_add_f32 v[44:45], v[44:45], v[18:19]
	v_pk_add_f32 v[46:47], v[46:47], v[20:21]
	v_pk_add_f32 v[48:49], v[48:49], v[22:23]
	s_mov_b64 exec, s[98:99]
	v_add_u32_e32 v58, -4, v150
	v_cmp_gt_u32_e32 vcc, s9, v58
	s_and_b64 exec, vcc, s[98:99]
	v_pk_add_f32 v[50:51], v[50:51], v[16:17]
	v_pk_add_f32 v[52:53], v[52:53], v[18:19]
	v_pk_add_f32 v[54:55], v[54:55], v[20:21]
	v_pk_add_f32 v[56:57], v[56:57], v[22:23]
	s_mov_b64 exec, s[98:99]
	v_add_u32_e32 v58, -3, v150
	v_cmp_gt_u32_e32 vcc, s9, v58
	s_and_b64 exec, vcc, s[98:99]
	v_pk_add_f32 v[64:65], v[64:65], v[16:17]
	v_pk_add_f32 v[66:67], v[66:67], v[18:19]
	v_pk_add_f32 v[68:69], v[68:69], v[20:21]
	v_pk_add_f32 v[70:71], v[70:71], v[22:23]
	s_mov_b64 exec, s[98:99]
	s_waitcnt vmcnt(19)
	v_lshlrev_b32_e32 v16, 16, v124
	v_and_b32_e32 v17, 0xffff0000, v124
	v_lshlrev_b32_e32 v18, 16, v125
	v_and_b32_e32 v19, 0xffff0000, v125
	v_lshlrev_b32_e32 v20, 16, v126
	v_and_b32_e32 v21, 0xffff0000, v126
	v_lshlrev_b32_e32 v22, 16, v127
	v_and_b32_e32 v23, 0xffff0000, v127
	v_add_u32_e32 v58, -5, v150
	v_cmp_gt_u32_e32 vcc, s9, v58
	s_and_b64 exec, vcc, s[98:99]
	v_pk_add_f32 v[34:35], v[34:35], v[16:17]
	v_pk_add_f32 v[36:37], v[36:37], v[18:19]
	v_pk_add_f32 v[38:39], v[38:39], v[20:21]
	v_pk_add_f32 v[40:41], v[40:41], v[22:23]
	s_mov_b64 exec, s[98:99]
	v_add_u32_e32 v58, -4, v150
	v_cmp_gt_u32_e32 vcc, s9, v58
	s_and_b64 exec, vcc, s[98:99]
	v_pk_add_f32 v[42:43], v[42:43], v[16:17]
	v_pk_add_f32 v[44:45], v[44:45], v[18:19]
	v_pk_add_f32 v[46:47], v[46:47], v[20:21]
	v_pk_add_f32 v[48:49], v[48:49], v[22:23]
	s_mov_b64 exec, s[98:99]
	v_add_u32_e32 v58, -3, v150
	v_cmp_gt_u32_e32 vcc, s9, v58
	s_and_b64 exec, vcc, s[98:99]
	v_pk_add_f32 v[50:51], v[50:51], v[16:17]
	v_pk_add_f32 v[52:53], v[52:53], v[18:19]
	v_pk_add_f32 v[54:55], v[54:55], v[20:21]
	v_pk_add_f32 v[56:57], v[56:57], v[22:23]
	s_mov_b64 exec, s[98:99]
	v_add_u32_e32 v58, -2, v150
	v_cmp_gt_u32_e32 vcc, s9, v58
	s_and_b64 exec, vcc, s[98:99]
	v_pk_add_f32 v[64:65], v[64:65], v[16:17]
	v_pk_add_f32 v[66:67], v[66:67], v[18:19]
	v_pk_add_f32 v[68:69], v[68:69], v[20:21]
	v_pk_add_f32 v[70:71], v[70:71], v[22:23]
	s_mov_b64 exec, s[98:99]
	s_waitcnt vmcnt(18)
	v_lshlrev_b32_e32 v16, 16, v128
	v_and_b32_e32 v17, 0xffff0000, v128
	v_lshlrev_b32_e32 v18, 16, v129
	v_and_b32_e32 v19, 0xffff0000, v129
	v_lshlrev_b32_e32 v20, 16, v130
	v_and_b32_e32 v21, 0xffff0000, v130
	v_lshlrev_b32_e32 v22, 16, v131
	v_and_b32_e32 v23, 0xffff0000, v131
	v_add_u32_e32 v58, -4, v150
	v_cmp_gt_u32_e32 vcc, s9, v58
	s_and_b64 exec, vcc, s[98:99]
	v_pk_add_f32 v[34:35], v[34:35], v[16:17]
	v_pk_add_f32 v[36:37], v[36:37], v[18:19]
	v_pk_add_f32 v[38:39], v[38:39], v[20:21]
	v_pk_add_f32 v[40:41], v[40:41], v[22:23]
	s_mov_b64 exec, s[98:99]
	v_add_u32_e32 v58, -3, v150
	v_cmp_gt_u32_e32 vcc, s9, v58
	s_and_b64 exec, vcc, s[98:99]
	v_pk_add_f32 v[42:43], v[42:43], v[16:17]
	v_pk_add_f32 v[44:45], v[44:45], v[18:19]
	v_pk_add_f32 v[46:47], v[46:47], v[20:21]
	v_pk_add_f32 v[48:49], v[48:49], v[22:23]
	s_mov_b64 exec, s[98:99]
	v_add_u32_e32 v58, -2, v150
	v_cmp_gt_u32_e32 vcc, s9, v58
	s_and_b64 exec, vcc, s[98:99]
	v_pk_add_f32 v[50:51], v[50:51], v[16:17]
	v_pk_add_f32 v[52:53], v[52:53], v[18:19]
	v_pk_add_f32 v[54:55], v[54:55], v[20:21]
	v_pk_add_f32 v[56:57], v[56:57], v[22:23]
	s_mov_b64 exec, s[98:99]
	v_add_u32_e32 v58, -1, v150
	v_cmp_gt_u32_e32 vcc, s9, v58
	s_and_b64 exec, vcc, s[98:99]
	v_pk_add_f32 v[64:65], v[64:65], v[16:17]
	v_pk_add_f32 v[66:67], v[66:67], v[18:19]
	v_pk_add_f32 v[68:69], v[68:69], v[20:21]
	v_pk_add_f32 v[70:71], v[70:71], v[22:23]
	s_mov_b64 exec, s[98:99]
	s_waitcnt vmcnt(17)
	v_lshlrev_b32_e32 v16, 16, v132
	v_and_b32_e32 v17, 0xffff0000, v132
	v_lshlrev_b32_e32 v18, 16, v133
	v_and_b32_e32 v19, 0xffff0000, v133
	v_lshlrev_b32_e32 v20, 16, v134
	v_and_b32_e32 v21, 0xffff0000, v134
	v_lshlrev_b32_e32 v22, 16, v135
	v_and_b32_e32 v23, 0xffff0000, v135
	v_add_u32_e32 v58, -3, v150
	v_cmp_gt_u32_e32 vcc, s9, v58
	s_and_b64 exec, vcc, s[98:99]
	v_pk_add_f32 v[34:35], v[34:35], v[16:17]
	v_pk_add_f32 v[36:37], v[36:37], v[18:19]
	v_pk_add_f32 v[38:39], v[38:39], v[20:21]
	v_pk_add_f32 v[40:41], v[40:41], v[22:23]
	s_mov_b64 exec, s[98:99]
	v_add_u32_e32 v58, -2, v150
	v_cmp_gt_u32_e32 vcc, s9, v58
	s_and_b64 exec, vcc, s[98:99]
	v_pk_add_f32 v[42:43], v[42:43], v[16:17]
	v_pk_add_f32 v[44:45], v[44:45], v[18:19]
	v_pk_add_f32 v[46:47], v[46:47], v[20:21]
	v_pk_add_f32 v[48:49], v[48:49], v[22:23]
	s_mov_b64 exec, s[98:99]
	v_add_u32_e32 v58, -1, v150
	v_cmp_gt_u32_e32 vcc, s9, v58
	s_and_b64 exec, vcc, s[98:99]
	v_pk_add_f32 v[50:51], v[50:51], v[16:17]
	v_pk_add_f32 v[52:53], v[52:53], v[18:19]
	v_pk_add_f32 v[54:55], v[54:55], v[20:21]
	v_pk_add_f32 v[56:57], v[56:57], v[22:23]
	s_mov_b64 exec, s[98:99]
	v_add_u32_e32 v58, 0, v150
	v_cmp_gt_u32_e32 vcc, s9, v58
	s_and_b64 exec, vcc, s[98:99]
	v_pk_add_f32 v[64:65], v[64:65], v[16:17]
	v_pk_add_f32 v[66:67], v[66:67], v[18:19]
	v_pk_add_f32 v[68:69], v[68:69], v[20:21]
	v_pk_add_f32 v[70:71], v[70:71], v[22:23]
	s_mov_b64 exec, s[98:99]
	s_waitcnt vmcnt(16)
	v_lshlrev_b32_e32 v16, 16, v136
	v_and_b32_e32 v17, 0xffff0000, v136
	v_lshlrev_b32_e32 v18, 16, v137
	v_and_b32_e32 v19, 0xffff0000, v137
	v_lshlrev_b32_e32 v20, 16, v138
	v_and_b32_e32 v21, 0xffff0000, v138
	v_lshlrev_b32_e32 v22, 16, v139
	v_and_b32_e32 v23, 0xffff0000, v139
	v_add_u32_e32 v58, -2, v150
	v_cmp_gt_u32_e32 vcc, s9, v58
	s_and_b64 exec, vcc, s[98:99]
	v_pk_add_f32 v[34:35], v[34:35], v[16:17]
	v_pk_add_f32 v[36:37], v[36:37], v[18:19]
	v_pk_add_f32 v[38:39], v[38:39], v[20:21]
	v_pk_add_f32 v[40:41], v[40:41], v[22:23]
	s_mov_b64 exec, s[98:99]
	v_add_u32_e32 v58, -1, v150
	v_cmp_gt_u32_e32 vcc, s9, v58
	s_and_b64 exec, vcc, s[98:99]
	v_pk_add_f32 v[42:43], v[42:43], v[16:17]
	v_pk_add_f32 v[44:45], v[44:45], v[18:19]
	v_pk_add_f32 v[46:47], v[46:47], v[20:21]
	v_pk_add_f32 v[48:49], v[48:49], v[22:23]
	s_mov_b64 exec, s[98:99]
	v_add_u32_e32 v58, 0, v150
	v_cmp_gt_u32_e32 vcc, s9, v58
	s_and_b64 exec, vcc, s[98:99]
	v_pk_add_f32 v[50:51], v[50:51], v[16:17]
	v_pk_add_f32 v[52:53], v[52:53], v[18:19]
	v_pk_add_f32 v[54:55], v[54:55], v[20:21]
	v_pk_add_f32 v[56:57], v[56:57], v[22:23]
	s_mov_b64 exec, s[98:99]
	v_add_u32_e32 v58, 1, v150
	v_cmp_gt_u32_e32 vcc, s9, v58
	s_and_b64 exec, vcc, s[98:99]
	v_pk_add_f32 v[64:65], v[64:65], v[16:17]
	v_pk_add_f32 v[66:67], v[66:67], v[18:19]
	v_pk_add_f32 v[68:69], v[68:69], v[20:21]
	v_pk_add_f32 v[70:71], v[70:71], v[22:23]
	s_mov_b64 exec, s[98:99]
	s_waitcnt vmcnt(15)
	v_lshlrev_b32_e32 v16, 16, v176
	v_and_b32_e32 v17, 0xffff0000, v176
	v_lshlrev_b32_e32 v18, 16, v177
	v_and_b32_e32 v19, 0xffff0000, v177
	v_lshlrev_b32_e32 v20, 16, v178
	v_and_b32_e32 v21, 0xffff0000, v178
	v_lshlrev_b32_e32 v22, 16, v179
	v_and_b32_e32 v23, 0xffff0000, v179
	v_add_u32_e32 v58, -1, v150
	v_cmp_gt_u32_e32 vcc, s9, v58
	s_and_b64 exec, vcc, s[98:99]
	v_pk_add_f32 v[34:35], v[34:35], v[16:17]
	v_pk_add_f32 v[36:37], v[36:37], v[18:19]
	v_pk_add_f32 v[38:39], v[38:39], v[20:21]
	v_pk_add_f32 v[40:41], v[40:41], v[22:23]
	s_mov_b64 exec, s[98:99]
	v_add_u32_e32 v58, 0, v150
	v_cmp_gt_u32_e32 vcc, s9, v58
	s_and_b64 exec, vcc, s[98:99]
	v_pk_add_f32 v[42:43], v[42:43], v[16:17]
	v_pk_add_f32 v[44:45], v[44:45], v[18:19]
	v_pk_add_f32 v[46:47], v[46:47], v[20:21]
	v_pk_add_f32 v[48:49], v[48:49], v[22:23]
	s_mov_b64 exec, s[98:99]
	v_add_u32_e32 v58, 1, v150
	v_cmp_gt_u32_e32 vcc, s9, v58
	s_and_b64 exec, vcc, s[98:99]
	v_pk_add_f32 v[50:51], v[50:51], v[16:17]
	v_pk_add_f32 v[52:53], v[52:53], v[18:19]
	v_pk_add_f32 v[54:55], v[54:55], v[20:21]
	v_pk_add_f32 v[56:57], v[56:57], v[22:23]
	s_mov_b64 exec, s[98:99]
	v_add_u32_e32 v58, 2, v150
	v_cmp_gt_u32_e32 vcc, s9, v58
	s_and_b64 exec, vcc, s[98:99]
	v_pk_add_f32 v[64:65], v[64:65], v[16:17]
	v_pk_add_f32 v[66:67], v[66:67], v[18:19]
	v_pk_add_f32 v[68:69], v[68:69], v[20:21]
	v_pk_add_f32 v[70:71], v[70:71], v[22:23]
	s_mov_b64 exec, s[98:99]
	s_waitcnt vmcnt(14)
	v_lshlrev_b32_e32 v16, 16, v180
	v_and_b32_e32 v17, 0xffff0000, v180
	v_lshlrev_b32_e32 v18, 16, v181
	v_and_b32_e32 v19, 0xffff0000, v181
	v_lshlrev_b32_e32 v20, 16, v182
	v_and_b32_e32 v21, 0xffff0000, v182
	v_lshlrev_b32_e32 v22, 16, v183
	v_and_b32_e32 v23, 0xffff0000, v183
	v_add_u32_e32 v58, 0, v150
	v_cmp_gt_u32_e32 vcc, s9, v58
	s_and_b64 exec, vcc, s[98:99]
	v_pk_add_f32 v[34:35], v[34:35], v[16:17]
	v_pk_add_f32 v[36:37], v[36:37], v[18:19]
	v_pk_add_f32 v[38:39], v[38:39], v[20:21]
	v_pk_add_f32 v[40:41], v[40:41], v[22:23]
	s_mov_b64 exec, s[98:99]
	v_add_u32_e32 v58, 1, v150
	v_cmp_gt_u32_e32 vcc, s9, v58
	s_and_b64 exec, vcc, s[98:99]
	v_pk_add_f32 v[42:43], v[42:43], v[16:17]
	v_pk_add_f32 v[44:45], v[44:45], v[18:19]
	v_pk_add_f32 v[46:47], v[46:47], v[20:21]
	v_pk_add_f32 v[48:49], v[48:49], v[22:23]
	s_mov_b64 exec, s[98:99]
	v_add_u32_e32 v58, 2, v150
	v_cmp_gt_u32_e32 vcc, s9, v58
	s_and_b64 exec, vcc, s[98:99]
	v_pk_add_f32 v[50:51], v[50:51], v[16:17]
	v_pk_add_f32 v[52:53], v[52:53], v[18:19]
	v_pk_add_f32 v[54:55], v[54:55], v[20:21]
	v_pk_add_f32 v[56:57], v[56:57], v[22:23]
	s_mov_b64 exec, s[98:99]
	v_add_u32_e32 v58, 3, v150
	v_cmp_gt_u32_e32 vcc, s9, v58
	s_and_b64 exec, vcc, s[98:99]
	v_pk_add_f32 v[64:65], v[64:65], v[16:17]
	v_pk_add_f32 v[66:67], v[66:67], v[18:19]
	v_pk_add_f32 v[68:69], v[68:69], v[20:21]
	v_pk_add_f32 v[70:71], v[70:71], v[22:23]
	s_mov_b64 exec, s[98:99]
	v_add_co_u32_e32 v72, vcc, 0x3800, v14
	v_addc_co_u32_e32 v73, vcc, 0, v15, vcc
	global_load_dwordx4 v[80:83], v[72:73], off offset:16
	global_load_dwordx4 v[72:75], v[72:73], off
	v_add_co_u32_e32 v92, vcc, 0x3000, v14
	v_addc_co_u32_e32 v93, vcc, 0, v15, vcc
	global_load_dwordx4 v[96:99], v[92:93], off offset:16
	global_load_dwordx4 v[92:95], v[92:93], off
	v_add_co_u32_e32 v100, vcc, 0x2800, v14
	v_addc_co_u32_e32 v101, vcc, 0, v15, vcc
	global_load_dwordx4 v[104:107], v[100:101], off offset:16
	global_load_dwordx4 v[100:103], v[100:101], off
	v_add_co_u32_e32 v108, vcc, 0x2000, v14
	v_addc_co_u32_e32 v109, vcc, 0, v15, vcc
	global_load_dwordx4 v[112:115], v[108:109], off offset:16
	global_load_dwordx4 v[108:111], v[108:109], off
	v_add_co_u32_e32 v116, vcc, 0x1800, v14
	v_addc_co_u32_e32 v117, vcc, 0, v15, vcc
	global_load_dwordx4 v[120:123], v[116:117], off offset:16
	global_load_dwordx4 v[116:119], v[116:117], off
	v_add_co_u32_e32 v124, vcc, 0x1000, v14
	v_addc_co_u32_e32 v125, vcc, 0, v15, vcc
	global_load_dwordx4 v[128:131], v[124:125], off offset:16
	global_load_dwordx4 v[124:127], v[124:125], off
	v_add_co_u32_e32 v132, vcc, 0x800, v14
	v_addc_co_u32_e32 v133, vcc, 0, v15, vcc
	global_load_dwordx4 v[136:139], v[132:133], off offset:16
	global_load_dwordx4 v[132:135], v[132:133], off
	v_mov_b32_e32 v176, v14
	v_mov_b32_e32 v177, v15
	global_load_dwordx4 v[180:183], v[176:177], off offset:16
	global_load_dwordx4 v[176:179], v[176:177], off
	s_waitcnt vmcnt(28)
	v_add_u32_e32 v58, 1, v150
	v_cmp_gt_u32_e32 vcc, s9, v58
	s_and_b64 exec, vcc, s[98:99]
	v_pk_add_f32 v[34:35], v[34:35], v[184:185]
	v_pk_add_f32 v[36:37], v[36:37], v[186:187]
	v_pk_add_f32 v[38:39], v[38:39], v[188:189]
	v_pk_add_f32 v[40:41], v[40:41], v[190:191]
	s_mov_b64 exec, s[98:99]
	v_add_u32_e32 v58, 2, v150
	v_cmp_gt_u32_e32 vcc, s9, v58
	s_and_b64 exec, vcc, s[98:99]
	v_pk_add_f32 v[42:43], v[42:43], v[184:185]
	v_pk_add_f32 v[44:45], v[44:45], v[186:187]
	v_pk_add_f32 v[46:47], v[46:47], v[188:189]
	v_pk_add_f32 v[48:49], v[48:49], v[190:191]
	s_mov_b64 exec, s[98:99]
	v_add_u32_e32 v58, 3, v150
	v_cmp_gt_u32_e32 vcc, s9, v58
	s_and_b64 exec, vcc, s[98:99]
	v_pk_add_f32 v[50:51], v[50:51], v[184:185]
	v_pk_add_f32 v[52:53], v[52:53], v[186:187]
	v_pk_add_f32 v[54:55], v[54:55], v[188:189]
	v_pk_add_f32 v[56:57], v[56:57], v[190:191]
	s_mov_b64 exec, s[98:99]
	v_add_u32_e32 v58, 4, v150
	v_cmp_gt_u32_e32 vcc, s9, v58
	s_and_b64 exec, vcc, s[98:99]
	v_pk_add_f32 v[64:65], v[64:65], v[184:185]
	v_pk_add_f32 v[66:67], v[66:67], v[186:187]
	v_pk_add_f32 v[68:69], v[68:69], v[188:189]
	v_pk_add_f32 v[70:71], v[70:71], v[190:191]
	s_mov_b64 exec, s[98:99]
	s_cmp_lt_u32 s9, 4
	s_cbranch_scc1 ATS2_END
	s_waitcnt vmcnt(26)
	v_add_u32_e32 v58, 2, v150
	v_cmp_gt_u32_e32 vcc, s9, v58
	s_and_b64 exec, vcc, s[98:99]
	v_pk_add_f32 v[34:35], v[34:35], v[192:193]
	v_pk_add_f32 v[36:37], v[36:37], v[194:195]
	v_pk_add_f32 v[38:39], v[38:39], v[196:197]
	v_pk_add_f32 v[40:41], v[40:41], v[198:199]
	s_mov_b64 exec, s[98:99]
	v_add_u32_e32 v58, 3, v150
	v_cmp_gt_u32_e32 vcc, s9, v58
	s_and_b64 exec, vcc, s[98:99]
	v_pk_add_f32 v[42:43], v[42:43], v[192:193]
	v_pk_add_f32 v[44:45], v[44:45], v[194:195]
	v_pk_add_f32 v[46:47], v[46:47], v[196:197]
	v_pk_add_f32 v[48:49], v[48:49], v[198:199]
	s_mov_b64 exec, s[98:99]
	v_add_u32_e32 v58, 4, v150
	v_cmp_gt_u32_e32 vcc, s9, v58
	s_and_b64 exec, vcc, s[98:99]
	v_pk_add_f32 v[50:51], v[50:51], v[192:193]
	v_pk_add_f32 v[52:53], v[52:53], v[194:195]
	v_pk_add_f32 v[54:55], v[54:55], v[196:197]
	v_pk_add_f32 v[56:57], v[56:57], v[198:199]
	s_mov_b64 exec, s[98:99]
	v_add_u32_e32 v58, 5, v150
	v_cmp_gt_u32_e32 vcc, s9, v58
	s_and_b64 exec, vcc, s[98:99]
	v_pk_add_f32 v[64:65], v[64:65], v[192:193]
	v_pk_add_f32 v[66:67], v[66:67], v[194:195]
	v_pk_add_f32 v[68:69], v[68:69], v[196:197]
	v_pk_add_f32 v[70:71], v[70:71], v[198:199]
	s_mov_b64 exec, s[98:99]
	s_waitcnt vmcnt(24)
	v_add_u32_e32 v58, 3, v150
	v_cmp_gt_u32_e32 vcc, s9, v58
	s_and_b64 exec, vcc, s[98:99]
	v_pk_add_f32 v[34:35], v[34:35], v[200:201]
	v_pk_add_f32 v[36:37], v[36:37], v[202:203]
	v_pk_add_f32 v[38:39], v[38:39], v[218:219]
	v_pk_add_f32 v[40:41], v[40:41], v[220:221]
	s_mov_b64 exec, s[98:99]
	v_add_u32_e32 v58, 4, v150
	v_cmp_gt_u32_e32 vcc, s9, v58
	s_and_b64 exec, vcc, s[98:99]
	v_pk_add_f32 v[42:43], v[42:43], v[200:201]
	v_pk_add_f32 v[44:45], v[44:45], v[202:203]
	v_pk_add_f32 v[46:47], v[46:47], v[218:219]
	v_pk_add_f32 v[48:49], v[48:49], v[220:221]
	s_mov_b64 exec, s[98:99]
	v_add_u32_e32 v58, 5, v150
	v_cmp_gt_u32_e32 vcc, s9, v58
	s_and_b64 exec, vcc, s[98:99]
	v_pk_add_f32 v[50:51], v[50:51], v[200:201]
	v_pk_add_f32 v[52:53], v[52:53], v[202:203]
	v_pk_add_f32 v[54:55], v[54:55], v[218:219]
	v_pk_add_f32 v[56:57], v[56:57], v[220:221]
	s_mov_b64 exec, s[98:99]
	v_add_u32_e32 v58, 6, v150
	v_cmp_gt_u32_e32 vcc, s9, v58
	s_and_b64 exec, vcc, s[98:99]
	v_pk_add_f32 v[64:65], v[64:65], v[200:201]
	v_pk_add_f32 v[66:67], v[66:67], v[202:203]
	v_pk_add_f32 v[68:69], v[68:69], v[218:219]
	v_pk_add_f32 v[70:71], v[70:71], v[220:221]
	s_mov_b64 exec, s[98:99]
	s_cmp_lt_u32 s9, 5
	s_cbranch_scc1 ATS2_END
	s_waitcnt vmcnt(22)
	v_add_u32_e32 v58, 4, v150
	v_cmp_gt_u32_e32 vcc, s9, v58
	s_and_b64 exec, vcc, s[98:99]
	v_pk_add_f32 v[34:35], v[34:35], v[222:223]
	v_pk_add_f32 v[36:37], v[36:37], v[224:225]
	v_pk_add_f32 v[38:39], v[38:39], v[226:227]
	v_pk_add_f32 v[40:41], v[40:41], v[228:229]
	s_mov_b64 exec, s[98:99]
	v_add_u32_e32 v58, 5, v150
	v_cmp_gt_u32_e32 vcc, s9, v58
	s_and_b64 exec, vcc, s[98:99]
	v_pk_add_f32 v[42:43], v[42:43], v[222:223]
	v_pk_add_f32 v[44:45], v[44:45], v[224:225]
	v_pk_add_f32 v[46:47], v[46:47], v[226:227]
	v_pk_add_f32 v[48:49], v[48:49], v[228:229]
	s_mov_b64 exec, s[98:99]
	v_add_u32_e32 v58, 6, v150
	v_cmp_gt_u32_e32 vcc, s9, v58
	s_and_b64 exec, vcc, s[98:99]
	v_pk_add_f32 v[50:51], v[50:51], v[222:223]
	v_pk_add_f32 v[52:53], v[52:53], v[224:225]
	v_pk_add_f32 v[54:55], v[54:55], v[226:227]
	v_pk_add_f32 v[56:57], v[56:57], v[228:229]
	s_mov_b64 exec, s[98:99]
	v_add_u32_e32 v58, 7, v150
	v_cmp_gt_u32_e32 vcc, s9, v58
	s_and_b64 exec, vcc, s[98:99]
	v_pk_add_f32 v[64:65], v[64:65], v[222:223]
	v_pk_add_f32 v[66:67], v[66:67], v[224:225]
	v_pk_add_f32 v[68:69], v[68:69], v[226:227]
	v_pk_add_f32 v[70:71], v[70:71], v[228:229]
	s_mov_b64 exec, s[98:99]
	s_waitcnt vmcnt(20)
	v_add_u32_e32 v58, 5, v150
	v_cmp_gt_u32_e32 vcc, s9, v58
	s_and_b64 exec, vcc, s[98:99]
	v_pk_add_f32 v[34:35], v[34:35], v[230:231]
	v_pk_add_f32 v[36:37], v[36:37], v[232:233]
	v_pk_add_f32 v[38:39], v[38:39], v[236:237]
	v_pk_add_f32 v[40:41], v[40:41], v[238:239]
	s_mov_b64 exec, s[98:99]
	v_add_u32_e32 v58, 6, v150
	v_cmp_gt_u32_e32 vcc, s9, v58
	s_and_b64 exec, vcc, s[98:99]
	v_pk_add_f32 v[42:43], v[42:43], v[230:231]
	v_pk_add_f32 v[44:45], v[44:45], v[232:233]
	v_pk_add_f32 v[46:47], v[46:47], v[236:237]
	v_pk_add_f32 v[48:49], v[48:49], v[238:239]
	s_mov_b64 exec, s[98:99]
	v_add_u32_e32 v58, 7, v150
	v_cmp_gt_u32_e32 vcc, s9, v58
	s_and_b64 exec, vcc, s[98:99]
	v_pk_add_f32 v[50:51], v[50:51], v[230:231]
	v_pk_add_f32 v[52:53], v[52:53], v[232:233]
	v_pk_add_f32 v[54:55], v[54:55], v[236:237]
	v_pk_add_f32 v[56:57], v[56:57], v[238:239]
	s_mov_b64 exec, s[98:99]
	v_add_u32_e32 v58, 8, v150
	v_cmp_gt_u32_e32 vcc, s9, v58
	s_and_b64 exec, vcc, s[98:99]
	v_pk_add_f32 v[64:65], v[64:65], v[230:231]
	v_pk_add_f32 v[66:67], v[66:67], v[232:233]
	v_pk_add_f32 v[68:69], v[68:69], v[236:237]
	v_pk_add_f32 v[70:71], v[70:71], v[238:239]
	s_mov_b64 exec, s[98:99]
	s_waitcnt vmcnt(18)
	v_add_u32_e32 v58, 6, v150
	v_cmp_gt_u32_e32 vcc, s9, v58
	s_and_b64 exec, vcc, s[98:99]
	v_pk_add_f32 v[34:35], v[34:35], v[240:241]
	v_pk_add_f32 v[36:37], v[36:37], v[242:243]
	v_pk_add_f32 v[38:39], v[38:39], v[244:245]
	v_pk_add_f32 v[40:41], v[40:41], v[246:247]
	s_mov_b64 exec, s[98:99]
	v_add_u32_e32 v58, 7, v150
	v_cmp_gt_u32_e32 vcc, s9, v58
	s_and_b64 exec, vcc, s[98:99]
	v_pk_add_f32 v[42:43], v[42:43], v[240:241]
	v_pk_add_f32 v[44:45], v[44:45], v[242:243]
	v_pk_add_f32 v[46:47], v[46:47], v[244:245]
	v_pk_add_f32 v[48:49], v[48:49], v[246:247]
	s_mov_b64 exec, s[98:99]
	v_add_u32_e32 v58, 8, v150
	v_cmp_gt_u32_e32 vcc, s9, v58
	s_and_b64 exec, vcc, s[98:99]
	v_pk_add_f32 v[50:51], v[50:51], v[240:241]
	v_pk_add_f32 v[52:53], v[52:53], v[242:243]
	v_pk_add_f32 v[54:55], v[54:55], v[244:245]
	v_pk_add_f32 v[56:57], v[56:57], v[246:247]
	s_mov_b64 exec, s[98:99]
	v_add_u32_e32 v58, 9, v150
	v_cmp_gt_u32_e32 vcc, s9, v58
	s_and_b64 exec, vcc, s[98:99]
	v_pk_add_f32 v[64:65], v[64:65], v[240:241]
	v_pk_add_f32 v[66:67], v[66:67], v[242:243]
	v_pk_add_f32 v[68:69], v[68:69], v[244:245]
	v_pk_add_f32 v[70:71], v[70:71], v[246:247]
	s_mov_b64 exec, s[98:99]
	s_waitcnt vmcnt(16)
	v_add_u32_e32 v58, 7, v150
	v_cmp_gt_u32_e32 vcc, s9, v58
	s_and_b64 exec, vcc, s[98:99]
	v_pk_add_f32 v[34:35], v[34:35], v[248:249]
	v_pk_add_f32 v[36:37], v[36:37], v[250:251]
	v_pk_add_f32 v[38:39], v[38:39], v[252:253]
	v_pk_add_f32 v[40:41], v[40:41], v[254:255]
	s_mov_b64 exec, s[98:99]
	v_add_u32_e32 v58, 8, v150
	v_cmp_gt_u32_e32 vcc, s9, v58
	s_and_b64 exec, vcc, s[98:99]
	v_pk_add_f32 v[42:43], v[42:43], v[248:249]
	v_pk_add_f32 v[44:45], v[44:45], v[250:251]
	v_pk_add_f32 v[46:47], v[46:47], v[252:253]
	v_pk_add_f32 v[48:49], v[48:49], v[254:255]
	s_mov_b64 exec, s[98:99]
	v_add_u32_e32 v58, 9, v150
	v_cmp_gt_u32_e32 vcc, s9, v58
	s_and_b64 exec, vcc, s[98:99]
	v_pk_add_f32 v[50:51], v[50:51], v[248:249]
	v_pk_add_f32 v[52:53], v[52:53], v[250:251]
	v_pk_add_f32 v[54:55], v[54:55], v[252:253]
	v_pk_add_f32 v[56:57], v[56:57], v[254:255]
	s_mov_b64 exec, s[98:99]
	v_add_u32_e32 v58, 10, v150
	v_cmp_gt_u32_e32 vcc, s9, v58
	s_and_b64 exec, vcc, s[98:99]
	v_pk_add_f32 v[64:65], v[64:65], v[248:249]
	v_pk_add_f32 v[66:67], v[66:67], v[250:251]
	v_pk_add_f32 v[68:69], v[68:69], v[252:253]
	v_pk_add_f32 v[70:71], v[70:71], v[254:255]
	s_mov_b64 exec, s[98:99]
	s_cmp_lt_u32 s9, 9
	s_cbranch_scc1 ATS2_END
	s_waitcnt vmcnt(14)
	v_add_u32_e32 v58, 8, v150
	v_cmp_gt_u32_e32 vcc, s9, v58
	s_and_b64 exec, vcc, s[98:99]
	v_pk_add_f32 v[34:35], v[34:35], v[72:73]
	v_pk_add_f32 v[36:37], v[36:37], v[74:75]
	v_pk_add_f32 v[38:39], v[38:39], v[80:81]
	v_pk_add_f32 v[40:41], v[40:41], v[82:83]
	s_mov_b64 exec, s[98:99]
	v_add_u32_e32 v58, 9, v150
	v_cmp_gt_u32_e32 vcc, s9, v58
	s_and_b64 exec, vcc, s[98:99]
	v_pk_add_f32 v[42:43], v[42:43], v[72:73]
	v_pk_add_f32 v[44:45], v[44:45], v[74:75]
	v_pk_add_f32 v[46:47], v[46:47], v[80:81]
	v_pk_add_f32 v[48:49], v[48:49], v[82:83]
	s_mov_b64 exec, s[98:99]
	v_add_u32_e32 v58, 10, v150
	v_cmp_gt_u32_e32 vcc, s9, v58
	s_and_b64 exec, vcc, s[98:99]
	v_pk_add_f32 v[50:51], v[50:51], v[72:73]
	v_pk_add_f32 v[52:53], v[52:53], v[74:75]
	v_pk_add_f32 v[54:55], v[54:55], v[80:81]
	v_pk_add_f32 v[56:57], v[56:57], v[82:83]
	s_mov_b64 exec, s[98:99]
	v_add_u32_e32 v58, 11, v150
	v_cmp_gt_u32_e32 vcc, s9, v58
	s_and_b64 exec, vcc, s[98:99]
	v_pk_add_f32 v[64:65], v[64:65], v[72:73]
	v_pk_add_f32 v[66:67], v[66:67], v[74:75]
	v_pk_add_f32 v[68:69], v[68:69], v[80:81]
	v_pk_add_f32 v[70:71], v[70:71], v[82:83]
	s_mov_b64 exec, s[98:99]
	s_waitcnt vmcnt(12)
	v_add_u32_e32 v58, 9, v150
	v_cmp_gt_u32_e32 vcc, s9, v58
	s_and_b64 exec, vcc, s[98:99]
	v_pk_add_f32 v[34:35], v[34:35], v[92:93]
	v_pk_add_f32 v[36:37], v[36:37], v[94:95]
	v_pk_add_f32 v[38:39], v[38:39], v[96:97]
	v_pk_add_f32 v[40:41], v[40:41], v[98:99]
	s_mov_b64 exec, s[98:99]
	v_add_u32_e32 v58, 10, v150
	v_cmp_gt_u32_e32 vcc, s9, v58
	s_and_b64 exec, vcc, s[98:99]
	v_pk_add_f32 v[42:43], v[42:43], v[92:93]
	v_pk_add_f32 v[44:45], v[44:45], v[94:95]
	v_pk_add_f32 v[46:47], v[46:47], v[96:97]
	v_pk_add_f32 v[48:49], v[48:49], v[98:99]
	s_mov_b64 exec, s[98:99]
	v_add_u32_e32 v58, 11, v150
	v_cmp_gt_u32_e32 vcc, s9, v58
	s_and_b64 exec, vcc, s[98:99]
	v_pk_add_f32 v[50:51], v[50:51], v[92:93]
	v_pk_add_f32 v[52:53], v[52:53], v[94:95]
	v_pk_add_f32 v[54:55], v[54:55], v[96:97]
	v_pk_add_f32 v[56:57], v[56:57], v[98:99]
	s_mov_b64 exec, s[98:99]
	v_add_u32_e32 v58, 12, v150
	v_cmp_gt_u32_e32 vcc, s9, v58
	s_and_b64 exec, vcc, s[98:99]
	v_pk_add_f32 v[64:65], v[64:65], v[92:93]
	v_pk_add_f32 v[66:67], v[66:67], v[94:95]
	v_pk_add_f32 v[68:69], v[68:69], v[96:97]
	v_pk_add_f32 v[70:71], v[70:71], v[98:99]
	s_mov_b64 exec, s[98:99]
	s_waitcnt vmcnt(10)
	v_add_u32_e32 v58, 10, v150
	v_cmp_gt_u32_e32 vcc, s9, v58
	s_and_b64 exec, vcc, s[98:99]
	v_pk_add_f32 v[34:35], v[34:35], v[100:101]
	v_pk_add_f32 v[36:37], v[36:37], v[102:103]
	v_pk_add_f32 v[38:39], v[38:39], v[104:105]
	v_pk_add_f32 v[40:41], v[40:41], v[106:107]
	s_mov_b64 exec, s[98:99]
	v_add_u32_e32 v58, 11, v150
	v_cmp_gt_u32_e32 vcc, s9, v58
	s_and_b64 exec, vcc, s[98:99]
	v_pk_add_f32 v[42:43], v[42:43], v[100:101]
	v_pk_add_f32 v[44:45], v[44:45], v[102:103]
	v_pk_add_f32 v[46:47], v[46:47], v[104:105]
	v_pk_add_f32 v[48:49], v[48:49], v[106:107]
	s_mov_b64 exec, s[98:99]
	v_add_u32_e32 v58, 12, v150
	v_cmp_gt_u32_e32 vcc, s9, v58
	s_and_b64 exec, vcc, s[98:99]
	v_pk_add_f32 v[50:51], v[50:51], v[100:101]
	v_pk_add_f32 v[52:53], v[52:53], v[102:103]
	v_pk_add_f32 v[54:55], v[54:55], v[104:105]
	v_pk_add_f32 v[56:57], v[56:57], v[106:107]
	s_mov_b64 exec, s[98:99]
	v_add_u32_e32 v58, 13, v150
	v_cmp_gt_u32_e32 vcc, s9, v58
	s_and_b64 exec, vcc, s[98:99]
	v_pk_add_f32 v[64:65], v[64:65], v[100:101]
	v_pk_add_f32 v[66:67], v[66:67], v[102:103]
	v_pk_add_f32 v[68:69], v[68:69], v[104:105]
	v_pk_add_f32 v[70:71], v[70:71], v[106:107]
	s_mov_b64 exec, s[98:99]
	s_waitcnt vmcnt(8)
	v_add_u32_e32 v58, 11, v150
	v_cmp_gt_u32_e32 vcc, s9, v58
	s_and_b64 exec, vcc, s[98:99]
	v_pk_add_f32 v[34:35], v[34:35], v[108:109]
	v_pk_add_f32 v[36:37], v[36:37], v[110:111]
	v_pk_add_f32 v[38:39], v[38:39], v[112:113]
	v_pk_add_f32 v[40:41], v[40:41], v[114:115]
	s_mov_b64 exec, s[98:99]
	v_add_u32_e32 v58, 12, v150
	v_cmp_gt_u32_e32 vcc, s9, v58
	s_and_b64 exec, vcc, s[98:99]
	v_pk_add_f32 v[42:43], v[42:43], v[108:109]
	v_pk_add_f32 v[44:45], v[44:45], v[110:111]
	v_pk_add_f32 v[46:47], v[46:47], v[112:113]
	v_pk_add_f32 v[48:49], v[48:49], v[114:115]
	s_mov_b64 exec, s[98:99]
	v_add_u32_e32 v58, 13, v150
	v_cmp_gt_u32_e32 vcc, s9, v58
	s_and_b64 exec, vcc, s[98:99]
	v_pk_add_f32 v[50:51], v[50:51], v[108:109]
	v_pk_add_f32 v[52:53], v[52:53], v[110:111]
	v_pk_add_f32 v[54:55], v[54:55], v[112:113]
	v_pk_add_f32 v[56:57], v[56:57], v[114:115]
	s_mov_b64 exec, s[98:99]
	v_add_u32_e32 v58, 14, v150
	v_cmp_gt_u32_e32 vcc, s9, v58
	s_and_b64 exec, vcc, s[98:99]
	v_pk_add_f32 v[64:65], v[64:65], v[108:109]
	v_pk_add_f32 v[66:67], v[66:67], v[110:111]
	v_pk_add_f32 v[68:69], v[68:69], v[112:113]
	v_pk_add_f32 v[70:71], v[70:71], v[114:115]
	s_mov_b64 exec, s[98:99]
	s_waitcnt vmcnt(6)
	v_add_u32_e32 v58, 12, v150
	v_cmp_gt_u32_e32 vcc, s9, v58
	s_and_b64 exec, vcc, s[98:99]
	v_pk_add_f32 v[34:35], v[34:35], v[116:117]
	v_pk_add_f32 v[36:37], v[36:37], v[118:119]
	v_pk_add_f32 v[38:39], v[38:39], v[120:121]
	v_pk_add_f32 v[40:41], v[40:41], v[122:123]
	s_mov_b64 exec, s[98:99]
	v_add_u32_e32 v58, 13, v150
	v_cmp_gt_u32_e32 vcc, s9, v58
	s_and_b64 exec, vcc, s[98:99]
	v_pk_add_f32 v[42:43], v[42:43], v[116:117]
	v_pk_add_f32 v[44:45], v[44:45], v[118:119]
	v_pk_add_f32 v[46:47], v[46:47], v[120:121]
	v_pk_add_f32 v[48:49], v[48:49], v[122:123]
	s_mov_b64 exec, s[98:99]
	v_add_u32_e32 v58, 14, v150
	v_cmp_gt_u32_e32 vcc, s9, v58
	s_and_b64 exec, vcc, s[98:99]
	v_pk_add_f32 v[50:51], v[50:51], v[116:117]
	v_pk_add_f32 v[52:53], v[52:53], v[118:119]
	v_pk_add_f32 v[54:55], v[54:55], v[120:121]
	v_pk_add_f32 v[56:57], v[56:57], v[122:123]
	s_mov_b64 exec, s[98:99]
	v_add_u32_e32 v58, 15, v150
	v_cmp_gt_u32_e32 vcc, s9, v58
	s_and_b64 exec, vcc, s[98:99]
	v_pk_add_f32 v[64:65], v[64:65], v[116:117]
	v_pk_add_f32 v[66:67], v[66:67], v[118:119]
	v_pk_add_f32 v[68:69], v[68:69], v[120:121]
	v_pk_add_f32 v[70:71], v[70:71], v[122:123]
	s_mov_b64 exec, s[98:99]
	s_waitcnt vmcnt(4)
	v_add_u32_e32 v58, 13, v150
	v_cmp_gt_u32_e32 vcc, s9, v58
	s_and_b64 exec, vcc, s[98:99]
	v_pk_add_f32 v[34:35], v[34:35], v[124:125]
	v_pk_add_f32 v[36:37], v[36:37], v[126:127]
	v_pk_add_f32 v[38:39], v[38:39], v[128:129]
	v_pk_add_f32 v[40:41], v[40:41], v[130:131]
	s_mov_b64 exec, s[98:99]
	v_add_u32_e32 v58, 14, v150
	v_cmp_gt_u32_e32 vcc, s9, v58
	s_and_b64 exec, vcc, s[98:99]
	v_pk_add_f32 v[42:43], v[42:43], v[124:125]
	v_pk_add_f32 v[44:45], v[44:45], v[126:127]
	v_pk_add_f32 v[46:47], v[46:47], v[128:129]
	v_pk_add_f32 v[48:49], v[48:49], v[130:131]
	s_mov_b64 exec, s[98:99]
	v_add_u32_e32 v58, 15, v150
	v_cmp_gt_u32_e32 vcc, s9, v58
	s_and_b64 exec, vcc, s[98:99]
	v_pk_add_f32 v[50:51], v[50:51], v[124:125]
	v_pk_add_f32 v[52:53], v[52:53], v[126:127]
	v_pk_add_f32 v[54:55], v[54:55], v[128:129]
	v_pk_add_f32 v[56:57], v[56:57], v[130:131]
	s_mov_b64 exec, s[98:99]
	s_waitcnt vmcnt(2)
	v_add_u32_e32 v58, 14, v150
	v_cmp_gt_u32_e32 vcc, s9, v58
	s_and_b64 exec, vcc, s[98:99]
	v_pk_add_f32 v[34:35], v[34:35], v[132:133]
	v_pk_add_f32 v[36:37], v[36:37], v[134:135]
	v_pk_add_f32 v[38:39], v[38:39], v[136:137]
	v_pk_add_f32 v[40:41], v[40:41], v[138:139]
	s_mov_b64 exec, s[98:99]
	v_add_u32_e32 v58, 15, v150
	v_cmp_gt_u32_e32 vcc, s9, v58
	s_and_b64 exec, vcc, s[98:99]
	v_pk_add_f32 v[42:43], v[42:43], v[132:133]
	v_pk_add_f32 v[44:45], v[44:45], v[134:135]
	v_pk_add_f32 v[46:47], v[46:47], v[136:137]
	v_pk_add_f32 v[48:49], v[48:49], v[138:139]
	s_mov_b64 exec, s[98:99]
	s_waitcnt vmcnt(0)
	v_add_u32_e32 v58, 15, v150
	v_cmp_gt_u32_e32 vcc, s9, v58
	s_and_b64 exec, vcc, s[98:99]
	v_pk_add_f32 v[34:35], v[34:35], v[176:177]
	v_pk_add_f32 v[36:37], v[36:37], v[178:179]
	v_pk_add_f32 v[38:39], v[38:39], v[180:181]
	v_pk_add_f32 v[40:41], v[40:41], v[182:183]
	s_mov_b64 exec, s[98:99]
ATS2_END:
	s_waitcnt vmcnt(0)
	v_ffbl_b32_e32 v58, s9
	v_lshlrev_b32_e32 v58, 23, v58
	v_sub_u32_e32 v58, 0x3f800000, v58
	v_lshlrev_b32_e32 v72, 16, v0
	v_and_b32_e32 v73, 0xffff0000, v0
	v_lshlrev_b32_e32 v74, 16, v1
	v_and_b32_e32 v75, 0xffff0000, v1
	v_lshlrev_b32_e32 v80, 16, v2
	v_and_b32_e32 v81, 0xffff0000, v2
	v_lshlrev_b32_e32 v82, 16, v3
	v_and_b32_e32 v83, 0xffff0000, v3
	v_fma_f32 v72, v58, v34, -v72
	v_fma_f32 v73, v58, v35, -v73
	v_fma_f32 v74, v58, v36, -v74
	v_fma_f32 v75, v58, v37, -v75
	v_fma_f32 v80, v58, v38, -v80
	v_fma_f32 v81, v58, v39, -v81
	v_fma_f32 v82, v58, v40, -v82
	v_fma_f32 v83, v58, v41, -v83
	v_cvt_pk_bf16_f32 v12, v72, v73
	v_cvt_pk_bf16_f32 v13, v74, v75
	v_cvt_pk_bf16_f32 v14, v80, v81
	v_cvt_pk_bf16_f32 v15, v82, v83
	v_lshlrev_b32_e32 v72, 16, v4
	v_and_b32_e32 v73, 0xffff0000, v4
	v_lshlrev_b32_e32 v74, 16, v5
	v_and_b32_e32 v75, 0xffff0000, v5
	v_lshlrev_b32_e32 v80, 16, v6
	v_and_b32_e32 v81, 0xffff0000, v6
	v_lshlrev_b32_e32 v82, 16, v7
	v_and_b32_e32 v83, 0xffff0000, v7
	v_fma_f32 v72, v58, v42, -v72
	v_fma_f32 v73, v58, v43, -v73
	v_fma_f32 v74, v58, v44, -v74
	v_fma_f32 v75, v58, v45, -v75
	v_fma_f32 v80, v58, v46, -v80
	v_fma_f32 v81, v58, v47, -v81
	v_fma_f32 v82, v58, v48, -v82
	v_fma_f32 v83, v58, v49, -v83
	v_cvt_pk_bf16_f32 v16, v72, v73
	v_cvt_pk_bf16_f32 v17, v74, v75
	v_cvt_pk_bf16_f32 v18, v80, v81
	v_cvt_pk_bf16_f32 v19, v82, v83
	v_lshlrev_b32_e32 v72, 16, v8
	v_and_b32_e32 v73, 0xffff0000, v8
	v_lshlrev_b32_e32 v74, 16, v9
	v_and_b32_e32 v75, 0xffff0000, v9
	v_lshlrev_b32_e32 v80, 16, v10
	v_and_b32_e32 v81, 0xffff0000, v10
	v_lshlrev_b32_e32 v82, 16, v11
	v_and_b32_e32 v83, 0xffff0000, v11
	v_fma_f32 v72, v58, v50, -v72
	v_fma_f32 v73, v58, v51, -v73
	v_fma_f32 v74, v58, v52, -v74
	v_fma_f32 v75, v58, v53, -v75
	v_fma_f32 v80, v58, v54, -v80
	v_fma_f32 v81, v58, v55, -v81
	v_fma_f32 v82, v58, v56, -v82
	v_fma_f32 v83, v58, v57, -v83
	v_cvt_pk_bf16_f32 v20, v72, v73
	v_cvt_pk_bf16_f32 v21, v74, v75
	v_cvt_pk_bf16_f32 v22, v80, v81
	v_cvt_pk_bf16_f32 v23, v82, v83
	v_lshlrev_b32_e32 v72, 16, v24
	v_and_b32_e32 v73, 0xffff0000, v24
	v_lshlrev_b32_e32 v74, 16, v25
	v_and_b32_e32 v75, 0xffff0000, v25
	v_lshlrev_b32_e32 v80, 16, v26
	v_and_b32_e32 v81, 0xffff0000, v26
	v_lshlrev_b32_e32 v82, 16, v27
	v_and_b32_e32 v83, 0xffff0000, v27
	v_fma_f32 v72, v58, v64, -v72
	v_fma_f32 v73, v58, v65, -v73
	v_fma_f32 v74, v58, v66, -v74
	v_fma_f32 v75, v58, v67, -v75
	v_fma_f32 v80, v58, v68, -v80
	v_fma_f32 v81, v58, v69, -v81
	v_fma_f32 v82, v58, v70, -v82
	v_fma_f32 v83, v58, v71, -v83
	v_cvt_pk_bf16_f32 v28, v72, v73
	v_cvt_pk_bf16_f32 v29, v74, v75
	v_cvt_pk_bf16_f32 v30, v80, v81
	v_cvt_pk_bf16_f32 v31, v82, v83
	s_branch .LBB0_1718

.LBB0_2401:
	s_and_b64 vcc, exec, s[0:1]
	s_cbranch_vccz .LBB0_2427
	s_lshl_b64 s[0:1], s[28:29], 2
	s_add_u32 s0, s56, s0
	s_addc_u32 s1, s57, s1
	v_mov_b32_e32 v4, 0
	s_lshl_b32 s12, 2, s26
	v_lshl_add_u64 v[28:29], v[32:33], 1, s[52:53]
	v_lshl_add_u64 v[30:31], v[32:33], 2, s[0:1]
	v_add_u32_e32 v8, s41, v150
	s_mov_b64 s[98:99], exec
	v_mov_b32_e32 v12, v28
	v_mov_b32_e32 v13, v29
	v_mov_b32_e32 v14, v30
	v_mov_b32_e32 v15, v31
	v_mov_b32_e32 v59, s41
	v_add3_u32 v58, v150, v59, 0
	v_mad_u64_u32 v[0:1], vcc, v58, s31, v[12:13]
	global_load_dwordx4 v[0:3], v[0:1], off
	v_add3_u32 v58, v150, v59, 1
	v_mad_u64_u32 v[4:5], vcc, v58, s31, v[12:13]
	global_load_dwordx4 v[4:7], v[4:5], off
	v_add3_u32 v58, v150, v59, 2
	v_mad_u64_u32 v[8:9], vcc, v58, s31, v[12:13]
	global_load_dwordx4 v[8:11], v[8:9], off
	v_add3_u32 v58, v150, v59, 3
	v_mad_u64_u32 v[24:25], vcc, v58, s31, v[12:13]
	global_load_dwordx4 v[24:27], v[24:25], off
	v_add_u32_e32 v58, 15, v59
	v_mad_u64_u32 v[72:73], vcc, v58, s31, v[12:13]
	global_load_dwordx4 v[72:75], v[72:73], off
	v_add_u32_e32 v58, 14, v59
	v_mad_u64_u32 v[80:81], vcc, v58, s31, v[12:13]
	global_load_dwordx4 v[80:83], v[80:81], off
	v_add_u32_e32 v58, 13, v59
	v_mad_u64_u32 v[92:93], vcc, v58, s31, v[12:13]
	global_load_dwordx4 v[92:95], v[92:93], off
	v_add_u32_e32 v58, 12, v59
	v_mad_u64_u32 v[96:97], vcc, v58, s31, v[12:13]
	global_load_dwordx4 v[96:99], v[96:97], off
	v_add_u32_e32 v58, 11, v59
	v_mad_u64_u32 v[100:101], vcc, v58, s31, v[12:13]
	global_load_dwordx4 v[100:103], v[100:101], off
	v_add_u32_e32 v58, 10, v59
	v_mad_u64_u32 v[104:105], vcc, v58, s31, v[12:13]
	global_load_dwordx4 v[104:107], v[104:105], off
	v_add_u32_e32 v58, 9, v59
	v_mad_u64_u32 v[108:109], vcc, v58, s31, v[12:13]
	global_load_dwordx4 v[108:111], v[108:109], off
	v_add_u32_e32 v58, 8, v59
	v_mad_u64_u32 v[112:113], vcc, v58, s31, v[12:13]
	global_load_dwordx4 v[112:115], v[112:113], off
	v_add_u32_e32 v58, 7, v59
	v_mad_u64_u32 v[116:117], vcc, v58, s31, v[12:13]
	global_load_dwordx4 v[116:119], v[116:117], off
	v_add_u32_e32 v58, 6, v59
	v_mad_u64_u32 v[120:121], vcc, v58, s31, v[12:13]
	global_load_dwordx4 v[120:123], v[120:121], off
	v_add_u32_e32 v58, 5, v59
	v_mad_u64_u32 v[124:125], vcc, v58, s31, v[12:13]
	global_load_dwordx4 v[124:127], v[124:125], off
	v_add_u32_e32 v58, 4, v59
	v_mad_u64_u32 v[128:129], vcc, v58, s31, v[12:13]
	global_load_dwordx4 v[128:131], v[128:129], off
	v_add_u32_e32 v58, 3, v59
	v_mad_u64_u32 v[132:133], vcc, v58, s31, v[12:13]
	global_load_dwordx4 v[132:135], v[132:133], off
	v_add_u32_e32 v58, 2, v59
	v_mad_u64_u32 v[136:137], vcc, v58, s31, v[12:13]
	global_load_dwordx4 v[136:139], v[136:137], off
	v_add_u32_e32 v58, 1, v59
	v_mad_u64_u32 v[176:177], vcc, v58, s31, v[12:13]
	global_load_dwordx4 v[176:179], v[176:177], off
	v_add_u32_e32 v58, 0, v59
	v_mad_u64_u32 v[180:181], vcc, v58, s31, v[12:13]
	global_load_dwordx4 v[180:183], v[180:181], off
	v_add_co_u32_e32 v184, vcc, 0x7000, v14
	v_addc_co_u32_e32 v185, vcc, 0, v15, vcc
	global_load_dwordx4 v[188:191], v[184:185], off offset:16
	global_load_dwordx4 v[184:187], v[184:185], off
	v_add_co_u32_e32 v192, vcc, 0x6800, v14
	v_addc_co_u32_e32 v193, vcc, 0, v15, vcc
	global_load_dwordx4 v[196:199], v[192:193], off offset:16
	global_load_dwordx4 v[192:195], v[192:193], off
	v_add_co_u32_e32 v200, vcc, 0x6000, v14
	v_addc_co_u32_e32 v201, vcc, 0, v15, vcc
	global_load_dwordx4 v[218:221], v[200:201], off offset:16
	global_load_dwordx4 v[200:203], v[200:201], off
	v_add_co_u32_e32 v222, vcc, 0x5800, v14
	v_addc_co_u32_e32 v223, vcc, 0, v15, vcc
	global_load_dwordx4 v[226:229], v[222:223], off offset:16
	global_load_dwordx4 v[222:225], v[222:223], off
	v_add_co_u32_e32 v230, vcc, 0x5000, v14
	v_addc_co_u32_e32 v231, vcc, 0, v15, vcc
	global_load_dwordx4 v[236:239], v[230:231], off offset:16
	global_load_dwordx4 v[230:233], v[230:231], off
	v_add_co_u32_e32 v240, vcc, 0x4800, v14
	v_addc_co_u32_e32 v241, vcc, 0, v15, vcc
	global_load_dwordx4 v[244:247], v[240:241], off offset:16
	global_load_dwordx4 v[240:243], v[240:241], off
	v_add_co_u32_e32 v248, vcc, 0x4000, v14
	v_addc_co_u32_e32 v249, vcc, 0, v15, vcc
	global_load_dwordx4 v[252:255], v[248:249], off offset:16
	global_load_dwordx4 v[248:251], v[248:249], off
	v_mov_b32_e32 v34, 0
	v_mov_b32_e32 v35, 0
	v_mov_b32_e32 v36, 0
	v_mov_b32_e32 v37, 0
	v_mov_b32_e32 v38, 0
	v_mov_b32_e32 v39, 0
	v_mov_b32_e32 v40, 0
	v_mov_b32_e32 v41, 0
	v_mov_b32_e32 v42, 0
	v_mov_b32_e32 v43, 0
	v_mov_b32_e32 v44, 0
	v_mov_b32_e32 v45, 0
	v_mov_b32_e32 v46, 0
	v_mov_b32_e32 v47, 0
	v_mov_b32_e32 v48, 0
	v_mov_b32_e32 v49, 0
	v_mov_b32_e32 v50, 0
	v_mov_b32_e32 v51, 0
	v_mov_b32_e32 v52, 0
	v_mov_b32_e32 v53, 0
	v_mov_b32_e32 v54, 0
	v_mov_b32_e32 v55, 0
	v_mov_b32_e32 v56, 0
	v_mov_b32_e32 v57, 0
	v_mov_b32_e32 v64, 0
	v_mov_b32_e32 v65, 0
	v_mov_b32_e32 v66, 0
	v_mov_b32_e32 v67, 0
	v_mov_b32_e32 v68, 0
	v_mov_b32_e32 v69, 0
	v_mov_b32_e32 v70, 0
	v_mov_b32_e32 v71, 0
	s_waitcnt vmcnt(29)
	v_lshlrev_b32_e32 v16, 16, v72
	v_and_b32_e32 v17, 0xffff0000, v72
	v_lshlrev_b32_e32 v18, 16, v73
	v_and_b32_e32 v19, 0xffff0000, v73
	v_lshlrev_b32_e32 v20, 16, v74
	v_and_b32_e32 v21, 0xffff0000, v74
	v_lshlrev_b32_e32 v22, 16, v75
	v_and_b32_e32 v23, 0xffff0000, v75
	v_add_u32_e32 v58, -12, v150
	v_cmp_gt_u32_e32 vcc, s12, v58
	s_and_b64 exec, vcc, s[98:99]
	v_pk_add_f32 v[64:65], v[64:65], v[16:17]
	v_pk_add_f32 v[66:67], v[66:67], v[18:19]
	v_pk_add_f32 v[68:69], v[68:69], v[20:21]
	v_pk_add_f32 v[70:71], v[70:71], v[22:23]
	s_mov_b64 exec, s[98:99]
	s_waitcnt vmcnt(28)
	v_lshlrev_b32_e32 v16, 16, v80
	v_and_b32_e32 v17, 0xffff0000, v80
	v_lshlrev_b32_e32 v18, 16, v81
	v_and_b32_e32 v19, 0xffff0000, v81
	v_lshlrev_b32_e32 v20, 16, v82
	v_and_b32_e32 v21, 0xffff0000, v82
	v_lshlrev_b32_e32 v22, 16, v83
	v_and_b32_e32 v23, 0xffff0000, v83
	v_add_u32_e32 v58, -12, v150
	v_cmp_gt_u32_e32 vcc, s12, v58
	s_and_b64 exec, vcc, s[98:99]
	v_pk_add_f32 v[50:51], v[50:51], v[16:17]
	v_pk_add_f32 v[52:53], v[52:53], v[18:19]
	v_pk_add_f32 v[54:55], v[54:55], v[20:21]
	v_pk_add_f32 v[56:57], v[56:57], v[22:23]
	s_mov_b64 exec, s[98:99]
	v_add_u32_e32 v58, -11, v150
	v_cmp_gt_u32_e32 vcc, s12, v58
	s_and_b64 exec, vcc, s[98:99]
	v_pk_add_f32 v[64:65], v[64:65], v[16:17]
	v_pk_add_f32 v[66:67], v[66:67], v[18:19]
	v_pk_add_f32 v[68:69], v[68:69], v[20:21]
	v_pk_add_f32 v[70:71], v[70:71], v[22:23]
	s_mov_b64 exec, s[98:99]
	s_waitcnt vmcnt(27)
	v_lshlrev_b32_e32 v16, 16, v92
	v_and_b32_e32 v17, 0xffff0000, v92
	v_lshlrev_b32_e32 v18, 16, v93
	v_and_b32_e32 v19, 0xffff0000, v93
	v_lshlrev_b32_e32 v20, 16, v94
	v_and_b32_e32 v21, 0xffff0000, v94
	v_lshlrev_b32_e32 v22, 16, v95
	v_and_b32_e32 v23, 0xffff0000, v95
	v_add_u32_e32 v58, -12, v150
	v_cmp_gt_u32_e32 vcc, s12, v58
	s_and_b64 exec, vcc, s[98:99]
	v_pk_add_f32 v[42:43], v[42:43], v[16:17]
	v_pk_add_f32 v[44:45], v[44:45], v[18:19]
	v_pk_add_f32 v[46:47], v[46:47], v[20:21]
	v_pk_add_f32 v[48:49], v[48:49], v[22:23]
	s_mov_b64 exec, s[98:99]
	v_add_u32_e32 v58, -11, v150
	v_cmp_gt_u32_e32 vcc, s12, v58
	s_and_b64 exec, vcc, s[98:99]
	v_pk_add_f32 v[50:51], v[50:51], v[16:17]
	v_pk_add_f32 v[52:53], v[52:53], v[18:19]
	v_pk_add_f32 v[54:55], v[54:55], v[20:21]
	v_pk_add_f32 v[56:57], v[56:57], v[22:23]
	s_mov_b64 exec, s[98:99]
	v_add_u32_e32 v58, -10, v150
	v_cmp_gt_u32_e32 vcc, s12, v58
	s_and_b64 exec, vcc, s[98:99]
	v_pk_add_f32 v[64:65], v[64:65], v[16:17]
	v_pk_add_f32 v[66:67], v[66:67], v[18:19]
	v_pk_add_f32 v[68:69], v[68:69], v[20:21]
	v_pk_add_f32 v[70:71], v[70:71], v[22:23]
	s_mov_b64 exec, s[98:99]
	s_waitcnt vmcnt(26)
	v_lshlrev_b32_e32 v16, 16, v96
	v_and_b32_e32 v17, 0xffff0000, v96
	v_lshlrev_b32_e32 v18, 16, v97
	v_and_b32_e32 v19, 0xffff0000, v97
	v_lshlrev_b32_e32 v20, 16, v98
	v_and_b32_e32 v21, 0xffff0000, v98
	v_lshlrev_b32_e32 v22, 16, v99
	v_and_b32_e32 v23, 0xffff0000, v99
	v_add_u32_e32 v58, -12, v150
	v_cmp_gt_u32_e32 vcc, s12, v58
	s_and_b64 exec, vcc, s[98:99]
	v_pk_add_f32 v[34:35], v[34:35], v[16:17]
	v_pk_add_f32 v[36:37], v[36:37], v[18:19]
	v_pk_add_f32 v[38:39], v[38:39], v[20:21]
	v_pk_add_f32 v[40:41], v[40:41], v[22:23]
	s_mov_b64 exec, s[98:99]
	v_add_u32_e32 v58, -11, v150
	v_cmp_gt_u32_e32 vcc, s12, v58
	s_and_b64 exec, vcc, s[98:99]
	v_pk_add_f32 v[42:43], v[42:43], v[16:17]
	v_pk_add_f32 v[44:45], v[44:45], v[18:19]
	v_pk_add_f32 v[46:47], v[46:47], v[20:21]
	v_pk_add_f32 v[48:49], v[48:49], v[22:23]
	s_mov_b64 exec, s[98:99]
	v_add_u32_e32 v58, -10, v150
	v_cmp_gt_u32_e32 vcc, s12, v58
	s_and_b64 exec, vcc, s[98:99]
	v_pk_add_f32 v[50:51], v[50:51], v[16:17]
	v_pk_add_f32 v[52:53], v[52:53], v[18:19]
	v_pk_add_f32 v[54:55], v[54:55], v[20:21]
	v_pk_add_f32 v[56:57], v[56:57], v[22:23]
	s_mov_b64 exec, s[98:99]
	v_add_u32_e32 v58, -9, v150
	v_cmp_gt_u32_e32 vcc, s12, v58
	s_and_b64 exec, vcc, s[98:99]
	v_pk_add_f32 v[64:65], v[64:65], v[16:17]
	v_pk_add_f32 v[66:67], v[66:67], v[18:19]
	v_pk_add_f32 v[68:69], v[68:69], v[20:21]
	v_pk_add_f32 v[70:71], v[70:71], v[22:23]
	s_mov_b64 exec, s[98:99]
	s_waitcnt vmcnt(25)
	v_lshlrev_b32_e32 v16, 16, v100
	v_and_b32_e32 v17, 0xffff0000, v100
	v_lshlrev_b32_e32 v18, 16, v101
	v_and_b32_e32 v19, 0xffff0000, v101
	v_lshlrev_b32_e32 v20, 16, v102
	v_and_b32_e32 v21, 0xffff0000, v102
	v_lshlrev_b32_e32 v22, 16, v103
	v_and_b32_e32 v23, 0xffff0000, v103
	v_add_u32_e32 v58, -11, v150
	v_cmp_gt_u32_e32 vcc, s12, v58
	s_and_b64 exec, vcc, s[98:99]
	v_pk_add_f32 v[34:35], v[34:35], v[16:17]
	v_pk_add_f32 v[36:37], v[36:37], v[18:19]
	v_pk_add_f32 v[38:39], v[38:39], v[20:21]
	v_pk_add_f32 v[40:41], v[40:41], v[22:23]
	s_mov_b64 exec, s[98:99]
	v_add_u32_e32 v58, -10, v150
	v_cmp_gt_u32_e32 vcc, s12, v58
	s_and_b64 exec, vcc, s[98:99]
	v_pk_add_f32 v[42:43], v[42:43], v[16:17]
	v_pk_add_f32 v[44:45], v[44:45], v[18:19]
	v_pk_add_f32 v[46:47], v[46:47], v[20:21]
	v_pk_add_f32 v[48:49], v[48:49], v[22:23]
	s_mov_b64 exec, s[98:99]
	v_add_u32_e32 v58, -9, v150
	v_cmp_gt_u32_e32 vcc, s12, v58
	s_and_b64 exec, vcc, s[98:99]
	v_pk_add_f32 v[50:51], v[50:51], v[16:17]
	v_pk_add_f32 v[52:53], v[52:53], v[18:19]
	v_pk_add_f32 v[54:55], v[54:55], v[20:21]
	v_pk_add_f32 v[56:57], v[56:57], v[22:23]
	s_mov_b64 exec, s[98:99]
	v_add_u32_e32 v58, -8, v150
	v_cmp_gt_u32_e32 vcc, s12, v58
	s_and_b64 exec, vcc, s[98:99]
	v_pk_add_f32 v[64:65], v[64:65], v[16:17]
	v_pk_add_f32 v[66:67], v[66:67], v[18:19]
	v_pk_add_f32 v[68:69], v[68:69], v[20:21]
	v_pk_add_f32 v[70:71], v[70:71], v[22:23]
	s_mov_b64 exec, s[98:99]
	s_waitcnt vmcnt(24)
	v_lshlrev_b32_e32 v16, 16, v104
	v_and_b32_e32 v17, 0xffff0000, v104
	v_lshlrev_b32_e32 v18, 16, v105
	v_and_b32_e32 v19, 0xffff0000, v105
	v_lshlrev_b32_e32 v20, 16, v106
	v_and_b32_e32 v21, 0xffff0000, v106
	v_lshlrev_b32_e32 v22, 16, v107
	v_and_b32_e32 v23, 0xffff0000, v107
	v_add_u32_e32 v58, -10, v150
	v_cmp_gt_u32_e32 vcc, s12, v58
	s_and_b64 exec, vcc, s[98:99]
	v_pk_add_f32 v[34:35], v[34:35], v[16:17]
	v_pk_add_f32 v[36:37], v[36:37], v[18:19]
	v_pk_add_f32 v[38:39], v[38:39], v[20:21]
	v_pk_add_f32 v[40:41], v[40:41], v[22:23]
	s_mov_b64 exec, s[98:99]
	v_add_u32_e32 v58, -9, v150
	v_cmp_gt_u32_e32 vcc, s12, v58
	s_and_b64 exec, vcc, s[98:99]
	v_pk_add_f32 v[42:43], v[42:43], v[16:17]
	v_pk_add_f32 v[44:45], v[44:45], v[18:19]
	v_pk_add_f32 v[46:47], v[46:47], v[20:21]
	v_pk_add_f32 v[48:49], v[48:49], v[22:23]
	s_mov_b64 exec, s[98:99]
	v_add_u32_e32 v58, -8, v150
	v_cmp_gt_u32_e32 vcc, s12, v58
	s_and_b64 exec, vcc, s[98:99]
	v_pk_add_f32 v[50:51], v[50:51], v[16:17]
	v_pk_add_f32 v[52:53], v[52:53], v[18:19]
	v_pk_add_f32 v[54:55], v[54:55], v[20:21]
	v_pk_add_f32 v[56:57], v[56:57], v[22:23]
	s_mov_b64 exec, s[98:99]
	v_add_u32_e32 v58, -7, v150
	v_cmp_gt_u32_e32 vcc, s12, v58
	s_and_b64 exec, vcc, s[98:99]
	v_pk_add_f32 v[64:65], v[64:65], v[16:17]
	v_pk_add_f32 v[66:67], v[66:67], v[18:19]
	v_pk_add_f32 v[68:69], v[68:69], v[20:21]
	v_pk_add_f32 v[70:71], v[70:71], v[22:23]
	s_mov_b64 exec, s[98:99]
	s_waitcnt vmcnt(23)
	v_lshlrev_b32_e32 v16, 16, v108
	v_and_b32_e32 v17, 0xffff0000, v108
	v_lshlrev_b32_e32 v18, 16, v109
	v_and_b32_e32 v19, 0xffff0000, v109
	v_lshlrev_b32_e32 v20, 16, v110
	v_and_b32_e32 v21, 0xffff0000, v110
	v_lshlrev_b32_e32 v22, 16, v111
	v_and_b32_e32 v23, 0xffff0000, v111
	v_add_u32_e32 v58, -9, v150
	v_cmp_gt_u32_e32 vcc, s12, v58
	s_and_b64 exec, vcc, s[98:99]
	v_pk_add_f32 v[34:35], v[34:35], v[16:17]
	v_pk_add_f32 v[36:37], v[36:37], v[18:19]
	v_pk_add_f32 v[38:39], v[38:39], v[20:21]
	v_pk_add_f32 v[40:41], v[40:41], v[22:23]
	s_mov_b64 exec, s[98:99]
	v_add_u32_e32 v58, -8, v150
	v_cmp_gt_u32_e32 vcc, s12, v58
	s_and_b64 exec, vcc, s[98:99]
	v_pk_add_f32 v[42:43], v[42:43], v[16:17]
	v_pk_add_f32 v[44:45], v[44:45], v[18:19]
	v_pk_add_f32 v[46:47], v[46:47], v[20:21]
	v_pk_add_f32 v[48:49], v[48:49], v[22:23]
	s_mov_b64 exec, s[98:99]
	v_add_u32_e32 v58, -7, v150
	v_cmp_gt_u32_e32 vcc, s12, v58
	s_and_b64 exec, vcc, s[98:99]
	v_pk_add_f32 v[50:51], v[50:51], v[16:17]
	v_pk_add_f32 v[52:53], v[52:53], v[18:19]
	v_pk_add_f32 v[54:55], v[54:55], v[20:21]
	v_pk_add_f32 v[56:57], v[56:57], v[22:23]
	s_mov_b64 exec, s[98:99]
	v_add_u32_e32 v58, -6, v150
	v_cmp_gt_u32_e32 vcc, s12, v58
	s_and_b64 exec, vcc, s[98:99]
	v_pk_add_f32 v[64:65], v[64:65], v[16:17]
	v_pk_add_f32 v[66:67], v[66:67], v[18:19]
	v_pk_add_f32 v[68:69], v[68:69], v[20:21]
	v_pk_add_f32 v[70:71], v[70:71], v[22:23]
	s_mov_b64 exec, s[98:99]
	s_waitcnt vmcnt(22)
	v_lshlrev_b32_e32 v16, 16, v112
	v_and_b32_e32 v17, 0xffff0000, v112
	v_lshlrev_b32_e32 v18, 16, v113
	v_and_b32_e32 v19, 0xffff0000, v113
	v_lshlrev_b32_e32 v20, 16, v114
	v_and_b32_e32 v21, 0xffff0000, v114
	v_lshlrev_b32_e32 v22, 16, v115
	v_and_b32_e32 v23, 0xffff0000, v115
	v_add_u32_e32 v58, -8, v150
	v_cmp_gt_u32_e32 vcc, s12, v58
	s_and_b64 exec, vcc, s[98:99]
	v_pk_add_f32 v[34:35], v[34:35], v[16:17]
	v_pk_add_f32 v[36:37], v[36:37], v[18:19]
	v_pk_add_f32 v[38:39], v[38:39], v[20:21]
	v_pk_add_f32 v[40:41], v[40:41], v[22:23]
	s_mov_b64 exec, s[98:99]
	v_add_u32_e32 v58, -7, v150
	v_cmp_gt_u32_e32 vcc, s12, v58
	s_and_b64 exec, vcc, s[98:99]
	v_pk_add_f32 v[42:43], v[42:43], v[16:17]
	v_pk_add_f32 v[44:45], v[44:45], v[18:19]
	v_pk_add_f32 v[46:47], v[46:47], v[20:21]
	v_pk_add_f32 v[48:49], v[48:49], v[22:23]
	s_mov_b64 exec, s[98:99]
	v_add_u32_e32 v58, -6, v150
	v_cmp_gt_u32_e32 vcc, s12, v58
	s_and_b64 exec, vcc, s[98:99]
	v_pk_add_f32 v[50:51], v[50:51], v[16:17]
	v_pk_add_f32 v[52:53], v[52:53], v[18:19]
	v_pk_add_f32 v[54:55], v[54:55], v[20:21]
	v_pk_add_f32 v[56:57], v[56:57], v[22:23]
	s_mov_b64 exec, s[98:99]
	v_add_u32_e32 v58, -5, v150
	v_cmp_gt_u32_e32 vcc, s12, v58
	s_and_b64 exec, vcc, s[98:99]
	v_pk_add_f32 v[64:65], v[64:65], v[16:17]
	v_pk_add_f32 v[66:67], v[66:67], v[18:19]
	v_pk_add_f32 v[68:69], v[68:69], v[20:21]
	v_pk_add_f32 v[70:71], v[70:71], v[22:23]
	s_mov_b64 exec, s[98:99]
	s_waitcnt vmcnt(21)
	v_lshlrev_b32_e32 v16, 16, v116
	v_and_b32_e32 v17, 0xffff0000, v116
	v_lshlrev_b32_e32 v18, 16, v117
	v_and_b32_e32 v19, 0xffff0000, v117
	v_lshlrev_b32_e32 v20, 16, v118
	v_and_b32_e32 v21, 0xffff0000, v118
	v_lshlrev_b32_e32 v22, 16, v119
	v_and_b32_e32 v23, 0xffff0000, v119
	v_add_u32_e32 v58, -7, v150
	v_cmp_gt_u32_e32 vcc, s12, v58
	s_and_b64 exec, vcc, s[98:99]
	v_pk_add_f32 v[34:35], v[34:35], v[16:17]
	v_pk_add_f32 v[36:37], v[36:37], v[18:19]
	v_pk_add_f32 v[38:39], v[38:39], v[20:21]
	v_pk_add_f32 v[40:41], v[40:41], v[22:23]
	s_mov_b64 exec, s[98:99]
	v_add_u32_e32 v58, -6, v150
	v_cmp_gt_u32_e32 vcc, s12, v58
	s_and_b64 exec, vcc, s[98:99]
	v_pk_add_f32 v[42:43], v[42:43], v[16:17]
	v_pk_add_f32 v[44:45], v[44:45], v[18:19]
	v_pk_add_f32 v[46:47], v[46:47], v[20:21]
	v_pk_add_f32 v[48:49], v[48:49], v[22:23]
	s_mov_b64 exec, s[98:99]
	v_add_u32_e32 v58, -5, v150
	v_cmp_gt_u32_e32 vcc, s12, v58
	s_and_b64 exec, vcc, s[98:99]
	v_pk_add_f32 v[50:51], v[50:51], v[16:17]
	v_pk_add_f32 v[52:53], v[52:53], v[18:19]
	v_pk_add_f32 v[54:55], v[54:55], v[20:21]
	v_pk_add_f32 v[56:57], v[56:57], v[22:23]
	s_mov_b64 exec, s[98:99]
	v_add_u32_e32 v58, -4, v150
	v_cmp_gt_u32_e32 vcc, s12, v58
	s_and_b64 exec, vcc, s[98:99]
	v_pk_add_f32 v[64:65], v[64:65], v[16:17]
	v_pk_add_f32 v[66:67], v[66:67], v[18:19]
	v_pk_add_f32 v[68:69], v[68:69], v[20:21]
	v_pk_add_f32 v[70:71], v[70:71], v[22:23]
	s_mov_b64 exec, s[98:99]
	s_waitcnt vmcnt(20)
	v_lshlrev_b32_e32 v16, 16, v120
	v_and_b32_e32 v17, 0xffff0000, v120
	v_lshlrev_b32_e32 v18, 16, v121
	v_and_b32_e32 v19, 0xffff0000, v121
	v_lshlrev_b32_e32 v20, 16, v122
	v_and_b32_e32 v21, 0xffff0000, v122
	v_lshlrev_b32_e32 v22, 16, v123
	v_and_b32_e32 v23, 0xffff0000, v123
	v_add_u32_e32 v58, -6, v150
	v_cmp_gt_u32_e32 vcc, s12, v58
	s_and_b64 exec, vcc, s[98:99]
	v_pk_add_f32 v[34:35], v[34:35], v[16:17]
	v_pk_add_f32 v[36:37], v[36:37], v[18:19]
	v_pk_add_f32 v[38:39], v[38:39], v[20:21]
	v_pk_add_f32 v[40:41], v[40:41], v[22:23]
	s_mov_b64 exec, s[98:99]
	v_add_u32_e32 v58, -5, v150
	v_cmp_gt_u32_e32 vcc, s12, v58
	s_and_b64 exec, vcc, s[98:99]
	v_pk_add_f32 v[42:43], v[42:43], v[16:17]
	v_pk_add_f32 v[44:45], v[44:45], v[18:19]
	v_pk_add_f32 v[46:47], v[46:47], v[20:21]
	v_pk_add_f32 v[48:49], v[48:49], v[22:23]
	s_mov_b64 exec, s[98:99]
	v_add_u32_e32 v58, -4, v150
	v_cmp_gt_u32_e32 vcc, s12, v58
	s_and_b64 exec, vcc, s[98:99]
	v_pk_add_f32 v[50:51], v[50:51], v[16:17]
	v_pk_add_f32 v[52:53], v[52:53], v[18:19]
	v_pk_add_f32 v[54:55], v[54:55], v[20:21]
	v_pk_add_f32 v[56:57], v[56:57], v[22:23]
	s_mov_b64 exec, s[98:99]
	v_add_u32_e32 v58, -3, v150
	v_cmp_gt_u32_e32 vcc, s12, v58
	s_and_b64 exec, vcc, s[98:99]
	v_pk_add_f32 v[64:65], v[64:65], v[16:17]
	v_pk_add_f32 v[66:67], v[66:67], v[18:19]
	v_pk_add_f32 v[68:69], v[68:69], v[20:21]
	v_pk_add_f32 v[70:71], v[70:71], v[22:23]
	s_mov_b64 exec, s[98:99]
	s_waitcnt vmcnt(19)
	v_lshlrev_b32_e32 v16, 16, v124
	v_and_b32_e32 v17, 0xffff0000, v124
	v_lshlrev_b32_e32 v18, 16, v125
	v_and_b32_e32 v19, 0xffff0000, v125
	v_lshlrev_b32_e32 v20, 16, v126
	v_and_b32_e32 v21, 0xffff0000, v126
	v_lshlrev_b32_e32 v22, 16, v127
	v_and_b32_e32 v23, 0xffff0000, v127
	v_add_u32_e32 v58, -5, v150
	v_cmp_gt_u32_e32 vcc, s12, v58
	s_and_b64 exec, vcc, s[98:99]
	v_pk_add_f32 v[34:35], v[34:35], v[16:17]
	v_pk_add_f32 v[36:37], v[36:37], v[18:19]
	v_pk_add_f32 v[38:39], v[38:39], v[20:21]
	v_pk_add_f32 v[40:41], v[40:41], v[22:23]
	s_mov_b64 exec, s[98:99]
	v_add_u32_e32 v58, -4, v150
	v_cmp_gt_u32_e32 vcc, s12, v58
	s_and_b64 exec, vcc, s[98:99]
	v_pk_add_f32 v[42:43], v[42:43], v[16:17]
	v_pk_add_f32 v[44:45], v[44:45], v[18:19]
	v_pk_add_f32 v[46:47], v[46:47], v[20:21]
	v_pk_add_f32 v[48:49], v[48:49], v[22:23]
	s_mov_b64 exec, s[98:99]
	v_add_u32_e32 v58, -3, v150
	v_cmp_gt_u32_e32 vcc, s12, v58
	s_and_b64 exec, vcc, s[98:99]
	v_pk_add_f32 v[50:51], v[50:51], v[16:17]
	v_pk_add_f32 v[52:53], v[52:53], v[18:19]
	v_pk_add_f32 v[54:55], v[54:55], v[20:21]
	v_pk_add_f32 v[56:57], v[56:57], v[22:23]
	s_mov_b64 exec, s[98:99]
	v_add_u32_e32 v58, -2, v150
	v_cmp_gt_u32_e32 vcc, s12, v58
	s_and_b64 exec, vcc, s[98:99]
	v_pk_add_f32 v[64:65], v[64:65], v[16:17]
	v_pk_add_f32 v[66:67], v[66:67], v[18:19]
	v_pk_add_f32 v[68:69], v[68:69], v[20:21]
	v_pk_add_f32 v[70:71], v[70:71], v[22:23]
	s_mov_b64 exec, s[98:99]
	s_waitcnt vmcnt(18)
	v_lshlrev_b32_e32 v16, 16, v128
	v_and_b32_e32 v17, 0xffff0000, v128
	v_lshlrev_b32_e32 v18, 16, v129
	v_and_b32_e32 v19, 0xffff0000, v129
	v_lshlrev_b32_e32 v20, 16, v130
	v_and_b32_e32 v21, 0xffff0000, v130
	v_lshlrev_b32_e32 v22, 16, v131
	v_and_b32_e32 v23, 0xffff0000, v131
	v_add_u32_e32 v58, -4, v150
	v_cmp_gt_u32_e32 vcc, s12, v58
	s_and_b64 exec, vcc, s[98:99]
	v_pk_add_f32 v[34:35], v[34:35], v[16:17]
	v_pk_add_f32 v[36:37], v[36:37], v[18:19]
	v_pk_add_f32 v[38:39], v[38:39], v[20:21]
	v_pk_add_f32 v[40:41], v[40:41], v[22:23]
	s_mov_b64 exec, s[98:99]
	v_add_u32_e32 v58, -3, v150
	v_cmp_gt_u32_e32 vcc, s12, v58
	s_and_b64 exec, vcc, s[98:99]
	v_pk_add_f32 v[42:43], v[42:43], v[16:17]
	v_pk_add_f32 v[44:45], v[44:45], v[18:19]
	v_pk_add_f32 v[46:47], v[46:47], v[20:21]
	v_pk_add_f32 v[48:49], v[48:49], v[22:23]
	s_mov_b64 exec, s[98:99]
	v_add_u32_e32 v58, -2, v150
	v_cmp_gt_u32_e32 vcc, s12, v58
	s_and_b64 exec, vcc, s[98:99]
	v_pk_add_f32 v[50:51], v[50:51], v[16:17]
	v_pk_add_f32 v[52:53], v[52:53], v[18:19]
	v_pk_add_f32 v[54:55], v[54:55], v[20:21]
	v_pk_add_f32 v[56:57], v[56:57], v[22:23]
	s_mov_b64 exec, s[98:99]
	v_add_u32_e32 v58, -1, v150
	v_cmp_gt_u32_e32 vcc, s12, v58
	s_and_b64 exec, vcc, s[98:99]
	v_pk_add_f32 v[64:65], v[64:65], v[16:17]
	v_pk_add_f32 v[66:67], v[66:67], v[18:19]
	v_pk_add_f32 v[68:69], v[68:69], v[20:21]
	v_pk_add_f32 v[70:71], v[70:71], v[22:23]
	s_mov_b64 exec, s[98:99]
	s_waitcnt vmcnt(17)
	v_lshlrev_b32_e32 v16, 16, v132
	v_and_b32_e32 v17, 0xffff0000, v132
	v_lshlrev_b32_e32 v18, 16, v133
	v_and_b32_e32 v19, 0xffff0000, v133
	v_lshlrev_b32_e32 v20, 16, v134
	v_and_b32_e32 v21, 0xffff0000, v134
	v_lshlrev_b32_e32 v22, 16, v135
	v_and_b32_e32 v23, 0xffff0000, v135
	v_add_u32_e32 v58, -3, v150
	v_cmp_gt_u32_e32 vcc, s12, v58
	s_and_b64 exec, vcc, s[98:99]
	v_pk_add_f32 v[34:35], v[34:35], v[16:17]
	v_pk_add_f32 v[36:37], v[36:37], v[18:19]
	v_pk_add_f32 v[38:39], v[38:39], v[20:21]
	v_pk_add_f32 v[40:41], v[40:41], v[22:23]
	s_mov_b64 exec, s[98:99]
	v_add_u32_e32 v58, -2, v150
	v_cmp_gt_u32_e32 vcc, s12, v58
	s_and_b64 exec, vcc, s[98:99]
	v_pk_add_f32 v[42:43], v[42:43], v[16:17]
	v_pk_add_f32 v[44:45], v[44:45], v[18:19]
	v_pk_add_f32 v[46:47], v[46:47], v[20:21]
	v_pk_add_f32 v[48:49], v[48:49], v[22:23]
	s_mov_b64 exec, s[98:99]
	v_add_u32_e32 v58, -1, v150
	v_cmp_gt_u32_e32 vcc, s12, v58
	s_and_b64 exec, vcc, s[98:99]
	v_pk_add_f32 v[50:51], v[50:51], v[16:17]
	v_pk_add_f32 v[52:53], v[52:53], v[18:19]
	v_pk_add_f32 v[54:55], v[54:55], v[20:21]
	v_pk_add_f32 v[56:57], v[56:57], v[22:23]
	s_mov_b64 exec, s[98:99]
	v_add_u32_e32 v58, 0, v150
	v_cmp_gt_u32_e32 vcc, s12, v58
	s_and_b64 exec, vcc, s[98:99]
	v_pk_add_f32 v[64:65], v[64:65], v[16:17]
	v_pk_add_f32 v[66:67], v[66:67], v[18:19]
	v_pk_add_f32 v[68:69], v[68:69], v[20:21]
	v_pk_add_f32 v[70:71], v[70:71], v[22:23]
	s_mov_b64 exec, s[98:99]
	s_waitcnt vmcnt(16)
	v_lshlrev_b32_e32 v16, 16, v136
	v_and_b32_e32 v17, 0xffff0000, v136
	v_lshlrev_b32_e32 v18, 16, v137
	v_and_b32_e32 v19, 0xffff0000, v137
	v_lshlrev_b32_e32 v20, 16, v138
	v_and_b32_e32 v21, 0xffff0000, v138
	v_lshlrev_b32_e32 v22, 16, v139
	v_and_b32_e32 v23, 0xffff0000, v139
	v_add_u32_e32 v58, -2, v150
	v_cmp_gt_u32_e32 vcc, s12, v58
	s_and_b64 exec, vcc, s[98:99]
	v_pk_add_f32 v[34:35], v[34:35], v[16:17]
	v_pk_add_f32 v[36:37], v[36:37], v[18:19]
	v_pk_add_f32 v[38:39], v[38:39], v[20:21]
	v_pk_add_f32 v[40:41], v[40:41], v[22:23]
	s_mov_b64 exec, s[98:99]
	v_add_u32_e32 v58, -1, v150
	v_cmp_gt_u32_e32 vcc, s12, v58
	s_and_b64 exec, vcc, s[98:99]
	v_pk_add_f32 v[42:43], v[42:43], v[16:17]
	v_pk_add_f32 v[44:45], v[44:45], v[18:19]
	v_pk_add_f32 v[46:47], v[46:47], v[20:21]
	v_pk_add_f32 v[48:49], v[48:49], v[22:23]
	s_mov_b64 exec, s[98:99]
	v_add_u32_e32 v58, 0, v150
	v_cmp_gt_u32_e32 vcc, s12, v58
	s_and_b64 exec, vcc, s[98:99]
	v_pk_add_f32 v[50:51], v[50:51], v[16:17]
	v_pk_add_f32 v[52:53], v[52:53], v[18:19]
	v_pk_add_f32 v[54:55], v[54:55], v[20:21]
	v_pk_add_f32 v[56:57], v[56:57], v[22:23]
	s_mov_b64 exec, s[98:99]
	v_add_u32_e32 v58, 1, v150
	v_cmp_gt_u32_e32 vcc, s12, v58
	s_and_b64 exec, vcc, s[98:99]
	v_pk_add_f32 v[64:65], v[64:65], v[16:17]
	v_pk_add_f32 v[66:67], v[66:67], v[18:19]
	v_pk_add_f32 v[68:69], v[68:69], v[20:21]
	v_pk_add_f32 v[70:71], v[70:71], v[22:23]
	s_mov_b64 exec, s[98:99]
	s_waitcnt vmcnt(15)
	v_lshlrev_b32_e32 v16, 16, v176
	v_and_b32_e32 v17, 0xffff0000, v176
	v_lshlrev_b32_e32 v18, 16, v177
	v_and_b32_e32 v19, 0xffff0000, v177
	v_lshlrev_b32_e32 v20, 16, v178
	v_and_b32_e32 v21, 0xffff0000, v178
	v_lshlrev_b32_e32 v22, 16, v179
	v_and_b32_e32 v23, 0xffff0000, v179
	v_add_u32_e32 v58, -1, v150
	v_cmp_gt_u32_e32 vcc, s12, v58
	s_and_b64 exec, vcc, s[98:99]
	v_pk_add_f32 v[34:35], v[34:35], v[16:17]
	v_pk_add_f32 v[36:37], v[36:37], v[18:19]
	v_pk_add_f32 v[38:39], v[38:39], v[20:21]
	v_pk_add_f32 v[40:41], v[40:41], v[22:23]
	s_mov_b64 exec, s[98:99]
	v_add_u32_e32 v58, 0, v150
	v_cmp_gt_u32_e32 vcc, s12, v58
	s_and_b64 exec, vcc, s[98:99]
	v_pk_add_f32 v[42:43], v[42:43], v[16:17]
	v_pk_add_f32 v[44:45], v[44:45], v[18:19]
	v_pk_add_f32 v[46:47], v[46:47], v[20:21]
	v_pk_add_f32 v[48:49], v[48:49], v[22:23]
	s_mov_b64 exec, s[98:99]
	v_add_u32_e32 v58, 1, v150
	v_cmp_gt_u32_e32 vcc, s12, v58
	s_and_b64 exec, vcc, s[98:99]
	v_pk_add_f32 v[50:51], v[50:51], v[16:17]
	v_pk_add_f32 v[52:53], v[52:53], v[18:19]
	v_pk_add_f32 v[54:55], v[54:55], v[20:21]
	v_pk_add_f32 v[56:57], v[56:57], v[22:23]
	s_mov_b64 exec, s[98:99]
	v_add_u32_e32 v58, 2, v150
	v_cmp_gt_u32_e32 vcc, s12, v58
	s_and_b64 exec, vcc, s[98:99]
	v_pk_add_f32 v[64:65], v[64:65], v[16:17]
	v_pk_add_f32 v[66:67], v[66:67], v[18:19]
	v_pk_add_f32 v[68:69], v[68:69], v[20:21]
	v_pk_add_f32 v[70:71], v[70:71], v[22:23]
	s_mov_b64 exec, s[98:99]
	s_waitcnt vmcnt(14)
	v_lshlrev_b32_e32 v16, 16, v180
	v_and_b32_e32 v17, 0xffff0000, v180
	v_lshlrev_b32_e32 v18, 16, v181
	v_and_b32_e32 v19, 0xffff0000, v181
	v_lshlrev_b32_e32 v20, 16, v182
	v_and_b32_e32 v21, 0xffff0000, v182
	v_lshlrev_b32_e32 v22, 16, v183
	v_and_b32_e32 v23, 0xffff0000, v183
	v_add_u32_e32 v58, 0, v150
	v_cmp_gt_u32_e32 vcc, s12, v58
	s_and_b64 exec, vcc, s[98:99]
	v_pk_add_f32 v[34:35], v[34:35], v[16:17]
	v_pk_add_f32 v[36:37], v[36:37], v[18:19]
	v_pk_add_f32 v[38:39], v[38:39], v[20:21]
	v_pk_add_f32 v[40:41], v[40:41], v[22:23]
	s_mov_b64 exec, s[98:99]
	v_add_u32_e32 v58, 1, v150
	v_cmp_gt_u32_e32 vcc, s12, v58
	s_and_b64 exec, vcc, s[98:99]
	v_pk_add_f32 v[42:43], v[42:43], v[16:17]
	v_pk_add_f32 v[44:45], v[44:45], v[18:19]
	v_pk_add_f32 v[46:47], v[46:47], v[20:21]
	v_pk_add_f32 v[48:49], v[48:49], v[22:23]
	s_mov_b64 exec, s[98:99]
	v_add_u32_e32 v58, 2, v150
	v_cmp_gt_u32_e32 vcc, s12, v58
	s_and_b64 exec, vcc, s[98:99]
	v_pk_add_f32 v[50:51], v[50:51], v[16:17]
	v_pk_add_f32 v[52:53], v[52:53], v[18:19]
	v_pk_add_f32 v[54:55], v[54:55], v[20:21]
	v_pk_add_f32 v[56:57], v[56:57], v[22:23]
	s_mov_b64 exec, s[98:99]
	v_add_u32_e32 v58, 3, v150
	v_cmp_gt_u32_e32 vcc, s12, v58
	s_and_b64 exec, vcc, s[98:99]
	v_pk_add_f32 v[64:65], v[64:65], v[16:17]
	v_pk_add_f32 v[66:67], v[66:67], v[18:19]
	v_pk_add_f32 v[68:69], v[68:69], v[20:21]
	v_pk_add_f32 v[70:71], v[70:71], v[22:23]
	s_mov_b64 exec, s[98:99]
	v_add_co_u32_e32 v72, vcc, 0x3800, v14
	v_addc_co_u32_e32 v73, vcc, 0, v15, vcc
	global_load_dwordx4 v[80:83], v[72:73], off offset:16
	global_load_dwordx4 v[72:75], v[72:73], off
	v_add_co_u32_e32 v92, vcc, 0x3000, v14
	v_addc_co_u32_e32 v93, vcc, 0, v15, vcc
	global_load_dwordx4 v[96:99], v[92:93], off offset:16
	global_load_dwordx4 v[92:95], v[92:93], off
	v_add_co_u32_e32 v100, vcc, 0x2800, v14
	v_addc_co_u32_e32 v101, vcc, 0, v15, vcc
	global_load_dwordx4 v[104:107], v[100:101], off offset:16
	global_load_dwordx4 v[100:103], v[100:101], off
	v_add_co_u32_e32 v108, vcc, 0x2000, v14
	v_addc_co_u32_e32 v109, vcc, 0, v15, vcc
	global_load_dwordx4 v[112:115], v[108:109], off offset:16
	global_load_dwordx4 v[108:111], v[108:109], off
	v_add_co_u32_e32 v116, vcc, 0x1800, v14
	v_addc_co_u32_e32 v117, vcc, 0, v15, vcc
	global_load_dwordx4 v[120:123], v[116:117], off offset:16
	global_load_dwordx4 v[116:119], v[116:117], off
	v_add_co_u32_e32 v124, vcc, 0x1000, v14
	v_addc_co_u32_e32 v125, vcc, 0, v15, vcc
	global_load_dwordx4 v[128:131], v[124:125], off offset:16
	global_load_dwordx4 v[124:127], v[124:125], off
	v_add_co_u32_e32 v132, vcc, 0x800, v14
	v_addc_co_u32_e32 v133, vcc, 0, v15, vcc
	global_load_dwordx4 v[136:139], v[132:133], off offset:16
	global_load_dwordx4 v[132:135], v[132:133], off
	v_mov_b32_e32 v176, v14
	v_mov_b32_e32 v177, v15
	global_load_dwordx4 v[180:183], v[176:177], off offset:16
	global_load_dwordx4 v[176:179], v[176:177], off
	s_waitcnt vmcnt(28)
	v_add_u32_e32 v58, 1, v150
	v_cmp_gt_u32_e32 vcc, s12, v58
	s_and_b64 exec, vcc, s[98:99]
	v_pk_add_f32 v[34:35], v[34:35], v[184:185]
	v_pk_add_f32 v[36:37], v[36:37], v[186:187]
	v_pk_add_f32 v[38:39], v[38:39], v[188:189]
	v_pk_add_f32 v[40:41], v[40:41], v[190:191]
	s_mov_b64 exec, s[98:99]
	v_add_u32_e32 v58, 2, v150
	v_cmp_gt_u32_e32 vcc, s12, v58
	s_and_b64 exec, vcc, s[98:99]
	v_pk_add_f32 v[42:43], v[42:43], v[184:185]
	v_pk_add_f32 v[44:45], v[44:45], v[186:187]
	v_pk_add_f32 v[46:47], v[46:47], v[188:189]
	v_pk_add_f32 v[48:49], v[48:49], v[190:191]
	s_mov_b64 exec, s[98:99]
	v_add_u32_e32 v58, 3, v150
	v_cmp_gt_u32_e32 vcc, s12, v58
	s_and_b64 exec, vcc, s[98:99]
	v_pk_add_f32 v[50:51], v[50:51], v[184:185]
	v_pk_add_f32 v[52:53], v[52:53], v[186:187]
	v_pk_add_f32 v[54:55], v[54:55], v[188:189]
	v_pk_add_f32 v[56:57], v[56:57], v[190:191]
	s_mov_b64 exec, s[98:99]
	v_add_u32_e32 v58, 4, v150
	v_cmp_gt_u32_e32 vcc, s12, v58
	s_and_b64 exec, vcc, s[98:99]
	v_pk_add_f32 v[64:65], v[64:65], v[184:185]
	v_pk_add_f32 v[66:67], v[66:67], v[186:187]
	v_pk_add_f32 v[68:69], v[68:69], v[188:189]
	v_pk_add_f32 v[70:71], v[70:71], v[190:191]
	s_mov_b64 exec, s[98:99]
	s_cmp_lt_u32 s12, 4
	s_cbranch_scc1 ATS3_END
	s_waitcnt vmcnt(26)
	v_add_u32_e32 v58, 2, v150
	v_cmp_gt_u32_e32 vcc, s12, v58
	s_and_b64 exec, vcc, s[98:99]
	v_pk_add_f32 v[34:35], v[34:35], v[192:193]
	v_pk_add_f32 v[36:37], v[36:37], v[194:195]
	v_pk_add_f32 v[38:39], v[38:39], v[196:197]
	v_pk_add_f32 v[40:41], v[40:41], v[198:199]
	s_mov_b64 exec, s[98:99]
	v_add_u32_e32 v58, 3, v150
	v_cmp_gt_u32_e32 vcc, s12, v58
	s_and_b64 exec, vcc, s[98:99]
	v_pk_add_f32 v[42:43], v[42:43], v[192:193]
	v_pk_add_f32 v[44:45], v[44:45], v[194:195]
	v_pk_add_f32 v[46:47], v[46:47], v[196:197]
	v_pk_add_f32 v[48:49], v[48:49], v[198:199]
	s_mov_b64 exec, s[98:99]
	v_add_u32_e32 v58, 4, v150
	v_cmp_gt_u32_e32 vcc, s12, v58
	s_and_b64 exec, vcc, s[98:99]
	v_pk_add_f32 v[50:51], v[50:51], v[192:193]
	v_pk_add_f32 v[52:53], v[52:53], v[194:195]
	v_pk_add_f32 v[54:55], v[54:55], v[196:197]
	v_pk_add_f32 v[56:57], v[56:57], v[198:199]
	s_mov_b64 exec, s[98:99]
	v_add_u32_e32 v58, 5, v150
	v_cmp_gt_u32_e32 vcc, s12, v58
	s_and_b64 exec, vcc, s[98:99]
	v_pk_add_f32 v[64:65], v[64:65], v[192:193]
	v_pk_add_f32 v[66:67], v[66:67], v[194:195]
	v_pk_add_f32 v[68:69], v[68:69], v[196:197]
	v_pk_add_f32 v[70:71], v[70:71], v[198:199]
	s_mov_b64 exec, s[98:99]
	s_waitcnt vmcnt(24)
	v_add_u32_e32 v58, 3, v150
	v_cmp_gt_u32_e32 vcc, s12, v58
	s_and_b64 exec, vcc, s[98:99]
	v_pk_add_f32 v[34:35], v[34:35], v[200:201]
	v_pk_add_f32 v[36:37], v[36:37], v[202:203]
	v_pk_add_f32 v[38:39], v[38:39], v[218:219]
	v_pk_add_f32 v[40:41], v[40:41], v[220:221]
	s_mov_b64 exec, s[98:99]
	v_add_u32_e32 v58, 4, v150
	v_cmp_gt_u32_e32 vcc, s12, v58
	s_and_b64 exec, vcc, s[98:99]
	v_pk_add_f32 v[42:43], v[42:43], v[200:201]
	v_pk_add_f32 v[44:45], v[44:45], v[202:203]
	v_pk_add_f32 v[46:47], v[46:47], v[218:219]
	v_pk_add_f32 v[48:49], v[48:49], v[220:221]
	s_mov_b64 exec, s[98:99]
	v_add_u32_e32 v58, 5, v150
	v_cmp_gt_u32_e32 vcc, s12, v58
	s_and_b64 exec, vcc, s[98:99]
	v_pk_add_f32 v[50:51], v[50:51], v[200:201]
	v_pk_add_f32 v[52:53], v[52:53], v[202:203]
	v_pk_add_f32 v[54:55], v[54:55], v[218:219]
	v_pk_add_f32 v[56:57], v[56:57], v[220:221]
	s_mov_b64 exec, s[98:99]
	v_add_u32_e32 v58, 6, v150
	v_cmp_gt_u32_e32 vcc, s12, v58
	s_and_b64 exec, vcc, s[98:99]
	v_pk_add_f32 v[64:65], v[64:65], v[200:201]
	v_pk_add_f32 v[66:67], v[66:67], v[202:203]
	v_pk_add_f32 v[68:69], v[68:69], v[218:219]
	v_pk_add_f32 v[70:71], v[70:71], v[220:221]
	s_mov_b64 exec, s[98:99]
	s_cmp_lt_u32 s12, 5
	s_cbranch_scc1 ATS3_END
	s_waitcnt vmcnt(22)
	v_add_u32_e32 v58, 4, v150
	v_cmp_gt_u32_e32 vcc, s12, v58
	s_and_b64 exec, vcc, s[98:99]
	v_pk_add_f32 v[34:35], v[34:35], v[222:223]
	v_pk_add_f32 v[36:37], v[36:37], v[224:225]
	v_pk_add_f32 v[38:39], v[38:39], v[226:227]
	v_pk_add_f32 v[40:41], v[40:41], v[228:229]
	s_mov_b64 exec, s[98:99]
	v_add_u32_e32 v58, 5, v150
	v_cmp_gt_u32_e32 vcc, s12, v58
	s_and_b64 exec, vcc, s[98:99]
	v_pk_add_f32 v[42:43], v[42:43], v[222:223]
	v_pk_add_f32 v[44:45], v[44:45], v[224:225]
	v_pk_add_f32 v[46:47], v[46:47], v[226:227]
	v_pk_add_f32 v[48:49], v[48:49], v[228:229]
	s_mov_b64 exec, s[98:99]
	v_add_u32_e32 v58, 6, v150
	v_cmp_gt_u32_e32 vcc, s12, v58
	s_and_b64 exec, vcc, s[98:99]
	v_pk_add_f32 v[50:51], v[50:51], v[222:223]
	v_pk_add_f32 v[52:53], v[52:53], v[224:225]
	v_pk_add_f32 v[54:55], v[54:55], v[226:227]
	v_pk_add_f32 v[56:57], v[56:57], v[228:229]
	s_mov_b64 exec, s[98:99]
	v_add_u32_e32 v58, 7, v150
	v_cmp_gt_u32_e32 vcc, s12, v58
	s_and_b64 exec, vcc, s[98:99]
	v_pk_add_f32 v[64:65], v[64:65], v[222:223]
	v_pk_add_f32 v[66:67], v[66:67], v[224:225]
	v_pk_add_f32 v[68:69], v[68:69], v[226:227]
	v_pk_add_f32 v[70:71], v[70:71], v[228:229]
	s_mov_b64 exec, s[98:99]
	s_waitcnt vmcnt(20)
	v_add_u32_e32 v58, 5, v150
	v_cmp_gt_u32_e32 vcc, s12, v58
	s_and_b64 exec, vcc, s[98:99]
	v_pk_add_f32 v[34:35], v[34:35], v[230:231]
	v_pk_add_f32 v[36:37], v[36:37], v[232:233]
	v_pk_add_f32 v[38:39], v[38:39], v[236:237]
	v_pk_add_f32 v[40:41], v[40:41], v[238:239]
	s_mov_b64 exec, s[98:99]
	v_add_u32_e32 v58, 6, v150
	v_cmp_gt_u32_e32 vcc, s12, v58
	s_and_b64 exec, vcc, s[98:99]
	v_pk_add_f32 v[42:43], v[42:43], v[230:231]
	v_pk_add_f32 v[44:45], v[44:45], v[232:233]
	v_pk_add_f32 v[46:47], v[46:47], v[236:237]
	v_pk_add_f32 v[48:49], v[48:49], v[238:239]
	s_mov_b64 exec, s[98:99]
	v_add_u32_e32 v58, 7, v150
	v_cmp_gt_u32_e32 vcc, s12, v58
	s_and_b64 exec, vcc, s[98:99]
	v_pk_add_f32 v[50:51], v[50:51], v[230:231]
	v_pk_add_f32 v[52:53], v[52:53], v[232:233]
	v_pk_add_f32 v[54:55], v[54:55], v[236:237]
	v_pk_add_f32 v[56:57], v[56:57], v[238:239]
	s_mov_b64 exec, s[98:99]
	v_add_u32_e32 v58, 8, v150
	v_cmp_gt_u32_e32 vcc, s12, v58
	s_and_b64 exec, vcc, s[98:99]
	v_pk_add_f32 v[64:65], v[64:65], v[230:231]
	v_pk_add_f32 v[66:67], v[66:67], v[232:233]
	v_pk_add_f32 v[68:69], v[68:69], v[236:237]
	v_pk_add_f32 v[70:71], v[70:71], v[238:239]
	s_mov_b64 exec, s[98:99]
	s_waitcnt vmcnt(18)
	v_add_u32_e32 v58, 6, v150
	v_cmp_gt_u32_e32 vcc, s12, v58
	s_and_b64 exec, vcc, s[98:99]
	v_pk_add_f32 v[34:35], v[34:35], v[240:241]
	v_pk_add_f32 v[36:37], v[36:37], v[242:243]
	v_pk_add_f32 v[38:39], v[38:39], v[244:245]
	v_pk_add_f32 v[40:41], v[40:41], v[246:247]
	s_mov_b64 exec, s[98:99]
	v_add_u32_e32 v58, 7, v150
	v_cmp_gt_u32_e32 vcc, s12, v58
	s_and_b64 exec, vcc, s[98:99]
	v_pk_add_f32 v[42:43], v[42:43], v[240:241]
	v_pk_add_f32 v[44:45], v[44:45], v[242:243]
	v_pk_add_f32 v[46:47], v[46:47], v[244:245]
	v_pk_add_f32 v[48:49], v[48:49], v[246:247]
	s_mov_b64 exec, s[98:99]
	v_add_u32_e32 v58, 8, v150
	v_cmp_gt_u32_e32 vcc, s12, v58
	s_and_b64 exec, vcc, s[98:99]
	v_pk_add_f32 v[50:51], v[50:51], v[240:241]
	v_pk_add_f32 v[52:53], v[52:53], v[242:243]
	v_pk_add_f32 v[54:55], v[54:55], v[244:245]
	v_pk_add_f32 v[56:57], v[56:57], v[246:247]
	s_mov_b64 exec, s[98:99]
	v_add_u32_e32 v58, 9, v150
	v_cmp_gt_u32_e32 vcc, s12, v58
	s_and_b64 exec, vcc, s[98:99]
	v_pk_add_f32 v[64:65], v[64:65], v[240:241]
	v_pk_add_f32 v[66:67], v[66:67], v[242:243]
	v_pk_add_f32 v[68:69], v[68:69], v[244:245]
	v_pk_add_f32 v[70:71], v[70:71], v[246:247]
	s_mov_b64 exec, s[98:99]
	s_waitcnt vmcnt(16)
	v_add_u32_e32 v58, 7, v150
	v_cmp_gt_u32_e32 vcc, s12, v58
	s_and_b64 exec, vcc, s[98:99]
	v_pk_add_f32 v[34:35], v[34:35], v[248:249]
	v_pk_add_f32 v[36:37], v[36:37], v[250:251]
	v_pk_add_f32 v[38:39], v[38:39], v[252:253]
	v_pk_add_f32 v[40:41], v[40:41], v[254:255]
	s_mov_b64 exec, s[98:99]
	v_add_u32_e32 v58, 8, v150
	v_cmp_gt_u32_e32 vcc, s12, v58
	s_and_b64 exec, vcc, s[98:99]
	v_pk_add_f32 v[42:43], v[42:43], v[248:249]
	v_pk_add_f32 v[44:45], v[44:45], v[250:251]
	v_pk_add_f32 v[46:47], v[46:47], v[252:253]
	v_pk_add_f32 v[48:49], v[48:49], v[254:255]
	s_mov_b64 exec, s[98:99]
	v_add_u32_e32 v58, 9, v150
	v_cmp_gt_u32_e32 vcc, s12, v58
	s_and_b64 exec, vcc, s[98:99]
	v_pk_add_f32 v[50:51], v[50:51], v[248:249]
	v_pk_add_f32 v[52:53], v[52:53], v[250:251]
	v_pk_add_f32 v[54:55], v[54:55], v[252:253]
	v_pk_add_f32 v[56:57], v[56:57], v[254:255]
	s_mov_b64 exec, s[98:99]
	v_add_u32_e32 v58, 10, v150
	v_cmp_gt_u32_e32 vcc, s12, v58
	s_and_b64 exec, vcc, s[98:99]
	v_pk_add_f32 v[64:65], v[64:65], v[248:249]
	v_pk_add_f32 v[66:67], v[66:67], v[250:251]
	v_pk_add_f32 v[68:69], v[68:69], v[252:253]
	v_pk_add_f32 v[70:71], v[70:71], v[254:255]
	s_mov_b64 exec, s[98:99]
	s_cmp_lt_u32 s12, 9
	s_cbranch_scc1 ATS3_END
	s_waitcnt vmcnt(14)
	v_add_u32_e32 v58, 8, v150
	v_cmp_gt_u32_e32 vcc, s12, v58
	s_and_b64 exec, vcc, s[98:99]
	v_pk_add_f32 v[34:35], v[34:35], v[72:73]
	v_pk_add_f32 v[36:37], v[36:37], v[74:75]
	v_pk_add_f32 v[38:39], v[38:39], v[80:81]
	v_pk_add_f32 v[40:41], v[40:41], v[82:83]
	s_mov_b64 exec, s[98:99]
	v_add_u32_e32 v58, 9, v150
	v_cmp_gt_u32_e32 vcc, s12, v58
	s_and_b64 exec, vcc, s[98:99]
	v_pk_add_f32 v[42:43], v[42:43], v[72:73]
	v_pk_add_f32 v[44:45], v[44:45], v[74:75]
	v_pk_add_f32 v[46:47], v[46:47], v[80:81]
	v_pk_add_f32 v[48:49], v[48:49], v[82:83]
	s_mov_b64 exec, s[98:99]
	v_add_u32_e32 v58, 10, v150
	v_cmp_gt_u32_e32 vcc, s12, v58
	s_and_b64 exec, vcc, s[98:99]
	v_pk_add_f32 v[50:51], v[50:51], v[72:73]
	v_pk_add_f32 v[52:53], v[52:53], v[74:75]
	v_pk_add_f32 v[54:55], v[54:55], v[80:81]
	v_pk_add_f32 v[56:57], v[56:57], v[82:83]
	s_mov_b64 exec, s[98:99]
	v_add_u32_e32 v58, 11, v150
	v_cmp_gt_u32_e32 vcc, s12, v58
	s_and_b64 exec, vcc, s[98:99]
	v_pk_add_f32 v[64:65], v[64:65], v[72:73]
	v_pk_add_f32 v[66:67], v[66:67], v[74:75]
	v_pk_add_f32 v[68:69], v[68:69], v[80:81]
	v_pk_add_f32 v[70:71], v[70:71], v[82:83]
	s_mov_b64 exec, s[98:99]
	s_waitcnt vmcnt(12)
	v_add_u32_e32 v58, 9, v150
	v_cmp_gt_u32_e32 vcc, s12, v58
	s_and_b64 exec, vcc, s[98:99]
	v_pk_add_f32 v[34:35], v[34:35], v[92:93]
	v_pk_add_f32 v[36:37], v[36:37], v[94:95]
	v_pk_add_f32 v[38:39], v[38:39], v[96:97]
	v_pk_add_f32 v[40:41], v[40:41], v[98:99]
	s_mov_b64 exec, s[98:99]
	v_add_u32_e32 v58, 10, v150
	v_cmp_gt_u32_e32 vcc, s12, v58
	s_and_b64 exec, vcc, s[98:99]
	v_pk_add_f32 v[42:43], v[42:43], v[92:93]
	v_pk_add_f32 v[44:45], v[44:45], v[94:95]
	v_pk_add_f32 v[46:47], v[46:47], v[96:97]
	v_pk_add_f32 v[48:49], v[48:49], v[98:99]
	s_mov_b64 exec, s[98:99]
	v_add_u32_e32 v58, 11, v150
	v_cmp_gt_u32_e32 vcc, s12, v58
	s_and_b64 exec, vcc, s[98:99]
	v_pk_add_f32 v[50:51], v[50:51], v[92:93]
	v_pk_add_f32 v[52:53], v[52:53], v[94:95]
	v_pk_add_f32 v[54:55], v[54:55], v[96:97]
	v_pk_add_f32 v[56:57], v[56:57], v[98:99]
	s_mov_b64 exec, s[98:99]
	v_add_u32_e32 v58, 12, v150
	v_cmp_gt_u32_e32 vcc, s12, v58
	s_and_b64 exec, vcc, s[98:99]
	v_pk_add_f32 v[64:65], v[64:65], v[92:93]
	v_pk_add_f32 v[66:67], v[66:67], v[94:95]
	v_pk_add_f32 v[68:69], v[68:69], v[96:97]
	v_pk_add_f32 v[70:71], v[70:71], v[98:99]
	s_mov_b64 exec, s[98:99]
	s_waitcnt vmcnt(10)
	v_add_u32_e32 v58, 10, v150
	v_cmp_gt_u32_e32 vcc, s12, v58
	s_and_b64 exec, vcc, s[98:99]
	v_pk_add_f32 v[34:35], v[34:35], v[100:101]
	v_pk_add_f32 v[36:37], v[36:37], v[102:103]
	v_pk_add_f32 v[38:39], v[38:39], v[104:105]
	v_pk_add_f32 v[40:41], v[40:41], v[106:107]
	s_mov_b64 exec, s[98:99]
	v_add_u32_e32 v58, 11, v150
	v_cmp_gt_u32_e32 vcc, s12, v58
	s_and_b64 exec, vcc, s[98:99]
	v_pk_add_f32 v[42:43], v[42:43], v[100:101]
	v_pk_add_f32 v[44:45], v[44:45], v[102:103]
	v_pk_add_f32 v[46:47], v[46:47], v[104:105]
	v_pk_add_f32 v[48:49], v[48:49], v[106:107]
	s_mov_b64 exec, s[98:99]
	v_add_u32_e32 v58, 12, v150
	v_cmp_gt_u32_e32 vcc, s12, v58
	s_and_b64 exec, vcc, s[98:99]
	v_pk_add_f32 v[50:51], v[50:51], v[100:101]
	v_pk_add_f32 v[52:53], v[52:53], v[102:103]
	v_pk_add_f32 v[54:55], v[54:55], v[104:105]
	v_pk_add_f32 v[56:57], v[56:57], v[106:107]
	s_mov_b64 exec, s[98:99]
	v_add_u32_e32 v58, 13, v150
	v_cmp_gt_u32_e32 vcc, s12, v58
	s_and_b64 exec, vcc, s[98:99]
	v_pk_add_f32 v[64:65], v[64:65], v[100:101]
	v_pk_add_f32 v[66:67], v[66:67], v[102:103]
	v_pk_add_f32 v[68:69], v[68:69], v[104:105]
	v_pk_add_f32 v[70:71], v[70:71], v[106:107]
	s_mov_b64 exec, s[98:99]
	s_waitcnt vmcnt(8)
	v_add_u32_e32 v58, 11, v150
	v_cmp_gt_u32_e32 vcc, s12, v58
	s_and_b64 exec, vcc, s[98:99]
	v_pk_add_f32 v[34:35], v[34:35], v[108:109]
	v_pk_add_f32 v[36:37], v[36:37], v[110:111]
	v_pk_add_f32 v[38:39], v[38:39], v[112:113]
	v_pk_add_f32 v[40:41], v[40:41], v[114:115]
	s_mov_b64 exec, s[98:99]
	v_add_u32_e32 v58, 12, v150
	v_cmp_gt_u32_e32 vcc, s12, v58
	s_and_b64 exec, vcc, s[98:99]
	v_pk_add_f32 v[42:43], v[42:43], v[108:109]
	v_pk_add_f32 v[44:45], v[44:45], v[110:111]
	v_pk_add_f32 v[46:47], v[46:47], v[112:113]
	v_pk_add_f32 v[48:49], v[48:49], v[114:115]
	s_mov_b64 exec, s[98:99]
	v_add_u32_e32 v58, 13, v150
	v_cmp_gt_u32_e32 vcc, s12, v58
	s_and_b64 exec, vcc, s[98:99]
	v_pk_add_f32 v[50:51], v[50:51], v[108:109]
	v_pk_add_f32 v[52:53], v[52:53], v[110:111]
	v_pk_add_f32 v[54:55], v[54:55], v[112:113]
	v_pk_add_f32 v[56:57], v[56:57], v[114:115]
	s_mov_b64 exec, s[98:99]
	v_add_u32_e32 v58, 14, v150
	v_cmp_gt_u32_e32 vcc, s12, v58
	s_and_b64 exec, vcc, s[98:99]
	v_pk_add_f32 v[64:65], v[64:65], v[108:109]
	v_pk_add_f32 v[66:67], v[66:67], v[110:111]
	v_pk_add_f32 v[68:69], v[68:69], v[112:113]
	v_pk_add_f32 v[70:71], v[70:71], v[114:115]
	s_mov_b64 exec, s[98:99]
	s_waitcnt vmcnt(6)
	v_add_u32_e32 v58, 12, v150
	v_cmp_gt_u32_e32 vcc, s12, v58
	s_and_b64 exec, vcc, s[98:99]
	v_pk_add_f32 v[34:35], v[34:35], v[116:117]
	v_pk_add_f32 v[36:37], v[36:37], v[118:119]
	v_pk_add_f32 v[38:39], v[38:39], v[120:121]
	v_pk_add_f32 v[40:41], v[40:41], v[122:123]
	s_mov_b64 exec, s[98:99]
	v_add_u32_e32 v58, 13, v150
	v_cmp_gt_u32_e32 vcc, s12, v58
	s_and_b64 exec, vcc, s[98:99]
	v_pk_add_f32 v[42:43], v[42:43], v[116:117]
	v_pk_add_f32 v[44:45], v[44:45], v[118:119]
	v_pk_add_f32 v[46:47], v[46:47], v[120:121]
	v_pk_add_f32 v[48:49], v[48:49], v[122:123]
	s_mov_b64 exec, s[98:99]
	v_add_u32_e32 v58, 14, v150
	v_cmp_gt_u32_e32 vcc, s12, v58
	s_and_b64 exec, vcc, s[98:99]
	v_pk_add_f32 v[50:51], v[50:51], v[116:117]
	v_pk_add_f32 v[52:53], v[52:53], v[118:119]
	v_pk_add_f32 v[54:55], v[54:55], v[120:121]
	v_pk_add_f32 v[56:57], v[56:57], v[122:123]
	s_mov_b64 exec, s[98:99]
	v_add_u32_e32 v58, 15, v150
	v_cmp_gt_u32_e32 vcc, s12, v58
	s_and_b64 exec, vcc, s[98:99]
	v_pk_add_f32 v[64:65], v[64:65], v[116:117]
	v_pk_add_f32 v[66:67], v[66:67], v[118:119]
	v_pk_add_f32 v[68:69], v[68:69], v[120:121]
	v_pk_add_f32 v[70:71], v[70:71], v[122:123]
	s_mov_b64 exec, s[98:99]
	s_waitcnt vmcnt(4)
	v_add_u32_e32 v58, 13, v150
	v_cmp_gt_u32_e32 vcc, s12, v58
	s_and_b64 exec, vcc, s[98:99]
	v_pk_add_f32 v[34:35], v[34:35], v[124:125]
	v_pk_add_f32 v[36:37], v[36:37], v[126:127]
	v_pk_add_f32 v[38:39], v[38:39], v[128:129]
	v_pk_add_f32 v[40:41], v[40:41], v[130:131]
	s_mov_b64 exec, s[98:99]
	v_add_u32_e32 v58, 14, v150
	v_cmp_gt_u32_e32 vcc, s12, v58
	s_and_b64 exec, vcc, s[98:99]
	v_pk_add_f32 v[42:43], v[42:43], v[124:125]
	v_pk_add_f32 v[44:45], v[44:45], v[126:127]
	v_pk_add_f32 v[46:47], v[46:47], v[128:129]
	v_pk_add_f32 v[48:49], v[48:49], v[130:131]
	s_mov_b64 exec, s[98:99]
	v_add_u32_e32 v58, 15, v150
	v_cmp_gt_u32_e32 vcc, s12, v58
	s_and_b64 exec, vcc, s[98:99]
	v_pk_add_f32 v[50:51], v[50:51], v[124:125]
	v_pk_add_f32 v[52:53], v[52:53], v[126:127]
	v_pk_add_f32 v[54:55], v[54:55], v[128:129]
	v_pk_add_f32 v[56:57], v[56:57], v[130:131]
	s_mov_b64 exec, s[98:99]
	s_waitcnt vmcnt(2)
	v_add_u32_e32 v58, 14, v150
	v_cmp_gt_u32_e32 vcc, s12, v58
	s_and_b64 exec, vcc, s[98:99]
	v_pk_add_f32 v[34:35], v[34:35], v[132:133]
	v_pk_add_f32 v[36:37], v[36:37], v[134:135]
	v_pk_add_f32 v[38:39], v[38:39], v[136:137]
	v_pk_add_f32 v[40:41], v[40:41], v[138:139]
	s_mov_b64 exec, s[98:99]
	v_add_u32_e32 v58, 15, v150
	v_cmp_gt_u32_e32 vcc, s12, v58
	s_and_b64 exec, vcc, s[98:99]
	v_pk_add_f32 v[42:43], v[42:43], v[132:133]
	v_pk_add_f32 v[44:45], v[44:45], v[134:135]
	v_pk_add_f32 v[46:47], v[46:47], v[136:137]
	v_pk_add_f32 v[48:49], v[48:49], v[138:139]
	s_mov_b64 exec, s[98:99]
	s_waitcnt vmcnt(0)
	v_add_u32_e32 v58, 15, v150
	v_cmp_gt_u32_e32 vcc, s12, v58
	s_and_b64 exec, vcc, s[98:99]
	v_pk_add_f32 v[34:35], v[34:35], v[176:177]
	v_pk_add_f32 v[36:37], v[36:37], v[178:179]
	v_pk_add_f32 v[38:39], v[38:39], v[180:181]
	v_pk_add_f32 v[40:41], v[40:41], v[182:183]
	s_mov_b64 exec, s[98:99]
ATS3_END:
	s_waitcnt vmcnt(0)
	v_ffbl_b32_e32 v58, s12
	v_lshlrev_b32_e32 v58, 23, v58
	v_sub_u32_e32 v58, 0x3f800000, v58
	v_lshlrev_b32_e32 v72, 16, v0
	v_and_b32_e32 v73, 0xffff0000, v0
	v_lshlrev_b32_e32 v74, 16, v1
	v_and_b32_e32 v75, 0xffff0000, v1
	v_lshlrev_b32_e32 v80, 16, v2
	v_and_b32_e32 v81, 0xffff0000, v2
	v_lshlrev_b32_e32 v82, 16, v3
	v_and_b32_e32 v83, 0xffff0000, v3
	v_fma_f32 v72, v58, v34, -v72
	v_fma_f32 v73, v58, v35, -v73
	v_fma_f32 v74, v58, v36, -v74
	v_fma_f32 v75, v58, v37, -v75
	v_fma_f32 v80, v58, v38, -v80
	v_fma_f32 v81, v58, v39, -v81
	v_fma_f32 v82, v58, v40, -v82
	v_fma_f32 v83, v58, v41, -v83
	v_cvt_pk_bf16_f32 v12, v72, v73
	v_cvt_pk_bf16_f32 v13, v74, v75
	v_cvt_pk_bf16_f32 v14, v80, v81
	v_cvt_pk_bf16_f32 v15, v82, v83
	v_lshlrev_b32_e32 v72, 16, v4
	v_and_b32_e32 v73, 0xffff0000, v4
	v_lshlrev_b32_e32 v74, 16, v5
	v_and_b32_e32 v75, 0xffff0000, v5
	v_lshlrev_b32_e32 v80, 16, v6
	v_and_b32_e32 v81, 0xffff0000, v6
	v_lshlrev_b32_e32 v82, 16, v7
	v_and_b32_e32 v83, 0xffff0000, v7
	v_fma_f32 v72, v58, v42, -v72
	v_fma_f32 v73, v58, v43, -v73
	v_fma_f32 v74, v58, v44, -v74
	v_fma_f32 v75, v58, v45, -v75
	v_fma_f32 v80, v58, v46, -v80
	v_fma_f32 v81, v58, v47, -v81
	v_fma_f32 v82, v58, v48, -v82
	v_fma_f32 v83, v58, v49, -v83
	v_cvt_pk_bf16_f32 v16, v72, v73
	v_cvt_pk_bf16_f32 v17, v74, v75
	v_cvt_pk_bf16_f32 v18, v80, v81
	v_cvt_pk_bf16_f32 v19, v82, v83
	v_lshlrev_b32_e32 v72, 16, v8
	v_and_b32_e32 v73, 0xffff0000, v8
	v_lshlrev_b32_e32 v74, 16, v9
	v_and_b32_e32 v75, 0xffff0000, v9
	v_lshlrev_b32_e32 v80, 16, v10
	v_and_b32_e32 v81, 0xffff0000, v10
	v_lshlrev_b32_e32 v82, 16, v11
	v_and_b32_e32 v83, 0xffff0000, v11
	v_fma_f32 v72, v58, v50, -v72
	v_fma_f32 v73, v58, v51, -v73
	v_fma_f32 v74, v58, v52, -v74
	v_fma_f32 v75, v58, v53, -v75
	v_fma_f32 v80, v58, v54, -v80
	v_fma_f32 v81, v58, v55, -v81
	v_fma_f32 v82, v58, v56, -v82
	v_fma_f32 v83, v58, v57, -v83
	v_cvt_pk_bf16_f32 v20, v72, v73
	v_cvt_pk_bf16_f32 v21, v74, v75
	v_cvt_pk_bf16_f32 v22, v80, v81
	v_cvt_pk_bf16_f32 v23, v82, v83
	v_lshlrev_b32_e32 v72, 16, v24
	v_and_b32_e32 v73, 0xffff0000, v24
	v_lshlrev_b32_e32 v74, 16, v25
	v_and_b32_e32 v75, 0xffff0000, v25
	v_lshlrev_b32_e32 v80, 16, v26
	v_and_b32_e32 v81, 0xffff0000, v26
	v_lshlrev_b32_e32 v82, 16, v27
	v_and_b32_e32 v83, 0xffff0000, v27
	v_fma_f32 v72, v58, v64, -v72
	v_fma_f32 v73, v58, v65, -v73
	v_fma_f32 v74, v58, v66, -v74
	v_fma_f32 v75, v58, v67, -v75
	v_fma_f32 v80, v58, v68, -v80
	v_fma_f32 v81, v58, v69, -v81
	v_fma_f32 v82, v58, v70, -v82
	v_fma_f32 v83, v58, v71, -v83
	v_cvt_pk_bf16_f32 v28, v72, v73
	v_cvt_pk_bf16_f32 v29, v74, v75
	v_cvt_pk_bf16_f32 v30, v80, v81
	v_cvt_pk_bf16_f32 v31, v82, v83
	s_branch .LBB0_2427
